# first K iteration of non-first units: phase-4 wait relaxed past the epilogue stores (+vmcnt(10) guard before the SA(1,1) read); nt hint on in-/up-projection epilogue stores
# speedup vs baseline: 1.0156x; 1.0067x over previous
; #define PG8_STAGE(bufoff, gbase, voff) do { _Pragma("unroll") for (int _i = 0; _i < 2; ++_i) \
;         __builtin_amdgcn_global_load_lds((const unsigned*)((const char*)(gbase) + (voff)[_i]), (LAS unsigned*)(lds + (bufoff) + ldsw + _i * 8192), 16, 0, 0); } while (0)
; #define PG8_LDA(dst, b, h) do { _Pragma("unroll") for (int m = 0; m < 4; ++m) _Pragma("unroll") for (int k = 0; k < 2; ++k) dst[m][k] = *(const LAS bf16x8*)(lds + PG8_SA(b, h) + aoff + m * 2048 + k * 1024); } while (0)
; #define PG8_LDB(dst, b, h) do { _Pragma("unroll") for (int n = 0; n < 2; ++n) _Pragma("unroll") for (int k = 0; k < 2; ++k) dst[n][k] = *(const LAS bf16x8*)(lds + PG8_SB(b, h) + boff + n * 2048 + k * 1024); } while (0)
; #define PG8_MMA(ai, bj, At, Bt) do { __builtin_amdgcn_s_setprio(1); _Pragma("unroll") for (int m = 0; m < 4; ++m) _Pragma("unroll") for (int n = 0; n < 2; ++n) _Pragma("unroll") for (int k = 0; k < 2; ++k) \
;         acc[ai][bj][m][n] = __builtin_amdgcn_mfma_f32_16x16x32_bf16(Bt[n][k], At[m][k], acc[ai][bj][m][n], 0, 0, 0); __builtin_amdgcn_s_setprio(0); } while (0)
; #define PG8_WAIT_V(n) asm volatile("s_waitcnt vmcnt(" #n ")" ::: "memory")
; #define PG8_WAIT_L(n) asm volatile("s_waitcnt lgkmcnt(" #n ")" ::: "memory")
; template <class Epi>
; __device__ __forceinline__ void gemm_phase(LAS unsigned char* lds, const Gemm g, const StaticOrder& S, const Epi& E) {
;     ...
;         for (int t = 0; t < nt; t += 2) {
;             const bool last = (t == nt - 2);
;             const char* a1 = cA + (size_t)(t + 1) * kstep;
;             const char* a2 = last ? nA : cA + (size_t)(t + 2) * kstep; const char* b2 = last ? nB : cB + (size_t)(t + 2) * kstep;
;             const char* a3 = a2 + kstep; const char* b3 = b2 + kstep;
;             PG8_LDB(B0, 0, 0); PG8_SCHED; PG8_LDA(At, 0, 0); PG8_STAGE(PG8_SA(1, 1), a1 + hstep, voffA);
;             PG8_WAIT_L(8); PG8_BAR; PG8_WAIT_L(0); PG8_MMA(0, 0, At, B0); PG8_BAR; PG8_SCHED;
;             PG8_LDB(B1, 0, 1); PG8_STAGE(PG8_SB(0, 0), b2, voffB);
;             PG8_BAR; PG8_WAIT_L(0); PG8_MMA(0, 1, At, B1); PG8_BAR;
;             PG8_LDA(At, 0, 1); PG8_STAGE(PG8_SA(0, 0), a2, voffA);
;             PG8_BAR; PG8_WAIT_L(0); PG8_MMA(1, 0, At, B0); PG8_BAR; PG8_SCHED;
;             PG8_STAGE(PG8_SB(0, 1), b2 + hstep, voffB);
;             PG8_WAIT_V(6); PG8_BAR; PG8_MMA(1, 1, At, B1); PG8_BAR;
.Lst5_done:
.LBB0_211:
	s_add_u32 s36, s0, 0xfffc0080
	s_addc_u32 s37, s1, -1
	s_add_i32 s58, 0, 0x10000
	v_add_u32_e32 v0, s58, v171
	ds_read_b128 v[42:45], v0
	ds_read_b128 v[46:49], v0 offset:1024
	ds_read_b128 v[50:53], v0 offset:2048
	ds_read_b128 v[54:57], v0 offset:3072
	s_cmp_eq_u32 s24, 12
	s_cselect_b32 s53, s65, s37
	s_cselect_b32 s52, s96, s36
	s_cselect_b32 s37, s63, vcc_hi
	s_cselect_b32 s36, s97, vcc_lo
	v_lshl_add_u64 v[202:203], s[0:1], 0, v[186:187]
	s_add_i32 m0, s30, 0xc000
	ds_read_b128 v[58:61], v242
	ds_read_b128 v[62:65], v242 offset:1024
	ds_read_b128 v[70:73], v242 offset:2048
	ds_read_b128 v[74:77], v242 offset:3072
	ds_read_b128 v[172:175], v242 offset:4096
	ds_read_b128 v[190:193], v242 offset:5120
	ds_read_b128 v[194:197], v242 offset:6144
	ds_read_b128 v[198:201], v242 offset:7168
	global_load_lds_dwordx4 v[202:203], off
	v_lshl_add_u64 v[202:203], s[0:1], 0, v[188:189]
	s_add_i32 m0, s30, 0xe000
	s_nop 0
	global_load_lds_dwordx4 v[202:203], off
	s_waitcnt lgkmcnt(8)
	s_barrier
	s_waitcnt lgkmcnt(0)
	s_setprio 1
	s_waitcnt lgkmcnt(0)
	v_mfma_f32_16x16x32_bf16 v[158:161], v[42:45], v[58:61], v[158:161]
	v_mfma_f32_16x16x32_bf16 v[154:157], v[50:53], v[58:61], v[154:157]
	v_mfma_f32_16x16x32_bf16 v[142:145], v[42:45], v[70:73], v[142:145]
	v_mfma_f32_16x16x32_bf16 v[138:141], v[50:53], v[70:73], v[138:141]
	v_mfma_f32_16x16x32_bf16 v[126:129], v[42:45], v[172:175], v[126:129]
	v_mfma_f32_16x16x32_bf16 v[122:125], v[50:53], v[172:175], v[122:125]
	v_mfma_f32_16x16x32_bf16 v[110:113], v[42:45], v[194:197], v[110:113]
	v_mfma_f32_16x16x32_bf16 v[106:109], v[50:53], v[194:197], v[106:109]
	v_mfma_f32_16x16x32_bf16 v[158:161], v[46:49], v[62:65], v[158:161]
	v_mfma_f32_16x16x32_bf16 v[154:157], v[54:57], v[62:65], v[154:157]
	v_mfma_f32_16x16x32_bf16 v[142:145], v[46:49], v[74:77], v[142:145]
	v_mfma_f32_16x16x32_bf16 v[138:141], v[54:57], v[74:77], v[138:141]
	v_mfma_f32_16x16x32_bf16 v[126:129], v[46:49], v[190:193], v[126:129]
	v_mfma_f32_16x16x32_bf16 v[122:125], v[54:57], v[190:193], v[122:125]
	v_mfma_f32_16x16x32_bf16 v[110:113], v[46:49], v[198:201], v[110:113]
	v_mfma_f32_16x16x32_bf16 v[106:109], v[54:57], v[198:201], v[106:109]
	s_setprio 0
	s_barrier
	s_add_i32 s56, 0, 0x14000
	s_add_i32 s57, s58, s26
	v_add_u32_e32 v0, s56, v171
	v_lshl_add_u64 v[222:223], s[36:37], 0, v[180:181]
	s_mov_b32 m0, s57
	ds_read_b128 v[202:205], v0
	ds_read_b128 v[206:209], v0 offset:1024
	ds_read_b128 v[210:213], v0 offset:2048
	ds_read_b128 v[214:217], v0 offset:3072
	global_load_lds_dwordx4 v[222:223], off
	v_lshl_add_u64 v[246:247], s[36:37], 0, v[176:177]
	s_add_i32 m0, s57, 0x2000
	s_nop 0
	global_load_lds_dwordx4 v[246:247], off
	s_barrier
	s_waitcnt lgkmcnt(0)
	s_setprio 1
	s_waitcnt lgkmcnt(0)
	v_mfma_f32_16x16x32_bf16 v[150:153], v[202:205], v[58:61], v[150:153]
	v_mfma_f32_16x16x32_bf16 v[58:61], v[210:213], v[58:61], v[146:149]
	v_mfma_f32_16x16x32_bf16 v[150:153], v[206:209], v[62:65], v[150:153]
	v_mfma_f32_16x16x32_bf16 v[58:61], v[214:217], v[62:65], v[58:61]
	v_mfma_f32_16x16x32_bf16 v[62:65], v[202:205], v[70:73], v[130:133]
	v_mfma_f32_16x16x32_bf16 v[70:73], v[210:213], v[70:73], v[134:137]
	v_mfma_f32_16x16x32_bf16 v[62:65], v[206:209], v[74:77], v[62:65]
	v_mfma_f32_16x16x32_bf16 v[70:73], v[214:217], v[74:77], v[70:73]
	v_mfma_f32_16x16x32_bf16 v[74:77], v[202:205], v[172:175], v[114:117]
	v_mfma_f32_16x16x32_bf16 v[114:117], v[210:213], v[172:175], v[118:121]
	v_mfma_f32_16x16x32_bf16 v[98:101], v[202:205], v[194:197], v[98:101]
	v_mfma_f32_16x16x32_bf16 v[102:105], v[210:213], v[194:197], v[102:105]
	v_mfma_f32_16x16x32_bf16 v[118:121], v[214:217], v[190:193], v[114:117]
	v_mfma_f32_16x16x32_bf16 v[98:101], v[206:209], v[198:201], v[98:101]
	v_mfma_f32_16x16x32_bf16 v[102:105], v[214:217], v[198:201], v[102:105]
	v_mfma_f32_16x16x32_bf16 v[74:77], v[206:209], v[190:193], v[74:77]
	s_setprio 0
	s_mov_b32 m0, s30
	v_lshl_add_u64 v[248:249], s[52:53], 0, v[182:183]
	s_barrier
	ds_read_b128 v[114:117], v242 offset:16384
	ds_read_b128 v[130:133], v242 offset:17408
	ds_read_b128 v[134:137], v242 offset:18432
	ds_read_b128 v[146:149], v242 offset:19456
	ds_read_b128 v[172:175], v242 offset:20480
	ds_read_b128 v[190:193], v242 offset:21504
	ds_read_b128 v[194:197], v242 offset:22528
	ds_read_b128 v[198:201], v242 offset:23552
	global_load_lds_dwordx4 v[248:249], off
	v_lshl_add_u64 v[236:237], s[52:53], 0, v[178:179]
	s_mov_b32 m0, s54
	s_nop 0
	global_load_lds_dwordx4 v[236:237], off
	s_barrier
	s_waitcnt lgkmcnt(0)
	s_setprio 1
	s_waitcnt lgkmcnt(0)
	v_mfma_f32_16x16x32_bf16 v[94:97], v[42:45], v[114:117], v[94:97]
	v_mfma_f32_16x16x32_bf16 v[90:93], v[50:53], v[114:117], v[90:93]
	v_mfma_f32_16x16x32_bf16 v[78:81], v[42:45], v[134:137], v[78:81]
	v_mfma_f32_16x16x32_bf16 v[66:69], v[50:53], v[134:137], v[66:69]
	v_mfma_f32_16x16x32_bf16 v[30:33], v[42:45], v[172:175], v[30:33]
	v_mfma_f32_16x16x32_bf16 v[26:29], v[50:53], v[172:175], v[26:29]
	v_mfma_f32_16x16x32_bf16 v[14:17], v[42:45], v[194:197], v[14:17]
	v_mfma_f32_16x16x32_bf16 v[10:13], v[50:53], v[194:197], v[10:13]
	v_mfma_f32_16x16x32_bf16 v[94:97], v[46:49], v[130:133], v[94:97]
	v_mfma_f32_16x16x32_bf16 v[90:93], v[54:57], v[130:133], v[90:93]
	v_mfma_f32_16x16x32_bf16 v[78:81], v[46:49], v[146:149], v[78:81]
	v_mfma_f32_16x16x32_bf16 v[66:69], v[54:57], v[146:149], v[66:69]
	v_mfma_f32_16x16x32_bf16 v[30:33], v[46:49], v[190:193], v[30:33]
	v_mfma_f32_16x16x32_bf16 v[26:29], v[54:57], v[190:193], v[26:29]
	v_mfma_f32_16x16x32_bf16 v[14:17], v[46:49], v[198:201], v[14:17]
	v_mfma_f32_16x16x32_bf16 v[10:13], v[54:57], v[198:201], v[10:13]
	s_setprio 0
	s_barrier
	s_add_u32 s58, s36, 0x40000
	s_addc_u32 s59, s37, 0
	s_add_i32 s56, s56, s26
	v_lshl_add_u64 v[42:43], s[58:59], 0, v[180:181]
	s_mov_b32 m0, s56
	s_nop 0
	global_load_lds_dwordx4 v[42:43], off
	v_lshl_add_u64 v[42:43], s[58:59], 0, v[176:177]
	s_add_i32 m0, s56, 0x2000
	s_nop 0
	global_load_lds_dwordx4 v[42:43], off
	s_cmp_lg_u32 s24, -2
	s_cbranch_scc1 .Lrx_s5_std
	s_cmp_lt_u32 s95, 2
	s_cbranch_scc1 .Lrx_s5_std
	s_waitcnt vmcnt(22)
	s_branch .Lrx_s5_done
; #define PG8_STAGE(bufoff, gbase, voff) do { _Pragma("unroll") for (int _i = 0; _i < 2; ++_i) \
;         __builtin_amdgcn_global_load_lds((const unsigned*)((const char*)(gbase) + (voff)[_i]), (LAS unsigned*)(lds + (bufoff) + ldsw + _i * 8192), 16, 0, 0); } while (0)
; #define PG8_LDA(dst, b, h) do { _Pragma("unroll") for (int m = 0; m < 4; ++m) _Pragma("unroll") for (int k = 0; k < 2; ++k) dst[m][k] = *(const LAS bf16x8*)(lds + PG8_SA(b, h) + aoff + m * 2048 + k * 1024); } while (0)
; #define PG8_LDB(dst, b, h) do { _Pragma("unroll") for (int n = 0; n < 2; ++n) _Pragma("unroll") for (int k = 0; k < 2; ++k) dst[n][k] = *(const LAS bf16x8*)(lds + PG8_SB(b, h) + boff + n * 2048 + k * 1024); } while (0)
; #define PG8_MMA(ai, bj, At, Bt) do { __builtin_amdgcn_s_setprio(1); _Pragma("unroll") for (int m = 0; m < 4; ++m) _Pragma("unroll") for (int n = 0; n < 2; ++n) _Pragma("unroll") for (int k = 0; k < 2; ++k) \
;         acc[ai][bj][m][n] = __builtin_amdgcn_mfma_f32_16x16x32_bf16(Bt[n][k], At[m][k], acc[ai][bj][m][n], 0, 0, 0); __builtin_amdgcn_s_setprio(0); } while (0)
; #define PG8_WAIT_V(n) asm volatile("s_waitcnt vmcnt(" #n ")" ::: "memory")
; #define PG8_WAIT_L(n) asm volatile("s_waitcnt lgkmcnt(" #n ")" ::: "memory")
; #define PG8_BAR __builtin_amdgcn_s_barrier()
; #define PG8_SCHED __builtin_amdgcn_sched_barrier(0)
; template <class Epi>
; __device__ __forceinline__ void gemm_phase(LAS unsigned char* lds, const Gemm g, const StaticOrder& S, const Epi& E) {
;     ...
;             PG8_WAIT_V(6); PG8_BAR; PG8_MMA(1, 1, At, B1); PG8_BAR;
;             PG8_LDB(B0, 1, 0); PG8_SCHED; PG8_LDA(At, 1, 0); PG8_STAGE(PG8_SA(0, 1), a2 + hstep, voffA);
;             PG8_WAIT_L(8); PG8_BAR; PG8_WAIT_L(0); PG8_MMA(0, 0, At, B0); PG8_BAR; PG8_SCHED;
;             PG8_LDB(B1, 1, 1); PG8_STAGE(PG8_SB(1, 0), b3, voffB);
;             PG8_BAR; PG8_WAIT_L(0); PG8_MMA(0, 1, At, B1); PG8_BAR;
;             PG8_LDA(At, 1, 1); PG8_STAGE(PG8_SA(1, 0), a3, voffA);
;             PG8_BAR; PG8_WAIT_L(0); PG8_MMA(1, 0, At, B0); PG8_BAR; PG8_SCHED;
;             PG8_STAGE(PG8_SB(1, 1), b3 + hstep, voffB);
;             PG8_WAIT_V(6); PG8_BAR; PG8_MMA(1, 1, At, B1); PG8_BAR;
.Lrx_s5_std:
	s_waitcnt vmcnt(6)
.Lrx_s5_done:
	s_barrier
	s_setprio 1
	v_mfma_f32_16x16x32_bf16 v[34:37], v[202:205], v[134:137], v[34:37]
	v_mfma_f32_16x16x32_bf16 v[38:41], v[210:213], v[134:137], v[38:41]
	v_mfma_f32_16x16x32_bf16 v[18:21], v[202:205], v[172:175], v[18:21]
	v_mfma_f32_16x16x32_bf16 v[22:25], v[210:213], v[172:175], v[22:25]
	v_mfma_f32_16x16x32_bf16 v[2:5], v[202:205], v[194:197], v[2:5]
	v_mfma_f32_16x16x32_bf16 v[6:9], v[210:213], v[194:197], v[6:9]
	v_mfma_f32_16x16x32_bf16 v[42:45], v[202:205], v[114:117], v[86:89]
	v_mfma_f32_16x16x32_bf16 v[46:49], v[210:213], v[114:117], v[82:85]
	v_mfma_f32_16x16x32_bf16 v[34:37], v[206:209], v[146:149], v[34:37]
	v_mfma_f32_16x16x32_bf16 v[38:41], v[214:217], v[146:149], v[38:41]
	v_mfma_f32_16x16x32_bf16 v[18:21], v[206:209], v[190:193], v[18:21]
	v_mfma_f32_16x16x32_bf16 v[22:25], v[214:217], v[190:193], v[22:25]
	v_mfma_f32_16x16x32_bf16 v[2:5], v[206:209], v[198:201], v[2:5]
	v_mfma_f32_16x16x32_bf16 v[6:9], v[214:217], v[198:201], v[6:9]
	v_mfma_f32_16x16x32_bf16 v[42:45], v[206:209], v[130:133], v[42:45]
	v_mfma_f32_16x16x32_bf16 v[46:49], v[214:217], v[130:133], v[46:49]
	s_setprio 0
	s_add_i32 s56, 0, 0x18000
	v_add_u32_e32 v0, s56, v171
	s_barrier
	ds_read_b128 v[50:53], v0
	ds_read_b128 v[54:57], v0 offset:1024
	ds_read_b128 v[82:85], v0 offset:2048
	ds_read_b128 v[86:89], v0 offset:3072
	s_add_u32 s52, s52, 0x40000
	s_addc_u32 s53, s53, 0
	s_mov_b32 m0, s55
	v_lshl_add_u64 v[146:147], s[52:53], 0, v[182:183]
	ds_read_b128 v[114:117], v242 offset:32768
	ds_read_b128 v[130:133], v242 offset:33792
	ds_read_b128 v[134:137], v242 offset:34816
	ds_read_b128 v[172:175], v242 offset:35840
	ds_read_b128 v[190:193], v242 offset:36864
	ds_read_b128 v[194:197], v242 offset:37888
	ds_read_b128 v[198:201], v242 offset:38912
	ds_read_b128 v[202:205], v242 offset:39936
	global_load_lds_dwordx4 v[146:147], off
	v_lshl_add_u64 v[146:147], s[52:53], 0, v[178:179]
	s_mov_b32 m0, s70
	s_nop 0
	global_load_lds_dwordx4 v[146:147], off
	s_waitcnt lgkmcnt(8)
	s_barrier
	s_waitcnt lgkmcnt(0)
	s_setprio 1
	s_waitcnt lgkmcnt(0)
	v_mfma_f32_16x16x32_bf16 v[146:149], v[50:53], v[114:117], v[158:161]
	v_mfma_f32_16x16x32_bf16 v[158:161], v[54:57], v[130:133], v[146:149]
	v_mfma_f32_16x16x32_bf16 v[146:149], v[82:85], v[114:117], v[154:157]
	v_mfma_f32_16x16x32_bf16 v[142:145], v[50:53], v[134:137], v[142:145]
	v_mfma_f32_16x16x32_bf16 v[138:141], v[82:85], v[134:137], v[138:141]
	v_mfma_f32_16x16x32_bf16 v[126:129], v[50:53], v[190:193], v[126:129]
	v_mfma_f32_16x16x32_bf16 v[122:125], v[82:85], v[190:193], v[122:125]
	v_mfma_f32_16x16x32_bf16 v[110:113], v[50:53], v[198:201], v[110:113]
	v_mfma_f32_16x16x32_bf16 v[106:109], v[82:85], v[198:201], v[106:109]
	v_mfma_f32_16x16x32_bf16 v[154:157], v[86:89], v[130:133], v[146:149]
	v_mfma_f32_16x16x32_bf16 v[142:145], v[54:57], v[172:175], v[142:145]
	v_mfma_f32_16x16x32_bf16 v[138:141], v[86:89], v[172:175], v[138:141]
	v_mfma_f32_16x16x32_bf16 v[126:129], v[54:57], v[194:197], v[126:129]
	v_mfma_f32_16x16x32_bf16 v[122:125], v[86:89], v[194:197], v[122:125]
	v_mfma_f32_16x16x32_bf16 v[110:113], v[54:57], v[202:205], v[110:113]
	v_mfma_f32_16x16x32_bf16 v[106:109], v[86:89], v[202:205], v[106:109]
	s_setprio 0
	s_barrier
	s_add_i32 s52, 0, 0x1c000
	s_add_i32 s53, s56, s26
	v_add_u32_e32 v0, s52, v171
	v_lshl_add_u64 v[146:147], v[222:223], 0, s[28:29]
	s_mov_b32 m0, s53
	ds_read_b128 v[206:209], v0
	ds_read_b128 v[210:213], v0 offset:1024
	ds_read_b128 v[214:217], v0 offset:2048
	ds_read_b128 v[218:221], v0 offset:3072
	global_load_lds_dwordx4 v[146:147], off
	v_lshl_add_u64 v[146:147], v[246:247], 0, s[28:29]
	s_add_i32 m0, s53, 0x2000
	s_nop 0
	global_load_lds_dwordx4 v[146:147], off
	s_barrier
	s_waitcnt lgkmcnt(0)
	s_setprio 1
	s_waitcnt lgkmcnt(0)
	v_mfma_f32_16x16x32_bf16 v[146:149], v[206:209], v[114:117], v[150:153]
	v_mfma_f32_16x16x32_bf16 v[58:61], v[214:217], v[114:117], v[58:61]
	v_mfma_f32_16x16x32_bf16 v[150:153], v[210:213], v[130:133], v[146:149]
	v_mfma_f32_16x16x32_bf16 v[146:149], v[218:221], v[130:133], v[58:61]
	v_mfma_f32_16x16x32_bf16 v[58:61], v[206:209], v[134:137], v[62:65]
	v_mfma_f32_16x16x32_bf16 v[130:133], v[210:213], v[172:175], v[58:61]
	v_mfma_f32_16x16x32_bf16 v[58:61], v[214:217], v[134:137], v[70:73]
	v_mfma_f32_16x16x32_bf16 v[134:137], v[218:221], v[172:175], v[58:61]
	v_mfma_f32_16x16x32_bf16 v[58:61], v[206:209], v[190:193], v[74:77]
	v_mfma_f32_16x16x32_bf16 v[114:117], v[210:213], v[194:197], v[58:61]
	v_mfma_f32_16x16x32_bf16 v[58:61], v[214:217], v[190:193], v[118:121]
	v_mfma_f32_16x16x32_bf16 v[118:121], v[218:221], v[194:197], v[58:61]
	v_mfma_f32_16x16x32_bf16 v[58:61], v[206:209], v[198:201], v[98:101]
	v_mfma_f32_16x16x32_bf16 v[98:101], v[210:213], v[202:205], v[58:61]
	v_mfma_f32_16x16x32_bf16 v[58:61], v[214:217], v[198:201], v[102:105]
	v_mfma_f32_16x16x32_bf16 v[102:105], v[218:221], v[202:205], v[58:61]
	s_setprio 0
	s_mov_b32 m0, s93
	v_lshl_add_u64 v[202:203], v[248:249], 0, s[28:29]
	s_waitcnt vmcnt(10)
	s_barrier
	s_nop 2
	ds_read_b128 v[58:61], v242 offset:49152
	ds_read_b128 v[62:65], v242 offset:50176
	ds_read_b128 v[70:73], v242 offset:51200
	ds_read_b128 v[74:77], v242 offset:52224
	ds_read_b128 v[172:175], v242 offset:53248
	ds_read_b128 v[190:193], v242 offset:54272
	ds_read_b128 v[194:197], v242 offset:55296
	ds_read_b128 v[198:201], v242 offset:56320
	global_load_lds_dwordx4 v[202:203], off
	v_lshl_add_u64 v[202:203], v[236:237], 0, s[28:29]
	s_mov_b32 m0, s94
	s_nop 0
	global_load_lds_dwordx4 v[202:203], off
	s_barrier
; __device__ __forceinline__ float rstd_fix(u64 v) { return rsqrtf((float)v * (1.f / (1048576.f * 1024.f)) + 1e-6f); }
; #define PG8_STAGE(bufoff, gbase, voff) do { _Pragma("unroll") for (int _i = 0; _i < 2; ++_i) \
;         __builtin_amdgcn_global_load_lds((const unsigned*)((const char*)(gbase) + (voff)[_i]), (LAS unsigned*)(lds + (bufoff) + ldsw + _i * 8192), 16, 0, 0); } while (0)
; #define PG8_MMA(ai, bj, At, Bt) do { __builtin_amdgcn_s_setprio(1); _Pragma("unroll") for (int m = 0; m < 4; ++m) _Pragma("unroll") for (int n = 0; n < 2; ++n) _Pragma("unroll") for (int k = 0; k < 2; ++k) \
;         acc[ai][bj][m][n] = __builtin_amdgcn_mfma_f32_16x16x32_bf16(Bt[n][k], At[m][k], acc[ai][bj][m][n], 0, 0, 0); __builtin_amdgcn_s_setprio(0); } while (0)
; #define PG8_BAR __builtin_amdgcn_s_barrier()
; template <class Epi>
; __device__ __forceinline__ void gemm_phase(LAS unsigned char* lds, const Gemm g, const StaticOrder& S, const Epi& E) {
;     ...
;             PG8_BAR; PG8_WAIT_L(0); PG8_MMA(1, 0, At, B0); PG8_BAR; PG8_SCHED;
;             PG8_STAGE(PG8_SB(1, 1), b3 + hstep, voffB);
;             PG8_WAIT_V(6); PG8_BAR; PG8_MMA(1, 1, At, B1); PG8_BAR;
;     __device__ __forceinline__ void operator()(const f32x4 (&acc)[2][2][4][2], const Unit& u, int wr, int wc, int fr, int fq) const {
;         const int row0 = u.pm * BM + wr * 64 + fr, f0 = u.pn * HALF + wc * 32 + 8 * fq;
;         float w0[8], w1[8], w2[8], bb[8];
;         *(f32x4*)w0 = *(const f32x4*)(cw + f0); *(f32x4*)(w0 + 4) = *(const f32x4*)(cw + f0 + 4);
;         *(f32x4*)w1 = *(const f32x4*)(cw + DFF + f0); *(f32x4*)(w1 + 4) = *(const f32x4*)(cw + DFF + f0 + 4);
;         *(f32x4*)w2 = *(const f32x4*)(cw + 2 * DFF + f0); *(f32x4*)(w2 + 4) = *(const f32x4*)(cw + 2 * DFF + f0 + 4);
;         *(f32x4*)bb = *(const f32x4*)(cb + f0); *(f32x4*)(bb + 4) = *(const f32x4*)(cb + f0 + 4);
;         u64 rv[2][4];
; #pragma unroll
;         for (int ai = 0; ai < 2; ++ai)
; #pragma unroll
;             for (int m = 0; m < 4; ++m) rv[ai][m] = rss[row0 + ai * HALF + m * 16];
; #pragma unroll
;         for (int ai = 0; ai < 2; ++ai) {
;             float gp[8];
; #pragma unroll
;             for (int e = 0; e < 8; ++e) gp[e] = 0.f;
; #pragma unroll
;             for (int m = 0; m < 4; ++m) {
;                 const int row = row0 + ai * HALF + m * 16;
;                 const float rs = rstd_fix(rv[ai][m]);
	s_waitcnt lgkmcnt(0)
	s_setprio 1
	s_waitcnt lgkmcnt(0)
	v_mfma_f32_16x16x32_bf16 v[94:97], v[50:53], v[58:61], v[94:97]
	v_mfma_f32_16x16x32_bf16 v[90:93], v[82:85], v[58:61], v[90:93]
	v_mfma_f32_16x16x32_bf16 v[78:81], v[50:53], v[70:73], v[78:81]
	v_mfma_f32_16x16x32_bf16 v[66:69], v[82:85], v[70:73], v[66:69]
	v_mfma_f32_16x16x32_bf16 v[30:33], v[50:53], v[172:175], v[30:33]
	v_mfma_f32_16x16x32_bf16 v[26:29], v[82:85], v[172:175], v[26:29]
	v_mfma_f32_16x16x32_bf16 v[14:17], v[50:53], v[194:197], v[14:17]
	v_mfma_f32_16x16x32_bf16 v[10:13], v[82:85], v[194:197], v[10:13]
	v_mfma_f32_16x16x32_bf16 v[94:97], v[54:57], v[62:65], v[94:97]
	v_mfma_f32_16x16x32_bf16 v[90:93], v[86:89], v[62:65], v[90:93]
	v_mfma_f32_16x16x32_bf16 v[78:81], v[54:57], v[74:77], v[78:81]
	v_mfma_f32_16x16x32_bf16 v[66:69], v[86:89], v[74:77], v[66:69]
	v_mfma_f32_16x16x32_bf16 v[30:33], v[54:57], v[190:193], v[30:33]
	v_mfma_f32_16x16x32_bf16 v[26:29], v[86:89], v[190:193], v[26:29]
	v_mfma_f32_16x16x32_bf16 v[14:17], v[54:57], v[198:201], v[14:17]
	v_mfma_f32_16x16x32_bf16 v[10:13], v[86:89], v[198:201], v[10:13]
	s_setprio 0
	s_barrier
	s_add_u32 s36, s36, 0x40080
	s_addc_u32 s37, s37, 0
	s_add_i32 s52, s52, s26
	v_lshl_add_u64 v[50:51], s[36:37], 0, v[180:181]
	s_mov_b32 m0, s52
	s_nop 0
	global_load_lds_dwordx4 v[50:51], off
	v_lshl_add_u64 v[50:51], s[36:37], 0, v[176:177]
	s_add_i32 m0, s52, 0x2000
	s_nop 0
	global_load_lds_dwordx4 v[50:51], off
	s_waitcnt vmcnt(6)
	s_barrier
	s_setprio 1
	v_mfma_f32_16x16x32_bf16 v[42:45], v[206:209], v[58:61], v[42:45]
	v_mfma_f32_16x16x32_bf16 v[86:89], v[210:213], v[62:65], v[42:45]
	v_mfma_f32_16x16x32_bf16 v[42:45], v[214:217], v[58:61], v[46:49]
	v_mfma_f32_16x16x32_bf16 v[34:37], v[206:209], v[70:73], v[34:37]
	v_mfma_f32_16x16x32_bf16 v[38:41], v[214:217], v[70:73], v[38:41]
	v_mfma_f32_16x16x32_bf16 v[18:21], v[206:209], v[172:175], v[18:21]
	v_mfma_f32_16x16x32_bf16 v[22:25], v[214:217], v[172:175], v[22:25]
	v_mfma_f32_16x16x32_bf16 v[2:5], v[206:209], v[194:197], v[2:5]
	v_mfma_f32_16x16x32_bf16 v[6:9], v[214:217], v[194:197], v[6:9]
	v_mfma_f32_16x16x32_bf16 v[82:85], v[218:221], v[62:65], v[42:45]
	v_mfma_f32_16x16x32_bf16 v[34:37], v[210:213], v[74:77], v[34:37]
	v_mfma_f32_16x16x32_bf16 v[38:41], v[218:221], v[74:77], v[38:41]
	v_mfma_f32_16x16x32_bf16 v[18:21], v[210:213], v[190:193], v[18:21]
	v_mfma_f32_16x16x32_bf16 v[22:25], v[218:221], v[190:193], v[22:25]
	v_mfma_f32_16x16x32_bf16 v[2:5], v[210:213], v[198:201], v[2:5]
	v_mfma_f32_16x16x32_bf16 v[6:9], v[218:221], v[198:201], v[6:9]
	s_setprio 0
	s_add_i32 s24, s24, 2
	s_add_u32 s0, s0, 0x100
	s_addc_u32 s1, s1, 0
	s_add_u32 vcc_lo, vcc_lo, 0x100
	s_addc_u32 vcc_hi, vcc_hi, 0
	s_cmp_gt_u32 s24, 13
	s_barrier
	s_cbranch_scc0 .LBB0_211
	s_lshl_b32 s2, s2, 8
	s_add_i32 s2, s2, s71
	v_lshl_or_b32 v190, s3, 7, v241
	v_or_b32_e32 v196, s2, v168
	v_ashrrev_i32_e32 v191, 31, v190
	v_ashrrev_i32_e32 v197, 31, v196
	s_and_b32 s24, s95, 1
	s_lshl_b32 s24, s24, 12
	s_add_i32 s24, s24, 0x20400
	v_lshl_add_u32 v173, v241, 2, s24
	v_add_lshl_u32 v172, s71, v168, 3
	v_add_u32_e32 v172, s24, v172
	ds_read_b128 v[42:45], v173
	ds_read_b128 v[58:61], v173 offset:16
	ds_read_b128 v[46:49], v173 offset:512
	ds_read_b128 v[62:65], v173 offset:528
	ds_read_b128 v[50:53], v173 offset:1024
	ds_read_b128 v[70:73], v173 offset:1040
	ds_read_b128 v[54:57], v173 offset:1536
	ds_read_b128 v[74:77], v173 offset:1552
	ds_read_b64 v[174:175], v172 offset:2048
	ds_read_b64 v[206:207], v172 offset:2176
	ds_read_b64 v[204:205], v172 offset:2304
	ds_read_b64 v[202:203], v172 offset:2432
	ds_read_b64 v[200:201], v172 offset:3072
	ds_read_b64 v[198:199], v172 offset:3200
	ds_read_b64 v[194:195], v172 offset:3328
	ds_read_b64 v[192:193], v172 offset:3456
	v_mov_b32_e32 v217, v1
	v_mov_b32_e32 v219, v1
	s_waitcnt lgkmcnt(0)
	v_ffbh_u32_e32 v0, v175
	v_min_u32_e32 v0, 32, v0
	v_lshlrev_b64 v[172:173], v0, v[174:175]
	v_min_u32_e32 v172, 1, v172
	v_or_b32_e32 v172, v173, v172
	v_cvt_f32_u32_e32 v172, v172
	v_sub_u32_e32 v0, 32, v0
	v_mov_b32_dpp v217, v217 row_ror:1 row_mask:0xf bank_mask:0xf
	v_mov_b32_dpp v219, v219 row_ror:2 row_mask:0xf bank_mask:0xf
	v_ldexp_f32 v0, v172, v0
	v_fmamk_f32 v0, v0, 0x30800000, v162
	v_cmp_gt_f32_e32 vcc, s79, v0
	v_mul_f32_e32 v172, 0x4b800000, v0
	v_mov_b32_e32 v212, v217
	v_cndmask_b32_e32 v0, v0, v172, vcc
	v_rsq_f32_e32 v0, v0
	v_mov_b32_e32 v213, v217
	v_mov_b32_e32 v214, v219
	v_mov_b32_e32 v215, v219
	v_mul_f32_e32 v172, 0x45800000, v0
	v_cndmask_b32_e32 v0, v0, v172, vcc
	v_pk_mul_f32 v[158:159], v[158:159], v[0:1] op_sel_hi:[1,0]
	v_pk_mul_f32 v[154:155], v[154:155], v[0:1] op_sel_hi:[1,0]
	v_pk_mul_f32 v[208:209], v[150:151], v[0:1] op_sel_hi:[1,0]
	v_pk_mul_f32 v[210:211], v[146:147], v[0:1] op_sel_hi:[1,0]
	v_pk_mul_f32 v[150:151], v[160:161], v[0:1] op_sel_hi:[1,0]
	v_pk_mul_f32 v[146:147], v[156:157], v[0:1] op_sel_hi:[1,0]
	v_mov_b32_e32 v156, v217
	v_mov_b32_e32 v157, v217
	v_mov_b32_e32 v160, v219
	v_mov_b32_e32 v161, v219
	v_mov_b32_e32 v220, v217
	v_mov_b32_e32 v221, v217
	v_mov_b32_e32 v222, v219
	v_mov_b32_e32 v223, v219
	v_mov_b32_e32 v216, v217
	v_mov_b32_e32 v218, v219
	v_pk_mul_f32 v[152:153], v[152:153], v[0:1] op_sel_hi:[1,0]
	v_pk_mul_f32 v[148:149], v[148:149], v[0:1] op_sel_hi:[1,0]
	v_mov_b32_dpp v156, v158 row_shr:1 row_mask:0xf bank_mask:0xf
	v_mov_b32_dpp v157, v159 row_shr:1 row_mask:0xf bank_mask:0xf
	v_mov_b32_dpp v160, v158 row_shr:2 row_mask:0xf bank_mask:0xf
	v_mov_b32_dpp v161, v159 row_shr:2 row_mask:0xf bank_mask:0xf
	v_mov_b32_dpp v212, v150 row_shr:1 row_mask:0xf bank_mask:0xf
	v_mov_b32_dpp v213, v151 row_shr:1 row_mask:0xf bank_mask:0xf
	v_mov_b32_dpp v214, v150 row_shr:2 row_mask:0xf bank_mask:0xf
	v_mov_b32_dpp v215, v151 row_shr:2 row_mask:0xf bank_mask:0xf
	v_mov_b32_dpp v220, v154 row_shr:1 row_mask:0xf bank_mask:0xf
	v_mov_b32_dpp v221, v155 row_shr:1 row_mask:0xf bank_mask:0xf
	v_mov_b32_dpp v222, v154 row_shr:2 row_mask:0xf bank_mask:0xf
	v_mov_b32_dpp v223, v155 row_shr:2 row_mask:0xf bank_mask:0xf
	v_mov_b32_dpp v216, v146 row_shr:1 row_mask:0xf bank_mask:0xf
	v_mov_b32_dpp v217, v147 row_shr:1 row_mask:0xf bank_mask:0xf
	v_mov_b32_dpp v218, v146 row_shr:2 row_mask:0xf bank_mask:0xf
	v_mov_b32_dpp v219, v147 row_shr:2 row_mask:0xf bank_mask:0xf
	s_and_saveexec_b64 s[0:1], s[40:41]
	s_xor_b64 s[0:1], exec, s[0:1]
	s_cbranch_execz .LBB0_214
; __device__ __forceinline__ u32x4 pack8(const float* f) { u32x4 w; w.x = pk2(f[0], f[1]); w.y = pk2(f[2], f[3]); w.z = pk2(f[4], f[5]); w.w = pk2(f[6], f[7]); return w; }
; template <int N> __device__ __forceinline__ float dpp_shr(float old, float src) { return __int_as_float(__builtin_amdgcn_update_dpp(__float_as_int(old), __float_as_int(src), 0x110 + N, 0xf, 0xf, false)); }
; template <int N> __device__ __forceinline__ float dpp_ror(float src) { return __int_as_float(__builtin_amdgcn_update_dpp(0, __float_as_int(src), 0x120 + N, 0xf, 0xf, false)); }
;     __device__ __forceinline__ void operator()(const f32x4 (&acc)[2][2][4][2], const Unit& u, int wr, int wc, int fr, int fq) const {
;     ...
;                 for (int e2 = 0; e2 < 4; ++e2) {
;                     const int e = 2 * e2;
;                     const f32x2 gv = {g[e], g[e + 1]};
;                     const f32x2 g1v = {dpp_shr<1>(dpp_ror<1>(gp[e]), g[e]), dpp_shr<1>(dpp_ror<1>(gp[e + 1]), g[e + 1])};
;                     const f32x2 g2v = {dpp_shr<2>(dpp_ror<2>(gp[e]), g[e]), dpp_shr<2>(dpp_ror<2>(gp[e + 1]), g[e + 1])};
;                     const f32x2 w0v = {w0[e], w0[e + 1]}, w1v = {w1[e], w1[e + 1]}, w2v = {w2[e], w2[e + 1]}, bbv = {bb[e], bb[e + 1]}, upv = {up[e], up[e + 1]};
;                     const f32x2 y = __builtin_elementwise_fma(w0v, g2v, __builtin_elementwise_fma(w1v, g1v, __builtin_elementwise_fma(w2v, gv, bbv)));
;                     const f32x2 z = y * __builtin_elementwise_fma(y * y, (f32x2){0.1029432397f, 0.1029432397f}, (f32x2){2.302208198f, 2.302208198f});
;                     f32x2 d; d.x = __builtin_amdgcn_exp2f(z.x); d.y = __builtin_amdgcn_exp2f(z.y);
;                     d = d + 1.0f;
;                     f32x2 r; r.x = __builtin_amdgcn_rcpf(d.x); r.y = __builtin_amdgcn_rcpf(d.y);
;                     const f32x2 ov = __builtin_elementwise_fma(-y, r, y) * upv;
;                     o[e] = ov.x; o[e + 1] = ov.y;
;                 }
;                 if (m == 0 && fr < 2) {
;                     const size_t so = ((size_t)(row >> 6) * 2 + fr) * DFF + f0;
;                     *(u32x4*)(gs01 + so) = pack8(g); *(u32x4*)(us01 + so) = pack8(up);
;                 } else *(u32x4*)(act + (size_t)row * DFF + f0) = pack8(o);
	v_pk_fma_f32 v[172:173], v[72:73], v[146:147], v[76:77]
	s_mov_b32 s24, 0x40135761
	v_pk_fma_f32 v[172:173], v[64:65], v[216:217], v[172:173]
	v_mov_b64_e32 v[216:217], s[24:25]
	v_pk_fma_f32 v[172:173], v[60:61], v[218:219], v[172:173]
	s_mov_b32 s24, 0x3dd2d3e8
	v_pk_mul_f32 v[174:175], v[172:173], v[172:173]
	v_readlane_b32 s36, v252, 57
	v_pk_fma_f32 v[174:175], v[174:175], s[24:25], v[216:217] op_sel_hi:[1,0,0]
	v_readlane_b32 s37, v252, 58
	v_pk_mul_f32 v[174:175], v[172:173], v[174:175]
	s_movk_i32 s3, 0x1600
	v_exp_f32_e32 v174, v174
	v_exp_f32_e32 v175, v175
	s_nop 0
	v_pk_add_f32 v[174:175], v[174:175], 1.0 op_sel_hi:[1,0]
	s_nop 0
	v_rcp_f32_e32 v174, v174
	v_rcp_f32_e32 v175, v175
	s_nop 0
	v_pk_fma_f32 v[172:173], v[172:173], v[174:175], v[172:173] neg_lo:[1,0,0] neg_hi:[1,0,0]
	s_nop 0
	v_pk_mul_f32 v[148:149], v[148:149], v[172:173]
	v_pk_fma_f32 v[172:173], v[70:71], v[154:155], v[74:75]
	s_nop 0
	v_pk_fma_f32 v[172:173], v[62:63], v[220:221], v[172:173]
	s_nop 0
	v_pk_fma_f32 v[172:173], v[58:59], v[222:223], v[172:173]
	s_nop 0
	v_pk_mul_f32 v[174:175], v[172:173], v[172:173]
	s_nop 0
	v_pk_fma_f32 v[174:175], v[174:175], s[24:25], v[216:217] op_sel_hi:[1,0,0]
	s_nop 0
	v_pk_mul_f32 v[174:175], v[172:173], v[174:175]
	s_nop 0
	v_exp_f32_e32 v174, v174
	v_exp_f32_e32 v175, v175
	s_nop 0
	v_pk_add_f32 v[174:175], v[174:175], 1.0 op_sel_hi:[1,0]
	s_nop 0
	v_rcp_f32_e32 v174, v174
	v_rcp_f32_e32 v175, v175
	s_nop 0
	v_pk_fma_f32 v[172:173], v[172:173], v[174:175], v[172:173] neg_lo:[1,0,0] neg_hi:[1,0,0]
	s_nop 0
	v_pk_mul_f32 v[174:175], v[210:211], v[172:173]
	v_pk_fma_f32 v[172:173], v[52:53], v[150:151], v[56:57]
	s_nop 0
	v_pk_fma_f32 v[172:173], v[48:49], v[212:213], v[172:173]
	s_nop 0
	v_pk_fma_f32 v[172:173], v[44:45], v[214:215], v[172:173]
	s_nop 0
	v_pk_mul_f32 v[210:211], v[172:173], v[172:173]
	s_nop 0
	v_pk_fma_f32 v[210:211], v[210:211], s[24:25], v[216:217] op_sel_hi:[1,0,0]
	s_nop 0
	v_pk_mul_f32 v[210:211], v[172:173], v[210:211]
	s_nop 0
	v_exp_f32_e32 v210, v210
	v_exp_f32_e32 v211, v211
	s_nop 0
	v_pk_add_f32 v[210:211], v[210:211], 1.0 op_sel_hi:[1,0]
	s_nop 0
	v_rcp_f32_e32 v210, v210
	v_rcp_f32_e32 v211, v211
	s_nop 0
	v_pk_fma_f32 v[172:173], v[172:173], v[210:211], v[172:173] neg_lo:[1,0,0] neg_hi:[1,0,0]
	s_nop 0
	v_pk_mul_f32 v[152:153], v[152:153], v[172:173]
	v_pk_fma_f32 v[172:173], v[50:51], v[158:159], v[54:55]
	s_nop 0
	v_pk_fma_f32 v[156:157], v[46:47], v[156:157], v[172:173]
	s_nop 0
	v_pk_fma_f32 v[156:157], v[42:43], v[160:161], v[156:157]
	s_nop 0
	v_pk_mul_f32 v[160:161], v[156:157], v[156:157]
	s_nop 0
	v_pk_fma_f32 v[160:161], v[160:161], s[24:25], v[216:217] op_sel_hi:[1,0,0]
	s_nop 0
	v_pk_mul_f32 v[160:161], v[156:157], v[160:161]
	s_nop 0
	v_exp_f32_e32 v160, v160
	v_exp_f32_e32 v161, v161
	s_nop 0
	v_pk_add_f32 v[160:161], v[160:161], 1.0 op_sel_hi:[1,0]
	s_nop 0
	v_rcp_f32_e32 v160, v160
	v_rcp_f32_e32 v161, v161
	s_nop 0
	v_pk_fma_f32 v[156:157], v[156:157], v[160:161], v[156:157] neg_lo:[1,0,0] neg_hi:[1,0,0]
	s_nop 0
	v_pk_mul_f32 v[156:157], v[208:209], v[156:157]
	s_nop 0
	v_cvt_pk_bf16_f32 v172, v156, v157
	v_cvt_pk_bf16_f32 v173, v152, v153
	v_cvt_pk_bf16_f32 v174, v174, v175
	v_cvt_pk_bf16_f32 v175, v148, v149
	v_mov_b64_e32 v[148:149], s[36:37]
	v_mad_i64_i32 v[148:149], s[36:37], v196, s3, v[148:149]
	v_lshl_add_u64 v[148:149], v[190:191], 1, v[148:149]
	global_store_dwordx4 v[148:149], v[172:175], off nt
.LBB0_214:
	s_or_saveexec_b64 s[0:1], s[0:1]
	s_ashr_i32 s36, s2, 6
	s_ashr_i32 s37, s36, 31
	s_lshl_b64 s[36:37], s[36:37], 1
	s_movk_i32 s97, 0x6000
	s_mov_b32 s96, 0xa000
	s_xor_b64 exec, exec, s[0:1]
	s_cbranch_execz .LBB0_216
	v_or_b32_e32 v0, s36, v168
	s_movk_i32 s3, 0xb00
	v_mad_i64_i32 v[156:157], s[52:53], v0, s3, v[190:191]
	v_readlane_b32 s52, v250, 16
	v_lshlrev_b64 v[156:157], 1, v[156:157]
	v_readlane_b32 s53, v250, 17
	v_cvt_pk_bf16_f32 v172, v158, v159
	v_cvt_pk_bf16_f32 v173, v150, v151
	v_cvt_pk_bf16_f32 v174, v154, v155
	v_cvt_pk_bf16_f32 v175, v146, v147
	s_nop 1
	v_lshl_add_u64 v[160:161], s[52:53], 0, v[156:157]
	v_readlane_b32 s52, v250, 18
	v_readlane_b32 s53, v250, 19
	global_store_dwordx4 v[160:161], v[172:175], off nt
	s_nop 1
	v_cvt_pk_bf16_f32 v172, v208, v209
	v_cvt_pk_bf16_f32 v173, v152, v153
	v_cvt_pk_bf16_f32 v174, v210, v211
	v_cvt_pk_bf16_f32 v175, v148, v149
	v_lshl_add_u64 v[148:149], s[52:53], 0, v[156:157]
	global_store_dwordx4 v[148:149], v[172:175], off nt
; __device__ __forceinline__ float rstd_fix(u64 v) { return rsqrtf((float)v * (1.f / (1048576.f * 1024.f)) + 1e-6f); }
; template <int N> __device__ __forceinline__ float dpp_shr(float old, float src) { return __int_as_float(__builtin_amdgcn_update_dpp(__float_as_int(old), __float_as_int(src), 0x110 + N, 0xf, 0xf, false)); }
;     __device__ __forceinline__ void operator()(const f32x4 (&acc)[2][2][4][2], const Unit& u, int wr, int wc, int fr, int fq) const {
;     ...
; #pragma unroll
;             for (int m = 0; m < 4; ++m) {
;                 const int row = row0 + ai * HALF + m * 16;
;                 const float rs = rstd_fix(rv[ai][m]);
;                 float g[8], up[8], o[8];
;                 { const f32x4 g0 = acc[ai][0][m][0] * rs, g1 = acc[ai][0][m][1] * rs, u0 = acc[ai][1][m][0] * rs, u1 = acc[ai][1][m][1] * rs;
; #pragma unroll
;                   for (int i = 0; i < 4; ++i) { g[i] = g0[i]; g[4 + i] = g1[i]; up[i] = u0[i]; up[4 + i] = u1[i]; } }
; #pragma unroll
;                 for (int e2 = 0; e2 < 4; ++e2) {
;                     const int e = 2 * e2;
;                     const f32x2 gv = {g[e], g[e + 1]};
;                     const f32x2 g1v = {dpp_shr<1>(dpp_ror<1>(gp[e]), g[e]), dpp_shr<1>(dpp_ror<1>(gp[e + 1]), g[e + 1])};
;                     const f32x2 g2v = {dpp_shr<2>(dpp_ror<2>(gp[e]), g[e]), dpp_shr<2>(dpp_ror<2>(gp[e + 1]), g[e + 1])};
;                     const f32x2 w0v = {w0[e], w0[e + 1]}, w1v = {w1[e], w1[e + 1]}, w2v = {w2[e], w2[e + 1]}, bbv = {bb[e], bb[e + 1]}, upv = {up[e], up[e + 1]};
;                     const f32x2 y = __builtin_elementwise_fma(w0v, g2v, __builtin_elementwise_fma(w1v, g1v, __builtin_elementwise_fma(w2v, gv, bbv)));
;                     const f32x2 z = y * __builtin_elementwise_fma(y * y, (f32x2){0.1029432397f, 0.1029432397f}, (f32x2){2.302208198f, 2.302208198f});
;                     f32x2 d; d.x = __builtin_amdgcn_exp2f(z.x); d.y = __builtin_amdgcn_exp2f(z.y);
;                     d = d + 1.0f;
;                     f32x2 r; r.x = __builtin_amdgcn_rcpf(d.x); r.y = __builtin_amdgcn_rcpf(d.y);
;                     const f32x2 ov = __builtin_elementwise_fma(-y, r, y) * upv;
;                     o[e] = ov.x; o[e + 1] = ov.y;
;                 }
.LBB0_216:
	s_or_b64 exec, exec, s[0:1]
	v_ffbh_u32_e32 v148, v207
	v_min_u32_e32 v152, 32, v148
	v_lshlrev_b64 v[148:149], v152, v[206:207]
	v_min_u32_e32 v148, 1, v148
	v_or_b32_e32 v148, v149, v148
	v_cvt_f32_u32_e32 v148, v148
	v_sub_u32_e32 v149, 32, v152
	s_mov_b32 s3, 0x800000
	v_mov_b32_e32 v156, v1
	v_ldexp_f32 v148, v148, v149
	v_fmamk_f32 v148, v148, 0x30800000, v162
	v_cmp_gt_f32_e32 vcc, s3, v148
	v_mul_f32_e32 v149, 0x4b800000, v148
	v_mov_b32_e32 v157, v1
	v_cndmask_b32_e32 v148, v148, v149, vcc
	v_rsq_f32_e32 v148, v148
	v_mov_b32_dpp v156, v158 row_ror:2 row_mask:0xf bank_mask:0xf
	v_mov_b32_dpp v157, v159 row_ror:2 row_mask:0xf bank_mask:0xf
	v_mov_b32_e32 v160, v1
	v_mul_f32_e32 v149, 0x45800000, v148
	v_cndmask_b32_e32 v152, v148, v149, vcc
	v_pk_mul_f32 v[148:149], v[142:143], v[152:153] op_sel_hi:[1,0]
	v_pk_mul_f32 v[142:143], v[138:139], v[152:153] op_sel_hi:[1,0]
	v_pk_mul_f32 v[138:139], v[140:141], v[152:153] op_sel_hi:[1,0]
	v_mov_b32_e32 v140, v1
	v_mov_b32_e32 v141, v1
	v_mov_b32_e32 v161, v1
	v_mov_b32_dpp v140, v158 row_ror:1 row_mask:0xf bank_mask:0xf
	v_mov_b32_dpp v141, v159 row_ror:1 row_mask:0xf bank_mask:0xf
	v_mov_b32_e32 v158, v1
	v_mov_b32_e32 v159, v1
	v_mov_b32_dpp v160, v150 row_ror:2 row_mask:0xf bank_mask:0xf
	v_mov_b32_dpp v158, v150 row_ror:1 row_mask:0xf bank_mask:0xf
	v_mov_b32_dpp v159, v151 row_ror:1 row_mask:0xf bank_mask:0xf
	v_mov_b32_dpp v161, v151 row_ror:2 row_mask:0xf bank_mask:0xf
	v_mov_b32_e32 v150, v1
	v_mov_b32_e32 v151, v1
	v_mov_b32_e32 v172, v1
	v_mov_b32_e32 v173, v1
	v_mov_b32_dpp v150, v154 row_ror:1 row_mask:0xf bank_mask:0xf
	v_mov_b32_dpp v151, v155 row_ror:1 row_mask:0xf bank_mask:0xf
	v_mov_b32_dpp v172, v154 row_ror:2 row_mask:0xf bank_mask:0xf
	v_mov_b32_dpp v173, v155 row_ror:2 row_mask:0xf bank_mask:0xf
	v_mov_b32_e32 v154, v1
	v_mov_b32_e32 v155, v1
	v_mov_b32_e32 v174, v1
	v_mov_b32_dpp v154, v146 row_ror:1 row_mask:0xf bank_mask:0xf
	v_mov_b32_dpp v155, v147 row_ror:1 row_mask:0xf bank_mask:0xf
	v_mov_b32_e32 v175, v1
	v_mov_b32_dpp v154, v138 row_shr:1 row_mask:0xf bank_mask:0xf
	v_mov_b32_dpp v155, v139 row_shr:1 row_mask:0xf bank_mask:0xf
	v_mov_b32_dpp v174, v146 row_ror:2 row_mask:0xf bank_mask:0xf
	v_mov_b32_dpp v175, v147 row_ror:2 row_mask:0xf bank_mask:0xf
	v_pk_mul_f32 v[146:147], v[136:137], v[152:153] op_sel_hi:[1,0]
	v_pk_fma_f32 v[136:137], v[72:73], v[138:139], v[76:77]
	v_mov_b32_dpp v174, v138 row_shr:2 row_mask:0xf bank_mask:0xf
	v_mov_b32_dpp v175, v139 row_shr:2 row_mask:0xf bank_mask:0xf
	v_pk_fma_f32 v[136:137], v[64:65], v[154:155], v[136:137]
	s_mov_b32 s0, 0x40135761
	v_pk_fma_f32 v[154:155], v[60:61], v[174:175], v[136:137]
	v_mov_b64_e32 v[136:137], s[0:1]
	v_pk_mul_f32 v[174:175], v[154:155], v[154:155]
	s_mov_b32 s56, 0x3dd2d3e8
	v_pk_fma_f32 v[174:175], v[174:175], s[56:57], v[136:137] op_sel_hi:[1,0,0]
	v_mov_b32_dpp v150, v142 row_shr:1 row_mask:0xf bank_mask:0xf
	v_pk_mul_f32 v[174:175], v[154:155], v[174:175]
	v_mov_b32_dpp v151, v143 row_shr:1 row_mask:0xf bank_mask:0xf
	v_exp_f32_e32 v174, v174
	v_exp_f32_e32 v175, v175
	v_mov_b32_dpp v172, v142 row_shr:2 row_mask:0xf bank_mask:0xf
	v_mov_b32_dpp v173, v143 row_shr:2 row_mask:0xf bank_mask:0xf
	v_pk_mul_f32 v[144:145], v[144:145], v[152:153] op_sel_hi:[1,0]
	v_pk_add_f32 v[174:175], v[174:175], 1.0 op_sel_hi:[1,0]
	v_pk_mul_f32 v[134:135], v[134:135], v[152:153] op_sel_hi:[1,0]
	v_rcp_f32_e32 v174, v174
	v_rcp_f32_e32 v175, v175
	v_mov_b32_dpp v158, v144 row_shr:1 row_mask:0xf bank_mask:0xf
	v_mov_b32_dpp v159, v145 row_shr:1 row_mask:0xf bank_mask:0xf
	v_mov_b32_dpp v160, v144 row_shr:2 row_mask:0xf bank_mask:0xf
	v_pk_fma_f32 v[154:155], v[154:155], v[174:175], v[154:155] neg_lo:[1,0,0] neg_hi:[1,0,0]
	v_mov_b32_dpp v161, v145 row_shr:2 row_mask:0xf bank_mask:0xf
	v_pk_mul_f32 v[146:147], v[146:147], v[154:155]
	v_pk_fma_f32 v[154:155], v[70:71], v[142:143], v[74:75]
	v_pk_mul_f32 v[132:133], v[132:133], v[152:153] op_sel_hi:[1,0]
	v_pk_fma_f32 v[150:151], v[62:63], v[150:151], v[154:155]
	v_mov_b32_dpp v140, v148 row_shr:1 row_mask:0xf bank_mask:0xf
	v_pk_fma_f32 v[150:151], v[58:59], v[172:173], v[150:151]
	v_mov_b32_dpp v141, v149 row_shr:1 row_mask:0xf bank_mask:0xf
	v_pk_mul_f32 v[154:155], v[150:151], v[150:151]
	v_mov_b32_dpp v156, v148 row_shr:2 row_mask:0xf bank_mask:0xf
	v_pk_fma_f32 v[154:155], v[154:155], s[56:57], v[136:137] op_sel_hi:[1,0,0]
	v_mov_b32_dpp v157, v149 row_shr:2 row_mask:0xf bank_mask:0xf
	v_pk_mul_f32 v[154:155], v[150:151], v[154:155]
	v_readlane_b32 s0, v252, 57
	v_exp_f32_e32 v154, v154
	v_exp_f32_e32 v155, v155
	v_pk_mul_f32 v[130:131], v[130:131], v[152:153] op_sel_hi:[1,0]
	v_readlane_b32 s1, v252, 58
	v_or_b32_e32 v197, 16, v196
	v_pk_add_f32 v[154:155], v[154:155], 1.0 op_sel_hi:[1,0]
	s_movk_i32 s52, 0x1600
	v_rcp_f32_e32 v154, v154
	v_rcp_f32_e32 v155, v155
	v_or_b32_e32 v208, 32, v196
	v_or_b32_e32 v0, 48, v196
	s_mov_b32 s24, 0x800000
	v_pk_fma_f32 v[150:151], v[150:151], v[154:155], v[150:151] neg_lo:[1,0,0] neg_hi:[1,0,0]
	s_movk_i32 s58, 0x1600
	v_pk_mul_f32 v[134:135], v[134:135], v[150:151]
	v_pk_fma_f32 v[150:151], v[52:53], v[144:145], v[56:57]
	s_nop 0
	v_pk_fma_f32 v[150:151], v[48:49], v[158:159], v[150:151]
	s_nop 0
	v_pk_fma_f32 v[150:151], v[44:45], v[160:161], v[150:151]
	s_nop 0
	v_pk_mul_f32 v[154:155], v[150:151], v[150:151]
	s_nop 0
	v_pk_fma_f32 v[154:155], v[154:155], s[56:57], v[136:137] op_sel_hi:[1,0,0]
	s_nop 0
	v_pk_mul_f32 v[154:155], v[150:151], v[154:155]
	s_nop 0
	v_exp_f32_e32 v154, v154
	v_exp_f32_e32 v155, v155
	s_nop 0
	v_pk_add_f32 v[154:155], v[154:155], 1.0 op_sel_hi:[1,0]
	s_nop 0
; __device__ __forceinline__ float rstd_fix(u64 v) { return rsqrtf((float)v * (1.f / (1048576.f * 1024.f)) + 1e-6f); }
; __device__ __forceinline__ u32x4 pack8(const float* f) { u32x4 w; w.x = pk2(f[0], f[1]); w.y = pk2(f[2], f[3]); w.z = pk2(f[4], f[5]); w.w = pk2(f[6], f[7]); return w; }
; template <int N> __device__ __forceinline__ float dpp_ror(float src) { return __int_as_float(__builtin_amdgcn_update_dpp(0, __float_as_int(src), 0x120 + N, 0xf, 0xf, false)); }
;     __device__ __forceinline__ void operator()(const f32x4 (&acc)[2][2][4][2], const Unit& u, int wr, int wc, int fr, int fq) const {
;     ...
; #pragma unroll
;             for (int m = 0; m < 4; ++m) {
;                 const int row = row0 + ai * HALF + m * 16;
;                 const float rs = rstd_fix(rv[ai][m]);
;                 float g[8], up[8], o[8];
;                 { const f32x4 g0 = acc[ai][0][m][0] * rs, g1 = acc[ai][0][m][1] * rs, u0 = acc[ai][1][m][0] * rs, u1 = acc[ai][1][m][1] * rs;
; #pragma unroll
;                   for (int i = 0; i < 4; ++i) { g[i] = g0[i]; g[4 + i] = g1[i]; up[i] = u0[i]; up[4 + i] = u1[i]; } }
; #pragma unroll
;                 for (int e2 = 0; e2 < 4; ++e2) {
;                     const int e = 2 * e2;
;                     const f32x2 gv = {g[e], g[e + 1]};
;                     const f32x2 g1v = {dpp_shr<1>(dpp_ror<1>(gp[e]), g[e]), dpp_shr<1>(dpp_ror<1>(gp[e + 1]), g[e + 1])};
;     ...
;                     const f32x2 y = __builtin_elementwise_fma(w0v, g2v, __builtin_elementwise_fma(w1v, g1v, __builtin_elementwise_fma(w2v, gv, bbv)));
;                     const f32x2 z = y * __builtin_elementwise_fma(y * y, (f32x2){0.1029432397f, 0.1029432397f}, (f32x2){2.302208198f, 2.302208198f});
;                     f32x2 d; d.x = __builtin_amdgcn_exp2f(z.x); d.y = __builtin_amdgcn_exp2f(z.y);
;                     d = d + 1.0f;
;                     f32x2 r; r.x = __builtin_amdgcn_rcpf(d.x); r.y = __builtin_amdgcn_rcpf(d.y);
;                     const f32x2 ov = __builtin_elementwise_fma(-y, r, y) * upv;
;                     o[e] = ov.x; o[e + 1] = ov.y;
;                 }
;                 if (m == 0 && fr < 2) {
;                     const size_t so = ((size_t)(row >> 6) * 2 + fr) * DFF + f0;
;                     *(u32x4*)(gs01 + so) = pack8(g); *(u32x4*)(us01 + so) = pack8(up);
;                 } else *(u32x4*)(act + (size_t)row * DFF + f0) = pack8(o);
	v_rcp_f32_e32 v154, v154
	v_rcp_f32_e32 v155, v155
	s_nop 0
	v_pk_fma_f32 v[150:151], v[150:151], v[154:155], v[150:151] neg_lo:[1,0,0] neg_hi:[1,0,0]
	s_nop 0
	v_pk_mul_f32 v[132:133], v[132:133], v[150:151]
	v_pk_fma_f32 v[150:151], v[50:51], v[148:149], v[54:55]
	v_mov_b32_e32 v154, v1
	v_pk_fma_f32 v[140:141], v[46:47], v[140:141], v[150:151]
	v_mov_b32_e32 v155, v1
	v_pk_fma_f32 v[140:141], v[42:43], v[156:157], v[140:141]
	v_mov_b32_dpp v154, v142 row_ror:2 row_mask:0xf bank_mask:0xf
	v_pk_mul_f32 v[150:151], v[140:141], v[140:141]
	v_mov_b32_dpp v155, v143 row_ror:2 row_mask:0xf bank_mask:0xf
	v_pk_fma_f32 v[150:151], v[150:151], s[56:57], v[136:137] op_sel_hi:[1,0,0]
	v_mov_b32_e32 v156, v1
	v_pk_mul_f32 v[150:151], v[140:141], v[150:151]
	v_mov_b32_e32 v157, v1
	v_exp_f32_e32 v150, v150
	v_exp_f32_e32 v151, v151
	v_mov_b32_dpp v156, v138 row_ror:2 row_mask:0xf bank_mask:0xf
	v_mov_b32_dpp v157, v139 row_ror:2 row_mask:0xf bank_mask:0xf
	v_pk_add_f32 v[150:151], v[150:151], 1.0 op_sel_hi:[1,0]
	s_nop 0
	v_rcp_f32_e32 v150, v150
	v_rcp_f32_e32 v151, v151
	s_nop 0
	v_pk_fma_f32 v[140:141], v[140:141], v[150:151], v[140:141] neg_lo:[1,0,0] neg_hi:[1,0,0]
	s_nop 0
	v_pk_mul_f32 v[130:131], v[130:131], v[140:141]
	s_nop 0
	v_cvt_pk_bf16_f32 v150, v130, v131
	v_cvt_pk_bf16_f32 v151, v132, v133
	v_mov_b64_e32 v[132:133], s[0:1]
	v_cvt_pk_bf16_f32 v152, v134, v135
	v_mad_i64_i32 v[134:135], s[0:1], v197, s52, v[132:133]
	v_lshlrev_b64 v[130:131], 1, v[190:191]
	v_lshl_add_u64 v[134:135], v[134:135], 0, v[130:131]
	v_cvt_pk_bf16_f32 v153, v146, v147
	global_store_dwordx4 v[134:135], v[150:153], off nt
	v_ffbh_u32_e32 v134, v205
	v_min_u32_e32 v140, 32, v134
	v_lshlrev_b64 v[134:135], v140, v[204:205]
	v_min_u32_e32 v134, 1, v134
	v_or_b32_e32 v134, v135, v134
	v_cvt_f32_u32_e32 v134, v134
	v_sub_u32_e32 v135, 32, v140
	v_mov_b32_e32 v146, v1
	v_mov_b32_e32 v147, v1
	v_ldexp_f32 v135, v134, v135
	v_ffbh_u32_e32 v134, v203
	v_min_u32_e32 v134, 32, v134
	v_lshlrev_b64 v[140:141], v134, v[202:203]
	v_min_u32_e32 v140, 1, v140
	v_or_b32_e32 v140, v141, v140
	v_mov_b32_e32 v150, v1
	v_mov_b32_e32 v151, v1
	v_cvt_f32_u32_e32 v140, v140
	v_mov_b32_dpp v146, v148 row_ror:1 row_mask:0xf bank_mask:0xf
	v_mov_b32_dpp v147, v149 row_ror:1 row_mask:0xf bank_mask:0xf
	v_mov_b32_dpp v150, v148 row_ror:2 row_mask:0xf bank_mask:0xf
	v_mov_b32_dpp v151, v149 row_ror:2 row_mask:0xf bank_mask:0xf
	v_mov_b32_e32 v148, v1
	v_mov_b32_e32 v149, v1
	v_mov_b32_e32 v152, v1
	v_mov_b32_e32 v153, v1
	v_mov_b32_dpp v148, v144 row_ror:1 row_mask:0xf bank_mask:0xf
	v_mov_b32_dpp v149, v145 row_ror:1 row_mask:0xf bank_mask:0xf
	v_mov_b32_dpp v152, v144 row_ror:2 row_mask:0xf bank_mask:0xf
	v_mov_b32_dpp v153, v145 row_ror:2 row_mask:0xf bank_mask:0xf
	v_mov_b32_e32 v144, v1
	v_mov_b32_e32 v145, v1
	v_sub_u32_e32 v134, 32, v134
	v_mov_b32_dpp v144, v142 row_ror:1 row_mask:0xf bank_mask:0xf
	v_mov_b32_dpp v145, v143 row_ror:1 row_mask:0xf bank_mask:0xf
	v_mov_b32_e32 v142, v1
	v_mov_b32_e32 v143, v1
	v_ldexp_f32 v134, v140, v134
	v_mov_b32_dpp v142, v138 row_ror:1 row_mask:0xf bank_mask:0xf
	v_mov_b32_dpp v143, v139 row_ror:1 row_mask:0xf bank_mask:0xf
	v_mad_i64_i32 v[138:139], s[0:1], v208, s52, v[132:133]
	s_mov_b32 s0, 0x30800000
	v_lshl_add_u64 v[140:141], v[138:139], 0, v[130:131]
	v_pk_fma_f32 v[138:139], v[134:135], s[0:1], v[162:163] op_sel_hi:[1,0,0]
	s_nop 0
	v_mul_f32_e32 v134, 0x4b800000, v139
	v_cmp_gt_f32_e64 s[0:1], s3, v139
	v_cmp_gt_f32_e32 vcc, s3, v138
	s_nop 0
	v_cndmask_b32_e64 v134, v139, v134, s[0:1]
	v_rsq_f32_e32 v134, v134
	v_mov_b32_e32 v139, v1
	v_mul_f32_e32 v135, 0x45800000, v134
	v_cndmask_b32_e64 v158, v134, v135, s[0:1]
	v_pk_mul_f32 v[134:135], v[126:127], v[158:159] op_sel_hi:[1,0]
	v_pk_mul_f32 v[126:127], v[122:123], v[158:159] op_sel_hi:[1,0]
	v_pk_mul_f32 v[122:123], v[124:125], v[158:159] op_sel_hi:[1,0]
	v_pk_mul_f32 v[120:121], v[120:121], v[158:159] op_sel_hi:[1,0]
	v_pk_fma_f32 v[124:125], v[72:73], v[122:123], v[76:77]
	v_mov_b32_dpp v142, v122 row_shr:1 row_mask:0xf bank_mask:0xf
	v_mov_b32_dpp v143, v123 row_shr:1 row_mask:0xf bank_mask:0xf
	v_mov_b32_dpp v156, v122 row_shr:2 row_mask:0xf bank_mask:0xf
	v_mov_b32_dpp v157, v123 row_shr:2 row_mask:0xf bank_mask:0xf
	v_pk_fma_f32 v[124:125], v[64:65], v[142:143], v[124:125]
	v_mov_b32_dpp v144, v126 row_shr:1 row_mask:0xf bank_mask:0xf
	v_pk_fma_f32 v[124:125], v[60:61], v[156:157], v[124:125]
	v_mov_b32_dpp v145, v127 row_shr:1 row_mask:0xf bank_mask:0xf
	v_pk_mul_f32 v[142:143], v[124:125], v[124:125]
	v_mov_b32_dpp v154, v126 row_shr:2 row_mask:0xf bank_mask:0xf
	v_pk_fma_f32 v[142:143], v[142:143], s[56:57], v[136:137] op_sel_hi:[1,0,0]
	v_mov_b32_dpp v155, v127 row_shr:2 row_mask:0xf bank_mask:0xf
	v_pk_mul_f32 v[142:143], v[124:125], v[142:143]
	v_pk_mul_f32 v[128:129], v[128:129], v[158:159] op_sel_hi:[1,0]
	v_exp_f32_e32 v142, v142
	v_exp_f32_e32 v143, v143
	v_pk_mul_f32 v[118:119], v[118:119], v[158:159] op_sel_hi:[1,0]
	v_mov_b32_dpp v148, v128 row_shr:1 row_mask:0xf bank_mask:0xf
	v_mov_b32_dpp v149, v129 row_shr:1 row_mask:0xf bank_mask:0xf
	v_pk_add_f32 v[142:143], v[142:143], 1.0 op_sel_hi:[1,0]
	v_mov_b32_dpp v152, v128 row_shr:2 row_mask:0xf bank_mask:0xf
	v_rcp_f32_e32 v142, v142
	v_rcp_f32_e32 v143, v143
	v_mov_b32_dpp v153, v129 row_shr:2 row_mask:0xf bank_mask:0xf
	v_pk_mul_f32 v[116:117], v[116:117], v[158:159] op_sel_hi:[1,0]
	v_mov_b32_dpp v146, v134 row_shr:1 row_mask:0xf bank_mask:0xf
	v_pk_fma_f32 v[124:125], v[124:125], v[142:143], v[124:125] neg_lo:[1,0,0] neg_hi:[1,0,0]
	v_mov_b32_dpp v147, v135 row_shr:1 row_mask:0xf bank_mask:0xf
; __device__ __forceinline__ float rstd_fix(u64 v) { return rsqrtf((float)v * (1.f / (1048576.f * 1024.f)) + 1e-6f); }
; __device__ __forceinline__ u32x4 pack8(const float* f) { u32x4 w; w.x = pk2(f[0], f[1]); w.y = pk2(f[2], f[3]); w.z = pk2(f[4], f[5]); w.w = pk2(f[6], f[7]); return w; }
; template <int N> __device__ __forceinline__ float dpp_ror(float src) { return __int_as_float(__builtin_amdgcn_update_dpp(0, __float_as_int(src), 0x120 + N, 0xf, 0xf, false)); }
;     __device__ __forceinline__ void operator()(const f32x4 (&acc)[2][2][4][2], const Unit& u, int wr, int wc, int fr, int fq) const {
;     ...
; #pragma unroll
;             for (int m = 0; m < 4; ++m) {
;                 const int row = row0 + ai * HALF + m * 16;
;                 const float rs = rstd_fix(rv[ai][m]);
;                 float g[8], up[8], o[8];
;                 { const f32x4 g0 = acc[ai][0][m][0] * rs, g1 = acc[ai][0][m][1] * rs, u0 = acc[ai][1][m][0] * rs, u1 = acc[ai][1][m][1] * rs;
; #pragma unroll
;                   for (int i = 0; i < 4; ++i) { g[i] = g0[i]; g[4 + i] = g1[i]; up[i] = u0[i]; up[4 + i] = u1[i]; } }
; #pragma unroll
;                 for (int e2 = 0; e2 < 4; ++e2) {
;                     const int e = 2 * e2;
;                     const f32x2 gv = {g[e], g[e + 1]};
;                     const f32x2 g1v = {dpp_shr<1>(dpp_ror<1>(gp[e]), g[e]), dpp_shr<1>(dpp_ror<1>(gp[e + 1]), g[e + 1])};
;     ...
;                     const f32x2 y = __builtin_elementwise_fma(w0v, g2v, __builtin_elementwise_fma(w1v, g1v, __builtin_elementwise_fma(w2v, gv, bbv)));
;                     const f32x2 z = y * __builtin_elementwise_fma(y * y, (f32x2){0.1029432397f, 0.1029432397f}, (f32x2){2.302208198f, 2.302208198f});
;                     f32x2 d; d.x = __builtin_amdgcn_exp2f(z.x); d.y = __builtin_amdgcn_exp2f(z.y);
;                     d = d + 1.0f;
;                     f32x2 r; r.x = __builtin_amdgcn_rcpf(d.x); r.y = __builtin_amdgcn_rcpf(d.y);
;                     const f32x2 ov = __builtin_elementwise_fma(-y, r, y) * upv;
;                     o[e] = ov.x; o[e + 1] = ov.y;
;                 }
;                 if (m == 0 && fr < 2) {
;                     const size_t so = ((size_t)(row >> 6) * 2 + fr) * DFF + f0;
;                     *(u32x4*)(gs01 + so) = pack8(g); *(u32x4*)(us01 + so) = pack8(up);
;                 } else *(u32x4*)(act + (size_t)row * DFF + f0) = pack8(o);
	v_pk_mul_f32 v[120:121], v[120:121], v[124:125]
	v_pk_fma_f32 v[124:125], v[70:71], v[126:127], v[74:75]
	v_mov_b32_dpp v150, v134 row_shr:2 row_mask:0xf bank_mask:0xf
	v_pk_fma_f32 v[124:125], v[62:63], v[144:145], v[124:125]
	v_mov_b32_dpp v151, v135 row_shr:2 row_mask:0xf bank_mask:0xf
	v_pk_fma_f32 v[124:125], v[58:59], v[154:155], v[124:125]
	v_pk_mul_f32 v[114:115], v[114:115], v[158:159] op_sel_hi:[1,0]
	v_pk_mul_f32 v[142:143], v[124:125], v[124:125]
	v_mov_b32_dpp v139, v123 row_ror:2 row_mask:0xf bank_mask:0xf
	v_pk_fma_f32 v[142:143], v[142:143], s[56:57], v[136:137] op_sel_hi:[1,0,0]
	s_nop 0
	v_pk_mul_f32 v[142:143], v[124:125], v[142:143]
	s_nop 0
	v_exp_f32_e32 v142, v142
	v_exp_f32_e32 v143, v143
	s_nop 0
	v_pk_add_f32 v[142:143], v[142:143], 1.0 op_sel_hi:[1,0]
	s_nop 0
	v_rcp_f32_e32 v142, v142
	v_rcp_f32_e32 v143, v143
	s_nop 0
	v_pk_fma_f32 v[124:125], v[124:125], v[142:143], v[124:125] neg_lo:[1,0,0] neg_hi:[1,0,0]
	s_nop 0
	v_pk_mul_f32 v[118:119], v[118:119], v[124:125]
	v_pk_fma_f32 v[124:125], v[52:53], v[128:129], v[56:57]
	s_nop 0
	v_pk_fma_f32 v[124:125], v[48:49], v[148:149], v[124:125]
	s_nop 0
	v_pk_fma_f32 v[124:125], v[44:45], v[152:153], v[124:125]
	s_nop 0
	v_pk_mul_f32 v[142:143], v[124:125], v[124:125]
	s_nop 0
	v_pk_fma_f32 v[142:143], v[142:143], s[56:57], v[136:137] op_sel_hi:[1,0,0]
	s_nop 0
	v_pk_mul_f32 v[142:143], v[124:125], v[142:143]
	s_nop 0
	v_exp_f32_e32 v142, v142
	v_exp_f32_e32 v143, v143
	s_nop 0
	v_pk_add_f32 v[142:143], v[142:143], 1.0 op_sel_hi:[1,0]
	s_nop 0
	v_rcp_f32_e32 v142, v142
	v_rcp_f32_e32 v143, v143
	s_nop 0
	v_pk_fma_f32 v[124:125], v[124:125], v[142:143], v[124:125] neg_lo:[1,0,0] neg_hi:[1,0,0]
	s_nop 0
	v_pk_mul_f32 v[116:117], v[116:117], v[124:125]
	v_pk_fma_f32 v[124:125], v[50:51], v[134:135], v[54:55]
	s_nop 0
	v_pk_fma_f32 v[124:125], v[46:47], v[146:147], v[124:125]
	s_nop 0
	v_pk_fma_f32 v[124:125], v[42:43], v[150:151], v[124:125]
	s_nop 0
	v_pk_mul_f32 v[142:143], v[124:125], v[124:125]
	s_nop 0
	v_pk_fma_f32 v[142:143], v[142:143], s[56:57], v[136:137] op_sel_hi:[1,0,0]
	s_nop 0
	v_pk_mul_f32 v[142:143], v[124:125], v[142:143]
	s_nop 0
	v_exp_f32_e32 v142, v142
	v_exp_f32_e32 v143, v143
	s_nop 0
	v_pk_add_f32 v[142:143], v[142:143], 1.0 op_sel_hi:[1,0]
	s_nop 0
	v_rcp_f32_e32 v142, v142
	v_rcp_f32_e32 v143, v143
	s_nop 0
	v_pk_fma_f32 v[124:125], v[124:125], v[142:143], v[124:125] neg_lo:[1,0,0] neg_hi:[1,0,0]
	s_nop 0
	v_pk_mul_f32 v[114:115], v[114:115], v[124:125]
	v_mov_b32_e32 v124, v1
	v_cvt_pk_bf16_f32 v114, v114, v115
	v_cvt_pk_bf16_f32 v115, v116, v117
	v_cvt_pk_bf16_f32 v116, v118, v119
	v_cvt_pk_bf16_f32 v117, v120, v121
	global_store_dwordx4 v[140:141], v[114:117], off nt
	v_mov_b32_e32 v118, v1
	v_mov_b32_e32 v119, v1
	v_mul_f32_e32 v114, 0x4b800000, v138
	v_cndmask_b32_e32 v114, v138, v114, vcc
	v_rsq_f32_e32 v114, v114
	v_mov_b32_e32 v116, v1
	v_mov_b32_e32 v117, v1
	v_mov_b32_e32 v120, v1
	v_mov_b32_e32 v121, v1
	v_mov_b32_e32 v125, v1
	v_mul_f32_e32 v115, 0x45800000, v114
	v_mov_b32_dpp v116, v134 row_ror:1 row_mask:0xf bank_mask:0xf
	v_mov_b32_dpp v117, v135 row_ror:1 row_mask:0xf bank_mask:0xf
	v_mov_b32_dpp v118, v134 row_ror:2 row_mask:0xf bank_mask:0xf
	v_mov_b32_dpp v119, v135 row_ror:2 row_mask:0xf bank_mask:0xf
	v_mov_b32_dpp v120, v128 row_ror:1 row_mask:0xf bank_mask:0xf
	v_mov_b32_dpp v121, v129 row_ror:1 row_mask:0xf bank_mask:0xf
	v_mov_b32_dpp v124, v128 row_ror:2 row_mask:0xf bank_mask:0xf
	v_mov_b32_dpp v125, v129 row_ror:2 row_mask:0xf bank_mask:0xf
	v_mov_b32_e32 v128, v1
	v_mov_b32_e32 v129, v1
	v_mov_b32_e32 v134, v1
	v_mov_b32_e32 v135, v1
	v_cndmask_b32_e32 v114, v114, v115, vcc
	v_mov_b32_dpp v128, v126 row_ror:1 row_mask:0xf bank_mask:0xf
	v_mov_b32_dpp v129, v127 row_ror:1 row_mask:0xf bank_mask:0xf
	v_mov_b32_dpp v134, v126 row_ror:2 row_mask:0xf bank_mask:0xf
	v_mov_b32_dpp v135, v127 row_ror:2 row_mask:0xf bank_mask:0xf
	v_mov_b32_e32 v126, v1
	v_mov_b32_e32 v127, v1
	v_pk_mul_f32 v[108:109], v[108:109], v[114:115] op_sel_hi:[1,0]
	v_mov_b32_dpp v126, v122 row_ror:1 row_mask:0xf bank_mask:0xf
	v_mov_b32_dpp v127, v123 row_ror:1 row_mask:0xf bank_mask:0xf
	v_mov_b32_e32 v138, v1
	v_mov_b32_dpp v126, v108 row_shr:1 row_mask:0xf bank_mask:0xf
	v_mov_b32_dpp v127, v109 row_shr:1 row_mask:0xf bank_mask:0xf
	v_mov_b32_dpp v138, v122 row_ror:2 row_mask:0xf bank_mask:0xf
	v_pk_fma_f32 v[122:123], v[72:73], v[108:109], v[76:77]
	v_mov_b32_dpp v139, v109 row_shr:2 row_mask:0xf bank_mask:0xf
	v_mov_b32_dpp v138, v108 row_shr:2 row_mask:0xf bank_mask:0xf
	v_pk_fma_f32 v[122:123], v[64:65], v[126:127], v[122:123]
	v_pk_mul_f32 v[106:107], v[106:107], v[114:115] op_sel_hi:[1,0]
	v_pk_fma_f32 v[122:123], v[60:61], v[138:139], v[122:123]
	v_pk_mul_f32 v[104:105], v[104:105], v[114:115] op_sel_hi:[1,0]
	v_pk_mul_f32 v[126:127], v[122:123], v[122:123]
	v_mov_b32_dpp v128, v106 row_shr:1 row_mask:0xf bank_mask:0xf
	v_pk_fma_f32 v[126:127], v[126:127], s[56:57], v[136:137] op_sel_hi:[1,0,0]
	v_mov_b32_dpp v129, v107 row_shr:1 row_mask:0xf bank_mask:0xf
	v_pk_mul_f32 v[126:127], v[122:123], v[126:127]
	v_mov_b32_dpp v134, v106 row_shr:2 row_mask:0xf bank_mask:0xf
	v_exp_f32_e32 v126, v126
	v_exp_f32_e32 v127, v127
	v_mov_b32_dpp v135, v107 row_shr:2 row_mask:0xf bank_mask:0xf
	v_pk_mul_f32 v[110:111], v[110:111], v[114:115] op_sel_hi:[1,0]
	v_pk_mul_f32 v[112:113], v[112:113], v[114:115] op_sel_hi:[1,0]
	v_pk_add_f32 v[126:127], v[126:127], 1.0 op_sel_hi:[1,0]
	v_pk_mul_f32 v[102:103], v[102:103], v[114:115] op_sel_hi:[1,0]
	v_rcp_f32_e32 v126, v126
	v_rcp_f32_e32 v127, v127
	v_mov_b32_dpp v116, v110 row_shr:1 row_mask:0xf bank_mask:0xf
; __device__ __forceinline__ u32x4 pack8(const float* f) { u32x4 w; w.x = pk2(f[0], f[1]); w.y = pk2(f[2], f[3]); w.z = pk2(f[4], f[5]); w.w = pk2(f[6], f[7]); return w; }
;     __device__ __forceinline__ void operator()(const f32x4 (&acc)[2][2][4][2], const Unit& u, int wr, int wc, int fr, int fq) const {
;     ...
;                     const f32x2 y = __builtin_elementwise_fma(w0v, g2v, __builtin_elementwise_fma(w1v, g1v, __builtin_elementwise_fma(w2v, gv, bbv)));
;                     const f32x2 z = y * __builtin_elementwise_fma(y * y, (f32x2){0.1029432397f, 0.1029432397f}, (f32x2){2.302208198f, 2.302208198f});
;                     f32x2 d; d.x = __builtin_amdgcn_exp2f(z.x); d.y = __builtin_amdgcn_exp2f(z.y);
;                     d = d + 1.0f;
;                     f32x2 r; r.x = __builtin_amdgcn_rcpf(d.x); r.y = __builtin_amdgcn_rcpf(d.y);
;                     const f32x2 ov = __builtin_elementwise_fma(-y, r, y) * upv;
;                     o[e] = ov.x; o[e + 1] = ov.y;
;                 }
;                 if (m == 0 && fr < 2) {
;                     const size_t so = ((size_t)(row >> 6) * 2 + fr) * DFF + f0;
;                     *(u32x4*)(gs01 + so) = pack8(g); *(u32x4*)(us01 + so) = pack8(up);
;                 } else *(u32x4*)(act + (size_t)row * DFF + f0) = pack8(o);
;                 if (m == 3 && fr >= 14) *(u32x4*)(gs23 + ((size_t)(row >> 6) * 2 + (fr - 14)) * DFF + f0) = pack8(g);
;                 const int ts = row & (SEQ - 1);
;                 if (ts >= SEQ - 2) { float* fo = fcp + ((size_t)(row >> 11) * 2 + (ts - (SEQ - 2))) * DFF + f0;
;                     *(f32x4*)fo = (f32x4){g[0], g[1], g[2], g[3]}; *(f32x4*)(fo + 4) = (f32x4){g[4], g[5], g[6], g[7]}; }
	v_mov_b32_dpp v117, v111 row_shr:1 row_mask:0xf bank_mask:0xf
	v_mov_b32_dpp v120, v112 row_shr:1 row_mask:0xf bank_mask:0xf
	v_pk_fma_f32 v[122:123], v[122:123], v[126:127], v[122:123] neg_lo:[1,0,0] neg_hi:[1,0,0]
	v_mov_b32_dpp v121, v113 row_shr:1 row_mask:0xf bank_mask:0xf
	v_pk_mul_f32 v[104:105], v[104:105], v[122:123]
	v_pk_fma_f32 v[122:123], v[70:71], v[106:107], v[74:75]
	v_pk_mul_f32 v[100:101], v[100:101], v[114:115] op_sel_hi:[1,0]
	v_pk_fma_f32 v[122:123], v[62:63], v[128:129], v[122:123]
	v_pk_mul_f32 v[98:99], v[98:99], v[114:115] op_sel_hi:[1,0]
	v_pk_fma_f32 v[122:123], v[58:59], v[134:135], v[122:123]
	v_pk_fma_f32 v[114:115], v[50:51], v[110:111], v[54:55]
	v_pk_mul_f32 v[126:127], v[122:123], v[122:123]
	v_mov_b32_dpp v118, v110 row_shr:2 row_mask:0xf bank_mask:0xf
	v_pk_fma_f32 v[126:127], v[126:127], s[56:57], v[136:137] op_sel_hi:[1,0,0]
	v_mov_b32_dpp v119, v111 row_shr:2 row_mask:0xf bank_mask:0xf
	v_pk_mul_f32 v[126:127], v[122:123], v[126:127]
	v_mov_b32_dpp v124, v112 row_shr:2 row_mask:0xf bank_mask:0xf
	v_exp_f32_e32 v126, v126
	v_exp_f32_e32 v127, v127
	v_mov_b32_dpp v125, v113 row_shr:2 row_mask:0xf bank_mask:0xf
	v_pk_fma_f32 v[114:115], v[46:47], v[116:117], v[114:115]
	v_pk_add_f32 v[126:127], v[126:127], 1.0 op_sel_hi:[1,0]
	s_nop 0
	v_rcp_f32_e32 v126, v126
	v_rcp_f32_e32 v127, v127
	v_pk_fma_f32 v[114:115], v[42:43], v[118:119], v[114:115]
	v_pk_fma_f32 v[122:123], v[122:123], v[126:127], v[122:123] neg_lo:[1,0,0] neg_hi:[1,0,0]
	s_nop 0
	v_pk_mul_f32 v[102:103], v[102:103], v[122:123]
	v_pk_fma_f32 v[122:123], v[52:53], v[112:113], v[56:57]
	v_pk_mul_f32 v[116:117], v[114:115], v[114:115]
	v_pk_fma_f32 v[120:121], v[48:49], v[120:121], v[122:123]
	v_pk_fma_f32 v[116:117], v[116:117], s[56:57], v[136:137] op_sel_hi:[1,0,0]
	v_pk_fma_f32 v[120:121], v[44:45], v[124:125], v[120:121]
	v_pk_mul_f32 v[116:117], v[114:115], v[116:117]
	v_pk_mul_f32 v[122:123], v[120:121], v[120:121]
	v_exp_f32_e32 v116, v116
	v_pk_fma_f32 v[122:123], v[122:123], s[56:57], v[136:137] op_sel_hi:[1,0,0]
	v_exp_f32_e32 v117, v117
	v_pk_mul_f32 v[122:123], v[120:121], v[122:123]
	v_pk_add_f32 v[116:117], v[116:117], 1.0 op_sel_hi:[1,0]
	v_exp_f32_e32 v122, v122
	v_exp_f32_e32 v123, v123
	v_rcp_f32_e32 v116, v116
	v_rcp_f32_e32 v117, v117
	v_pk_add_f32 v[122:123], v[122:123], 1.0 op_sel_hi:[1,0]
	s_nop 0
	v_rcp_f32_e32 v122, v122
	v_rcp_f32_e32 v123, v123
	v_pk_fma_f32 v[114:115], v[114:115], v[116:117], v[114:115] neg_lo:[1,0,0] neg_hi:[1,0,0]
	v_pk_fma_f32 v[120:121], v[120:121], v[122:123], v[120:121] neg_lo:[1,0,0] neg_hi:[1,0,0]
	s_nop 0
	v_pk_mul_f32 v[100:101], v[100:101], v[120:121]
	v_pk_mul_f32 v[98:99], v[98:99], v[114:115]
	s_nop 0
	v_cvt_pk_bf16_f32 v98, v98, v99
	v_cvt_pk_bf16_f32 v99, v100, v101
	v_cvt_pk_bf16_f32 v100, v102, v103
	v_mad_i64_i32 v[102:103], s[0:1], v0, s52, v[132:133]
	v_lshl_add_u64 v[102:103], v[102:103], 0, v[130:131]
	v_cvt_pk_bf16_f32 v101, v104, v105
	global_store_dwordx4 v[102:103], v[98:101], off nt
	s_and_saveexec_b64 s[0:1], s[42:43]
	s_cbranch_execz .LBB0_218
	v_lshl_add_u64 v[102:103], s[36:37], 0, v[184:185]
	v_readlane_b32 s36, v250, 20
	v_readlane_b32 s37, v250, 21
	s_movk_i32 s3, 0x1600
	v_cvt_pk_bf16_f32 v98, v110, v111
	v_cvt_pk_bf16_f32 v99, v112, v113
	v_cvt_pk_bf16_f32 v100, v106, v107
	v_cvt_pk_bf16_f32 v101, v108, v109
	s_nop 0
	v_mov_b64_e32 v[104:105], s[36:37]
	v_mad_u64_u32 v[104:105], s[36:37], v102, s3, v[104:105]
	v_mad_i32_i24 v105, v103, s3, v105
	v_lshl_add_u64 v[102:103], v[190:191], 1, v[104:105]
	global_store_dwordx4 v[102:103], v[98:101], off nt
.LBB0_218:
	s_or_b64 exec, exec, s[0:1]
	v_and_b32_e32 v0, 0x7ff, v0
	s_movk_i32 s0, 0x7fd
	v_cmp_lt_u32_e32 vcc, s0, v0
	s_and_saveexec_b64 s[0:1], vcc
	v_readlane_b32 s84, v254, 44
	v_readlane_b32 s85, v254, 45
	s_cbranch_execz .LBB0_220
	s_ashr_i32 s2, s2, 11
	s_ashr_i32 s3, s2, 31
	v_add_u32_e32 v0, 0xfffff802, v0
	v_lshl_add_u64 v[98:99], s[2:3], 1, v[0:1]
	v_mov_b64_e32 v[100:101], s[60:61]
	s_movk_i32 s36, 0x2c00
	v_mad_u64_u32 v[100:101], s[2:3], v98, s36, v[100:101]
	v_mad_i32_i24 v101, v99, s36, v101
	v_lshl_add_u64 v[98:99], v[190:191], 2, v[100:101]
	global_store_dwordx4 v[98:99], v[110:113], off nt
	global_store_dwordx4 v[98:99], v[106:109], off offset:16 nt
; __device__ __forceinline__ float rstd_fix(u64 v) { return rsqrtf((float)v * (1.f / (1048576.f * 1024.f)) + 1e-6f); }
;     __device__ __forceinline__ void operator()(const f32x4 (&acc)[2][2][4][2], const Unit& u, int wr, int wc, int fr, int fq) const {
;     ...
; #pragma unroll
;             for (int m = 0; m < 4; ++m) {
;                 const int row = row0 + ai * HALF + m * 16;
;                 const float rs = rstd_fix(rv[ai][m]);
;                 float g[8], up[8], o[8];
;                 { const f32x4 g0 = acc[ai][0][m][0] * rs, g1 = acc[ai][0][m][1] * rs, u0 = acc[ai][1][m][0] * rs, u1 = acc[ai][1][m][1] * rs;
; #pragma unroll
;                   for (int i = 0; i < 4; ++i) { g[i] = g0[i]; g[4 + i] = g1[i]; up[i] = u0[i]; up[4 + i] = u1[i]; } }
; #pragma unroll
;                 for (int e2 = 0; e2 < 4; ++e2) {
;                     const int e = 2 * e2;
;                     const f32x2 gv = {g[e], g[e + 1]};
;                     const f32x2 g1v = {dpp_shr<1>(dpp_ror<1>(gp[e]), g[e]), dpp_shr<1>(dpp_ror<1>(gp[e + 1]), g[e + 1])};
;                     const f32x2 g2v = {dpp_shr<2>(dpp_ror<2>(gp[e]), g[e]), dpp_shr<2>(dpp_ror<2>(gp[e + 1]), g[e + 1])};
;                     const f32x2 w0v = {w0[e], w0[e + 1]}, w1v = {w1[e], w1[e + 1]}, w2v = {w2[e], w2[e + 1]}, bbv = {bb[e], bb[e + 1]}, upv = {up[e], up[e + 1]};
;                     const f32x2 y = __builtin_elementwise_fma(w0v, g2v, __builtin_elementwise_fma(w1v, g1v, __builtin_elementwise_fma(w2v, gv, bbv)));
;                     const f32x2 z = y * __builtin_elementwise_fma(y * y, (f32x2){0.1029432397f, 0.1029432397f}, (f32x2){2.302208198f, 2.302208198f});
;                     f32x2 d; d.x = __builtin_amdgcn_exp2f(z.x); d.y = __builtin_amdgcn_exp2f(z.y);
;                     d = d + 1.0f;
;                     f32x2 r; r.x = __builtin_amdgcn_rcpf(d.x); r.y = __builtin_amdgcn_rcpf(d.y);
;                     const f32x2 ov = __builtin_elementwise_fma(-y, r, y) * upv;
;                     o[e] = ov.x; o[e + 1] = ov.y;
;                 }
;                 if (m == 0 && fr < 2) {
;                     const size_t so = ((size_t)(row >> 6) * 2 + fr) * DFF + f0;
;                     *(u32x4*)(gs01 + so) = pack8(g); *(u32x4*)(us01 + so) = pack8(up);
;                 } else *(u32x4*)(act + (size_t)row * DFF + f0) = pack8(o);
.LBB0_220:
	s_or_b64 exec, exec, s[0:1]
	v_ffbh_u32_e32 v0, v201
	v_min_u32_e32 v0, 32, v0
	v_lshlrev_b64 v[98:99], v0, v[200:201]
	v_min_u32_e32 v98, 1, v98
	v_or_b32_e32 v98, v99, v98
	v_cvt_f32_u32_e32 v98, v98
	v_sub_u32_e32 v0, 32, v0
	v_mov_b32_e32 v111, v1
	v_mov_b32_e32 v113, v1
	v_ldexp_f32 v0, v98, v0
	v_fmamk_f32 v0, v0, 0x30800000, v162
	v_mul_f32_e32 v98, 0x4b800000, v0
	v_cmp_gt_f32_e32 vcc, s24, v0
	v_mov_b32_dpp v111, v111 row_ror:1 row_mask:0xf bank_mask:0xf
	v_mov_b32_dpp v113, v113 row_ror:2 row_mask:0xf bank_mask:0xf
	v_cndmask_b32_e32 v0, v0, v98, vcc
	v_rsq_f32_e32 v98, v0
	v_mov_b32_e32 v106, v111
	v_mov_b32_e32 v107, v111
	v_mov_b32_e32 v108, v113
	v_mul_f32_e32 v99, 0x45800000, v98
	v_cndmask_b32_e32 v104, v98, v99, vcc
	v_pk_mul_f32 v[98:99], v[94:95], v[104:105] op_sel_hi:[1,0]
	v_pk_mul_f32 v[90:91], v[90:91], v[104:105] op_sel_hi:[1,0]
	v_pk_mul_f32 v[100:101], v[86:87], v[104:105] op_sel_hi:[1,0]
	v_pk_mul_f32 v[102:103], v[82:83], v[104:105] op_sel_hi:[1,0]
	v_pk_mul_f32 v[94:95], v[96:97], v[104:105] op_sel_hi:[1,0]
	v_pk_mul_f32 v[86:87], v[92:93], v[104:105] op_sel_hi:[1,0]
	v_pk_mul_f32 v[88:89], v[88:89], v[104:105] op_sel_hi:[1,0]
	v_pk_mul_f32 v[104:105], v[84:85], v[104:105] op_sel_hi:[1,0]
	v_mov_b32_e32 v82, v111
	v_mov_b32_e32 v83, v111
	v_mov_b32_e32 v84, v113
	v_mov_b32_e32 v85, v113
	v_mov_b32_e32 v92, v111
	v_mov_b32_e32 v93, v111
	v_mov_b32_e32 v96, v113
	v_mov_b32_e32 v97, v113
	v_mov_b32_e32 v109, v113
	v_mov_b32_e32 v110, v111
	v_mov_b32_e32 v112, v113
	v_add_u32_e32 v0, 0x80, v196
	v_mov_b32_dpp v82, v98 row_shr:1 row_mask:0xf bank_mask:0xf
	v_mov_b32_dpp v83, v99 row_shr:1 row_mask:0xf bank_mask:0xf
	v_mov_b32_dpp v84, v98 row_shr:2 row_mask:0xf bank_mask:0xf
	v_mov_b32_dpp v85, v99 row_shr:2 row_mask:0xf bank_mask:0xf
	v_mov_b32_dpp v92, v94 row_shr:1 row_mask:0xf bank_mask:0xf
	v_mov_b32_dpp v93, v95 row_shr:1 row_mask:0xf bank_mask:0xf
	v_mov_b32_dpp v96, v94 row_shr:2 row_mask:0xf bank_mask:0xf
	v_mov_b32_dpp v97, v95 row_shr:2 row_mask:0xf bank_mask:0xf
	v_mov_b32_dpp v106, v90 row_shr:1 row_mask:0xf bank_mask:0xf
	v_mov_b32_dpp v107, v91 row_shr:1 row_mask:0xf bank_mask:0xf
	v_mov_b32_dpp v108, v90 row_shr:2 row_mask:0xf bank_mask:0xf
	v_mov_b32_dpp v109, v91 row_shr:2 row_mask:0xf bank_mask:0xf
	v_mov_b32_dpp v110, v86 row_shr:1 row_mask:0xf bank_mask:0xf
	v_mov_b32_dpp v111, v87 row_shr:1 row_mask:0xf bank_mask:0xf
	v_mov_b32_dpp v112, v86 row_shr:2 row_mask:0xf bank_mask:0xf
	v_mov_b32_dpp v113, v87 row_shr:2 row_mask:0xf bank_mask:0xf
	s_and_saveexec_b64 s[0:1], s[40:41]
	s_xor_b64 s[0:1], exec, s[0:1]
	s_cbranch_execz .LBB0_222
	v_pk_fma_f32 v[114:115], v[72:73], v[86:87], v[76:77]
	s_mov_b32 s2, 0x40135761
	v_pk_fma_f32 v[110:111], v[64:65], v[110:111], v[114:115]
	v_mov_b64_e32 v[114:115], s[2:3]
	v_pk_fma_f32 v[110:111], v[60:61], v[112:113], v[110:111]
	s_mov_b32 s2, 0x3dd2d3e8
	v_pk_mul_f32 v[112:113], v[110:111], v[110:111]
	s_nop 0
	v_pk_fma_f32 v[112:113], v[112:113], s[2:3], v[114:115] op_sel_hi:[1,0,0]
	s_nop 0
	v_pk_mul_f32 v[112:113], v[110:111], v[112:113]
	s_nop 0
	v_exp_f32_e32 v112, v112
	v_exp_f32_e32 v113, v113
	s_nop 0
	v_pk_add_f32 v[112:113], v[112:113], 1.0 op_sel_hi:[1,0]
	s_nop 0
	v_rcp_f32_e32 v112, v112
	v_rcp_f32_e32 v113, v113
	s_nop 0
	v_pk_fma_f32 v[110:111], v[110:111], v[112:113], v[110:111] neg_lo:[1,0,0] neg_hi:[1,0,0]
	s_nop 0
	v_pk_mul_f32 v[104:105], v[104:105], v[110:111]
	v_pk_fma_f32 v[110:111], v[70:71], v[90:91], v[74:75]
	s_nop 0
	v_pk_fma_f32 v[106:107], v[62:63], v[106:107], v[110:111]
	s_nop 0
	v_pk_fma_f32 v[106:107], v[58:59], v[108:109], v[106:107]
	s_nop 0
	v_pk_mul_f32 v[108:109], v[106:107], v[106:107]
	s_nop 0
	v_pk_fma_f32 v[108:109], v[108:109], s[2:3], v[114:115] op_sel_hi:[1,0,0]
	s_nop 0
	v_pk_mul_f32 v[108:109], v[106:107], v[108:109]
	s_nop 0
	v_exp_f32_e32 v108, v108
	v_exp_f32_e32 v109, v109
	s_nop 0
	v_pk_add_f32 v[108:109], v[108:109], 1.0 op_sel_hi:[1,0]
	s_nop 0
	v_rcp_f32_e32 v108, v108
	v_rcp_f32_e32 v109, v109
	s_nop 0
	v_pk_fma_f32 v[106:107], v[106:107], v[108:109], v[106:107] neg_lo:[1,0,0] neg_hi:[1,0,0]
	s_nop 0
	v_pk_mul_f32 v[102:103], v[102:103], v[106:107]
	v_pk_fma_f32 v[106:107], v[52:53], v[94:95], v[56:57]
	s_nop 0
	v_pk_fma_f32 v[92:93], v[48:49], v[92:93], v[106:107]
	s_nop 0
	v_pk_fma_f32 v[92:93], v[44:45], v[96:97], v[92:93]
	s_nop 0
	v_pk_mul_f32 v[96:97], v[92:93], v[92:93]
	s_nop 0
	v_pk_fma_f32 v[96:97], v[96:97], s[2:3], v[114:115] op_sel_hi:[1,0,0]
	s_nop 0
	v_pk_mul_f32 v[96:97], v[92:93], v[96:97]
	s_nop 0
	v_exp_f32_e32 v96, v96
	v_exp_f32_e32 v97, v97
	s_nop 0
	v_pk_add_f32 v[96:97], v[96:97], 1.0 op_sel_hi:[1,0]
	s_nop 0
	v_rcp_f32_e32 v96, v96
	v_rcp_f32_e32 v97, v97
	s_nop 0
	v_pk_fma_f32 v[92:93], v[92:93], v[96:97], v[92:93] neg_lo:[1,0,0] neg_hi:[1,0,0]
	s_nop 0
	v_pk_mul_f32 v[88:89], v[88:89], v[92:93]
	v_pk_fma_f32 v[92:93], v[50:51], v[98:99], v[54:55]
	s_nop 0
	v_pk_fma_f32 v[82:83], v[46:47], v[82:83], v[92:93]
	s_nop 0
	v_pk_fma_f32 v[82:83], v[42:43], v[84:85], v[82:83]
	s_nop 0
	v_pk_mul_f32 v[84:85], v[82:83], v[82:83]
	s_nop 0
	v_pk_fma_f32 v[84:85], v[84:85], s[2:3], v[114:115] op_sel_hi:[1,0,0]
	v_readlane_b32 s2, v252, 57
	v_pk_mul_f32 v[84:85], v[82:83], v[84:85]
	v_readlane_b32 s3, v252, 58
	v_exp_f32_e32 v84, v84
	v_exp_f32_e32 v85, v85
	s_nop 0
	v_pk_add_f32 v[84:85], v[84:85], 1.0 op_sel_hi:[1,0]
	s_nop 0
	v_rcp_f32_e32 v84, v84
	v_rcp_f32_e32 v85, v85
	s_nop 0
	v_pk_fma_f32 v[82:83], v[82:83], v[84:85], v[82:83] neg_lo:[1,0,0] neg_hi:[1,0,0]
	s_nop 0
	v_pk_mul_f32 v[82:83], v[100:101], v[82:83]
	s_nop 0
	v_cvt_pk_bf16_f32 v82, v82, v83
	v_cvt_pk_bf16_f32 v83, v88, v89
	v_mov_b64_e32 v[88:89], s[2:3]
	v_mad_i64_i32 v[88:89], s[2:3], v0, s58, v[88:89]
	v_lshl_add_u64 v[88:89], v[190:191], 1, v[88:89]
	v_cvt_pk_bf16_f32 v84, v102, v103
	v_cvt_pk_bf16_f32 v85, v104, v105
	global_store_dwordx4 v[88:89], v[82:85], off nt
; __device__ __forceinline__ float rstd_fix(u64 v) { return rsqrtf((float)v * (1.f / (1048576.f * 1024.f)) + 1e-6f); }
;     __device__ __forceinline__ void operator()(const f32x4 (&acc)[2][2][4][2], const Unit& u, int wr, int wc, int fr, int fq) const {
;     ...
;             for (int m = 0; m < 4; ++m) {
;                 const int row = row0 + ai * HALF + m * 16;
;                 const float rs = rstd_fix(rv[ai][m]);
;                 float g[8], up[8], o[8];
;                 { const f32x4 g0 = acc[ai][0][m][0] * rs, g1 = acc[ai][0][m][1] * rs, u0 = acc[ai][1][m][0] * rs, u1 = acc[ai][1][m][1] * rs;
; #pragma unroll
;                   for (int i = 0; i < 4; ++i) { g[i] = g0[i]; g[4 + i] = g1[i]; up[i] = u0[i]; up[4 + i] = u1[i]; } }
; #pragma unroll
;                 for (int e2 = 0; e2 < 4; ++e2) {
;                     const int e = 2 * e2;
;                     const f32x2 gv = {g[e], g[e + 1]};
;                     const f32x2 g1v = {dpp_shr<1>(dpp_ror<1>(gp[e]), g[e]), dpp_shr<1>(dpp_ror<1>(gp[e + 1]), g[e + 1])};
;                     const f32x2 g2v = {dpp_shr<2>(dpp_ror<2>(gp[e]), g[e]), dpp_shr<2>(dpp_ror<2>(gp[e + 1]), g[e + 1])};
;                     const f32x2 w0v = {w0[e], w0[e + 1]}, w1v = {w1[e], w1[e + 1]}, w2v = {w2[e], w2[e + 1]}, bbv = {bb[e], bb[e + 1]}, upv = {up[e], up[e + 1]};
;                     const f32x2 y = __builtin_elementwise_fma(w0v, g2v, __builtin_elementwise_fma(w1v, g1v, __builtin_elementwise_fma(w2v, gv, bbv)));
;                     const f32x2 z = y * __builtin_elementwise_fma(y * y, (f32x2){0.1029432397f, 0.1029432397f}, (f32x2){2.302208198f, 2.302208198f});
;                     f32x2 d; d.x = __builtin_amdgcn_exp2f(z.x); d.y = __builtin_amdgcn_exp2f(z.y);
;                     d = d + 1.0f;
;                     f32x2 r; r.x = __builtin_amdgcn_rcpf(d.x); r.y = __builtin_amdgcn_rcpf(d.y);
;                     const f32x2 ov = __builtin_elementwise_fma(-y, r, y) * upv;
;                     o[e] = ov.x; o[e + 1] = ov.y;
;                 }
;                 if (m == 0 && fr < 2) {
;                     const size_t so = ((size_t)(row >> 6) * 2 + fr) * DFF + f0;
;                     *(u32x4*)(gs01 + so) = pack8(g); *(u32x4*)(us01 + so) = pack8(up);
;                 } else *(u32x4*)(act + (size_t)row * DFF + f0) = pack8(o);
.LBB0_222:
	s_or_saveexec_b64 s[0:1], s[0:1]
	s_nop 0
	v_ashrrev_i32_e32 v82, 6, v0
	v_ashrrev_i32_e32 v83, 31, v82
	v_lshlrev_b64 v[82:83], 1, v[82:83]
	s_xor_b64 exec, exec, s[0:1]
	s_cbranch_execz .LBB0_224
	v_or_b32_e32 v84, v82, v168
	s_movk_i32 s2, 0xb00
	v_mad_i64_i32 v[84:85], s[2:3], v84, s2, v[190:191]
	v_readlane_b32 s2, v250, 16
	v_lshlrev_b64 v[84:85], 1, v[84:85]
	v_readlane_b32 s3, v250, 17
	v_cvt_pk_bf16_f32 v106, v98, v99
	v_cvt_pk_bf16_f32 v107, v94, v95
	v_cvt_pk_bf16_f32 v108, v90, v91
	v_cvt_pk_bf16_f32 v109, v86, v87
	s_nop 1
	v_lshl_add_u64 v[92:93], s[2:3], 0, v[84:85]
	v_readlane_b32 s2, v250, 18
	v_readlane_b32 s3, v250, 19
	global_store_dwordx4 v[92:93], v[106:109], off nt
	v_cvt_pk_bf16_f32 v100, v100, v101
	v_cvt_pk_bf16_f32 v101, v88, v89
	v_cvt_pk_bf16_f32 v102, v102, v103
	v_cvt_pk_bf16_f32 v103, v104, v105
	s_nop 0
	v_lshl_add_u64 v[84:85], s[2:3], 0, v[84:85]
	global_store_dwordx4 v[84:85], v[100:103], off nt
.LBB0_224:
	s_or_b64 exec, exec, s[0:1]
	v_ffbh_u32_e32 v84, v199
	v_min_u32_e32 v92, 32, v84
	v_lshlrev_b64 v[84:85], v92, v[198:199]
	v_min_u32_e32 v84, 1, v84
	v_or_b32_e32 v84, v85, v84
	v_cvt_f32_u32_e32 v84, v84
	v_sub_u32_e32 v85, 32, v92
	s_mov_b32 s2, 0x800000
	v_mov_b32_e32 v96, v1
	v_ldexp_f32 v84, v84, v85
	v_fmamk_f32 v84, v84, 0x30800000, v162
	v_cmp_gt_f32_e32 vcc, s2, v84
	v_mul_f32_e32 v85, 0x4b800000, v84
	v_mov_b32_e32 v97, v1
	v_cndmask_b32_e32 v84, v84, v85, vcc
	v_rsq_f32_e32 v84, v84
	v_mov_b32_dpp v96, v98 row_ror:2 row_mask:0xf bank_mask:0xf
	v_mov_b32_dpp v97, v99 row_ror:2 row_mask:0xf bank_mask:0xf
	v_mov_b32_e32 v100, v1
	v_mul_f32_e32 v85, 0x45800000, v84
	v_cndmask_b32_e32 v92, v84, v85, vcc
	v_pk_mul_f32 v[84:85], v[78:79], v[92:93] op_sel_hi:[1,0]
	v_pk_mul_f32 v[78:79], v[66:67], v[92:93] op_sel_hi:[1,0]
	v_pk_mul_f32 v[66:67], v[68:69], v[92:93] op_sel_hi:[1,0]
	v_mov_b32_e32 v68, v1
	v_mov_b32_e32 v69, v1
	v_mov_b32_e32 v101, v1
	v_mov_b32_dpp v68, v98 row_ror:1 row_mask:0xf bank_mask:0xf
	v_mov_b32_dpp v69, v99 row_ror:1 row_mask:0xf bank_mask:0xf
	v_mov_b32_e32 v98, v1
	v_mov_b32_e32 v99, v1
	v_mov_b32_dpp v100, v94 row_ror:2 row_mask:0xf bank_mask:0xf
	v_mov_b32_dpp v98, v94 row_ror:1 row_mask:0xf bank_mask:0xf
	v_mov_b32_dpp v99, v95 row_ror:1 row_mask:0xf bank_mask:0xf
	v_mov_b32_dpp v101, v95 row_ror:2 row_mask:0xf bank_mask:0xf
	v_mov_b32_e32 v94, v1
	v_mov_b32_e32 v95, v1
	v_mov_b32_e32 v102, v1
	v_mov_b32_e32 v103, v1
	v_mov_b32_dpp v94, v90 row_ror:1 row_mask:0xf bank_mask:0xf
	v_mov_b32_dpp v95, v91 row_ror:1 row_mask:0xf bank_mask:0xf
	v_mov_b32_dpp v102, v90 row_ror:2 row_mask:0xf bank_mask:0xf
	v_mov_b32_dpp v103, v91 row_ror:2 row_mask:0xf bank_mask:0xf
	v_mov_b32_e32 v90, v1
	v_mov_b32_e32 v91, v1
	v_mov_b32_e32 v104, v1
	v_mov_b32_dpp v90, v86 row_ror:1 row_mask:0xf bank_mask:0xf
	v_mov_b32_dpp v91, v87 row_ror:1 row_mask:0xf bank_mask:0xf
	v_mov_b32_e32 v105, v1
	v_mov_b32_dpp v90, v66 row_shr:1 row_mask:0xf bank_mask:0xf
	v_mov_b32_dpp v91, v67 row_shr:1 row_mask:0xf bank_mask:0xf
	v_mov_b32_dpp v104, v86 row_ror:2 row_mask:0xf bank_mask:0xf
	v_mov_b32_dpp v105, v87 row_ror:2 row_mask:0xf bank_mask:0xf
	v_pk_mul_f32 v[86:87], v[40:41], v[92:93] op_sel_hi:[1,0]
	v_pk_fma_f32 v[40:41], v[72:73], v[66:67], v[76:77]
	v_mov_b32_dpp v104, v66 row_shr:2 row_mask:0xf bank_mask:0xf
	v_mov_b32_dpp v105, v67 row_shr:2 row_mask:0xf bank_mask:0xf
	v_pk_fma_f32 v[40:41], v[64:65], v[90:91], v[40:41]
	s_mov_b32 s0, 0x40135761
	v_pk_fma_f32 v[90:91], v[60:61], v[104:105], v[40:41]
	v_mov_b64_e32 v[40:41], s[0:1]
	v_pk_mul_f32 v[104:105], v[90:91], v[90:91]
	s_mov_b32 s24, 0x3dd2d3e8
	v_pk_fma_f32 v[104:105], v[104:105], s[24:25], v[40:41] op_sel_hi:[1,0,0]
	v_mov_b32_dpp v94, v78 row_shr:1 row_mask:0xf bank_mask:0xf
	v_pk_mul_f32 v[104:105], v[90:91], v[104:105]
	v_mov_b32_dpp v95, v79 row_shr:1 row_mask:0xf bank_mask:0xf
	v_exp_f32_e32 v104, v104
	v_exp_f32_e32 v105, v105
	v_mov_b32_dpp v102, v78 row_shr:2 row_mask:0xf bank_mask:0xf
	v_mov_b32_dpp v103, v79 row_shr:2 row_mask:0xf bank_mask:0xf
	v_pk_mul_f32 v[80:81], v[80:81], v[92:93] op_sel_hi:[1,0]
	v_pk_add_f32 v[104:105], v[104:105], 1.0 op_sel_hi:[1,0]
	v_pk_mul_f32 v[38:39], v[38:39], v[92:93] op_sel_hi:[1,0]
	v_rcp_f32_e32 v104, v104
	v_rcp_f32_e32 v105, v105
	v_mov_b32_dpp v98, v80 row_shr:1 row_mask:0xf bank_mask:0xf
	v_mov_b32_dpp v99, v81 row_shr:1 row_mask:0xf bank_mask:0xf
	v_mov_b32_dpp v100, v80 row_shr:2 row_mask:0xf bank_mask:0xf
	v_pk_fma_f32 v[90:91], v[90:91], v[104:105], v[90:91] neg_lo:[1,0,0] neg_hi:[1,0,0]
	v_mov_b32_dpp v101, v81 row_shr:2 row_mask:0xf bank_mask:0xf
	v_pk_mul_f32 v[86:87], v[86:87], v[90:91]
	v_pk_fma_f32 v[90:91], v[70:71], v[78:79], v[74:75]
	v_pk_mul_f32 v[36:37], v[36:37], v[92:93] op_sel_hi:[1,0]
	v_pk_fma_f32 v[90:91], v[62:63], v[94:95], v[90:91]
	v_mov_b32_dpp v68, v84 row_shr:1 row_mask:0xf bank_mask:0xf
	v_pk_fma_f32 v[90:91], v[58:59], v[102:103], v[90:91]
	v_mov_b32_dpp v69, v85 row_shr:1 row_mask:0xf bank_mask:0xf
	v_pk_mul_f32 v[94:95], v[90:91], v[90:91]
	v_mov_b32_dpp v96, v84 row_shr:2 row_mask:0xf bank_mask:0xf
	v_pk_fma_f32 v[94:95], v[94:95], s[24:25], v[40:41] op_sel_hi:[1,0,0]
	v_mov_b32_dpp v97, v85 row_shr:2 row_mask:0xf bank_mask:0xf
	v_pk_mul_f32 v[94:95], v[90:91], v[94:95]
	v_pk_mul_f32 v[34:35], v[34:35], v[92:93] op_sel_hi:[1,0]
	v_exp_f32_e32 v94, v94
	v_exp_f32_e32 v95, v95
	v_readlane_b32 s0, v252, 57
	v_readlane_b32 s1, v252, 58
	v_add_u32_e32 v89, 0x90, v196
	v_pk_add_f32 v[94:95], v[94:95], 1.0 op_sel_hi:[1,0]
	s_movk_i32 s3, 0x1600
	v_rcp_f32_e32 v94, v94
	v_rcp_f32_e32 v95, v95
	v_add_u32_e32 v106, 0xa0, v196
	v_mov_b32_e32 v92, v1
; __device__ __forceinline__ float rstd_fix(u64 v) { return rsqrtf((float)v * (1.f / (1048576.f * 1024.f)) + 1e-6f); }
;     __device__ __forceinline__ void operator()(const f32x4 (&acc)[2][2][4][2], const Unit& u, int wr, int wc, int fr, int fq) const {
;     ...
;             for (int m = 0; m < 4; ++m) {
;                 const int row = row0 + ai * HALF + m * 16;
;                 const float rs = rstd_fix(rv[ai][m]);
;                 float g[8], up[8], o[8];
;                 { const f32x4 g0 = acc[ai][0][m][0] * rs, g1 = acc[ai][0][m][1] * rs, u0 = acc[ai][1][m][0] * rs, u1 = acc[ai][1][m][1] * rs;
; #pragma unroll
;                   for (int i = 0; i < 4; ++i) { g[i] = g0[i]; g[4 + i] = g1[i]; up[i] = u0[i]; up[4 + i] = u1[i]; } }
; #pragma unroll
;                 for (int e2 = 0; e2 < 4; ++e2) {
;                     const int e = 2 * e2;
;                     const f32x2 gv = {g[e], g[e + 1]};
;                     const f32x2 g1v = {dpp_shr<1>(dpp_ror<1>(gp[e]), g[e]), dpp_shr<1>(dpp_ror<1>(gp[e + 1]), g[e + 1])};
;                     const f32x2 g2v = {dpp_shr<2>(dpp_ror<2>(gp[e]), g[e]), dpp_shr<2>(dpp_ror<2>(gp[e + 1]), g[e + 1])};
;                     const f32x2 w0v = {w0[e], w0[e + 1]}, w1v = {w1[e], w1[e + 1]}, w2v = {w2[e], w2[e + 1]}, bbv = {bb[e], bb[e + 1]}, upv = {up[e], up[e + 1]};
;                     const f32x2 y = __builtin_elementwise_fma(w0v, g2v, __builtin_elementwise_fma(w1v, g1v, __builtin_elementwise_fma(w2v, gv, bbv)));
;                     const f32x2 z = y * __builtin_elementwise_fma(y * y, (f32x2){0.1029432397f, 0.1029432397f}, (f32x2){2.302208198f, 2.302208198f});
;                     f32x2 d; d.x = __builtin_amdgcn_exp2f(z.x); d.y = __builtin_amdgcn_exp2f(z.y);
;                     d = d + 1.0f;
;                     f32x2 r; r.x = __builtin_amdgcn_rcpf(d.x); r.y = __builtin_amdgcn_rcpf(d.y);
;                     const f32x2 ov = __builtin_elementwise_fma(-y, r, y) * upv;
;                     o[e] = ov.x; o[e + 1] = ov.y;
;                 }
;                 if (m == 0 && fr < 2) {
;                     const size_t so = ((size_t)(row >> 6) * 2 + fr) * DFF + f0;
;                     *(u32x4*)(gs01 + so) = pack8(g); *(u32x4*)(us01 + so) = pack8(up);
;                 } else *(u32x4*)(act + (size_t)row * DFF + f0) = pack8(o);
	v_mov_b32_e32 v93, v1
	v_pk_fma_f32 v[90:91], v[90:91], v[94:95], v[90:91] neg_lo:[1,0,0] neg_hi:[1,0,0]
	v_mov_b32_dpp v92, v78 row_ror:2 row_mask:0xf bank_mask:0xf
	v_pk_mul_f32 v[38:39], v[38:39], v[90:91]
	v_pk_fma_f32 v[90:91], v[52:53], v[80:81], v[56:57]
	v_mov_b32_dpp v93, v79 row_ror:2 row_mask:0xf bank_mask:0xf
	v_pk_fma_f32 v[90:91], v[48:49], v[98:99], v[90:91]
	v_add_u32_e32 v88, 0xb0, v196
	v_pk_fma_f32 v[90:91], v[44:45], v[100:101], v[90:91]
	s_mov_b32 s79, 0x800000
	v_pk_mul_f32 v[94:95], v[90:91], v[90:91]
	s_nop 0
	v_pk_fma_f32 v[94:95], v[94:95], s[24:25], v[40:41] op_sel_hi:[1,0,0]
	s_nop 0
	v_pk_mul_f32 v[94:95], v[90:91], v[94:95]
	s_nop 0
	v_exp_f32_e32 v94, v94
	v_exp_f32_e32 v95, v95
	s_nop 0
	v_pk_add_f32 v[94:95], v[94:95], 1.0 op_sel_hi:[1,0]
	s_nop 0
	v_rcp_f32_e32 v94, v94
	v_rcp_f32_e32 v95, v95
	s_nop 0
	v_pk_fma_f32 v[90:91], v[90:91], v[94:95], v[90:91] neg_lo:[1,0,0] neg_hi:[1,0,0]
	s_nop 0
	v_pk_mul_f32 v[90:91], v[36:37], v[90:91]
	v_pk_fma_f32 v[36:37], v[50:51], v[84:85], v[54:55]
	v_mov_b32_e32 v94, v1
	v_pk_fma_f32 v[36:37], v[46:47], v[68:69], v[36:37]
	v_mov_b32_e32 v95, v1
	v_pk_fma_f32 v[36:37], v[42:43], v[96:97], v[36:37]
	v_mov_b32_dpp v94, v66 row_ror:2 row_mask:0xf bank_mask:0xf
	v_pk_mul_f32 v[68:69], v[36:37], v[36:37]
	v_mov_b32_dpp v95, v67 row_ror:2 row_mask:0xf bank_mask:0xf
	v_pk_fma_f32 v[68:69], v[68:69], s[24:25], v[40:41] op_sel_hi:[1,0,0]
	s_nop 0
	v_pk_mul_f32 v[68:69], v[36:37], v[68:69]
	s_nop 0
	v_exp_f32_e32 v68, v68
	v_exp_f32_e32 v69, v69
	s_nop 0
	v_pk_add_f32 v[68:69], v[68:69], 1.0 op_sel_hi:[1,0]
	s_nop 0
	v_rcp_f32_e32 v68, v68
	v_rcp_f32_e32 v69, v69
	s_nop 0
	v_pk_fma_f32 v[36:37], v[36:37], v[68:69], v[36:37] neg_lo:[1,0,0] neg_hi:[1,0,0]
	s_nop 0
	v_pk_mul_f32 v[34:35], v[34:35], v[36:37]
	s_nop 0
	v_cvt_pk_bf16_f32 v36, v34, v35
	v_mov_b64_e32 v[34:35], s[0:1]
	v_mad_i64_i32 v[68:69], s[0:1], v89, s3, v[34:35]
	v_lshl_add_u64 v[68:69], v[68:69], 0, v[130:131]
	v_cvt_pk_bf16_f32 v37, v90, v91
	v_cvt_pk_bf16_f32 v38, v38, v39
	v_cvt_pk_bf16_f32 v39, v86, v87
	global_store_dwordx4 v[68:69], v[36:39], off nt
	v_mov_b32_e32 v68, v1
	v_mov_b32_e32 v69, v1
	v_ffbh_u32_e32 v36, v195
	v_min_u32_e32 v38, 32, v36
	v_lshlrev_b64 v[36:37], v38, v[194:195]
	v_min_u32_e32 v36, 1, v36
	v_or_b32_e32 v36, v37, v36
	v_cvt_f32_u32_e32 v36, v36
	v_sub_u32_e32 v37, 32, v38
	v_mov_b32_e32 v86, v1
	v_mov_b32_e32 v87, v1
	v_ldexp_f32 v37, v36, v37
	v_ffbh_u32_e32 v36, v193
	v_min_u32_e32 v36, 32, v36
	v_lshlrev_b64 v[38:39], v36, v[192:193]
	v_min_u32_e32 v38, 1, v38
	v_or_b32_e32 v38, v39, v38
	v_cvt_f32_u32_e32 v38, v38
	v_sub_u32_e32 v36, 32, v36
	v_mov_b32_dpp v68, v84 row_ror:1 row_mask:0xf bank_mask:0xf
	v_mov_b32_dpp v69, v85 row_ror:1 row_mask:0xf bank_mask:0xf
	v_mov_b32_dpp v86, v84 row_ror:2 row_mask:0xf bank_mask:0xf
	v_mov_b32_dpp v87, v85 row_ror:2 row_mask:0xf bank_mask:0xf
	v_mov_b32_e32 v84, v1
	v_mov_b32_e32 v85, v1
	v_mov_b32_e32 v90, v1
	v_mov_b32_e32 v91, v1
	v_ldexp_f32 v36, v38, v36
	v_mov_b32_dpp v84, v80 row_ror:1 row_mask:0xf bank_mask:0xf
	v_mov_b32_dpp v85, v81 row_ror:1 row_mask:0xf bank_mask:0xf
	v_mov_b32_dpp v90, v80 row_ror:2 row_mask:0xf bank_mask:0xf
	v_mov_b32_dpp v91, v81 row_ror:2 row_mask:0xf bank_mask:0xf
	v_mov_b32_e32 v80, v1
	v_mov_b32_e32 v81, v1
	v_mad_i64_i32 v[38:39], s[0:1], v106, s3, v[34:35]
	v_mov_b32_dpp v80, v78 row_ror:1 row_mask:0xf bank_mask:0xf
	v_mov_b32_dpp v81, v79 row_ror:1 row_mask:0xf bank_mask:0xf
	v_mov_b32_e32 v78, v1
	v_mov_b32_e32 v79, v1
	s_mov_b32 s0, 0x30800000
	v_mov_b32_dpp v78, v66 row_ror:1 row_mask:0xf bank_mask:0xf
	v_mov_b32_dpp v79, v67 row_ror:1 row_mask:0xf bank_mask:0xf
	v_lshl_add_u64 v[66:67], v[38:39], 0, v[130:131]
	v_pk_fma_f32 v[38:39], v[36:37], s[0:1], v[162:163] op_sel_hi:[1,0,0]
	s_nop 0
	v_mul_f32_e32 v36, 0x4b800000, v39
	v_cmp_gt_f32_e64 s[0:1], s2, v39
	v_cmp_gt_f32_e32 vcc, s2, v38
	s_nop 0
	v_cndmask_b32_e64 v36, v39, v36, s[0:1]
	v_rsq_f32_e32 v36, v36
	v_mov_b32_e32 v39, v1
	v_mul_f32_e32 v37, 0x45800000, v36
	v_cndmask_b32_e64 v96, v36, v37, s[0:1]
	v_pk_mul_f32 v[36:37], v[30:31], v[96:97] op_sel_hi:[1,0]
	v_pk_mul_f32 v[30:31], v[26:27], v[96:97] op_sel_hi:[1,0]
	v_pk_mul_f32 v[26:27], v[28:29], v[96:97] op_sel_hi:[1,0]
	v_pk_mul_f32 v[24:25], v[24:25], v[96:97] op_sel_hi:[1,0]
	v_pk_fma_f32 v[28:29], v[72:73], v[26:27], v[76:77]
	v_mov_b32_dpp v78, v26 row_shr:1 row_mask:0xf bank_mask:0xf
	v_mov_b32_dpp v79, v27 row_shr:1 row_mask:0xf bank_mask:0xf
	v_mov_b32_dpp v94, v26 row_shr:2 row_mask:0xf bank_mask:0xf
	v_mov_b32_dpp v95, v27 row_shr:2 row_mask:0xf bank_mask:0xf
	v_pk_fma_f32 v[28:29], v[64:65], v[78:79], v[28:29]
	v_mov_b32_dpp v80, v30 row_shr:1 row_mask:0xf bank_mask:0xf
	v_pk_fma_f32 v[28:29], v[60:61], v[94:95], v[28:29]
	v_mov_b32_dpp v81, v31 row_shr:1 row_mask:0xf bank_mask:0xf
	v_pk_mul_f32 v[78:79], v[28:29], v[28:29]
	v_mov_b32_dpp v92, v30 row_shr:2 row_mask:0xf bank_mask:0xf
	v_pk_fma_f32 v[78:79], v[78:79], s[24:25], v[40:41] op_sel_hi:[1,0,0]
	v_mov_b32_dpp v93, v31 row_shr:2 row_mask:0xf bank_mask:0xf
	v_pk_mul_f32 v[78:79], v[28:29], v[78:79]
	v_pk_mul_f32 v[32:33], v[32:33], v[96:97] op_sel_hi:[1,0]
	v_exp_f32_e32 v78, v78
	v_exp_f32_e32 v79, v79
	v_pk_mul_f32 v[22:23], v[22:23], v[96:97] op_sel_hi:[1,0]
	v_mov_b32_dpp v84, v32 row_shr:1 row_mask:0xf bank_mask:0xf
	v_mov_b32_dpp v85, v33 row_shr:1 row_mask:0xf bank_mask:0xf
	v_pk_add_f32 v[78:79], v[78:79], 1.0 op_sel_hi:[1,0]
	v_mov_b32_dpp v90, v32 row_shr:2 row_mask:0xf bank_mask:0xf
	v_rcp_f32_e32 v78, v78
	v_rcp_f32_e32 v79, v79
	v_mov_b32_dpp v91, v33 row_shr:2 row_mask:0xf bank_mask:0xf
; __device__ __forceinline__ float rstd_fix(u64 v) { return rsqrtf((float)v * (1.f / (1048576.f * 1024.f)) + 1e-6f); }
;     __device__ __forceinline__ void operator()(const f32x4 (&acc)[2][2][4][2], const Unit& u, int wr, int wc, int fr, int fq) const {
;     ...
;             for (int m = 0; m < 4; ++m) {
;                 const int row = row0 + ai * HALF + m * 16;
;                 const float rs = rstd_fix(rv[ai][m]);
;                 float g[8], up[8], o[8];
;                 { const f32x4 g0 = acc[ai][0][m][0] * rs, g1 = acc[ai][0][m][1] * rs, u0 = acc[ai][1][m][0] * rs, u1 = acc[ai][1][m][1] * rs;
; #pragma unroll
;                   for (int i = 0; i < 4; ++i) { g[i] = g0[i]; g[4 + i] = g1[i]; up[i] = u0[i]; up[4 + i] = u1[i]; } }
; #pragma unroll
;                 for (int e2 = 0; e2 < 4; ++e2) {
;                     const int e = 2 * e2;
;                     const f32x2 gv = {g[e], g[e + 1]};
;                     const f32x2 g1v = {dpp_shr<1>(dpp_ror<1>(gp[e]), g[e]), dpp_shr<1>(dpp_ror<1>(gp[e + 1]), g[e + 1])};
;                     const f32x2 g2v = {dpp_shr<2>(dpp_ror<2>(gp[e]), g[e]), dpp_shr<2>(dpp_ror<2>(gp[e + 1]), g[e + 1])};
;                     const f32x2 w0v = {w0[e], w0[e + 1]}, w1v = {w1[e], w1[e + 1]}, w2v = {w2[e], w2[e + 1]}, bbv = {bb[e], bb[e + 1]}, upv = {up[e], up[e + 1]};
;                     const f32x2 y = __builtin_elementwise_fma(w0v, g2v, __builtin_elementwise_fma(w1v, g1v, __builtin_elementwise_fma(w2v, gv, bbv)));
;                     const f32x2 z = y * __builtin_elementwise_fma(y * y, (f32x2){0.1029432397f, 0.1029432397f}, (f32x2){2.302208198f, 2.302208198f});
;                     f32x2 d; d.x = __builtin_amdgcn_exp2f(z.x); d.y = __builtin_amdgcn_exp2f(z.y);
;                     d = d + 1.0f;
;                     f32x2 r; r.x = __builtin_amdgcn_rcpf(d.x); r.y = __builtin_amdgcn_rcpf(d.y);
;                     const f32x2 ov = __builtin_elementwise_fma(-y, r, y) * upv;
;                     o[e] = ov.x; o[e + 1] = ov.y;
;                 }
;                 if (m == 0 && fr < 2) {
;                     const size_t so = ((size_t)(row >> 6) * 2 + fr) * DFF + f0;
;                     *(u32x4*)(gs01 + so) = pack8(g); *(u32x4*)(us01 + so) = pack8(up);
;                 } else *(u32x4*)(act + (size_t)row * DFF + f0) = pack8(o);
	v_pk_mul_f32 v[20:21], v[20:21], v[96:97] op_sel_hi:[1,0]
	v_mov_b32_dpp v68, v36 row_shr:1 row_mask:0xf bank_mask:0xf
	v_pk_fma_f32 v[28:29], v[28:29], v[78:79], v[28:29] neg_lo:[1,0,0] neg_hi:[1,0,0]
	v_mov_b32_dpp v69, v37 row_shr:1 row_mask:0xf bank_mask:0xf
	v_pk_mul_f32 v[24:25], v[24:25], v[28:29]
	v_pk_fma_f32 v[28:29], v[70:71], v[30:31], v[74:75]
	v_mov_b32_dpp v86, v36 row_shr:2 row_mask:0xf bank_mask:0xf
	v_pk_fma_f32 v[28:29], v[62:63], v[80:81], v[28:29]
	v_mov_b32_dpp v87, v37 row_shr:2 row_mask:0xf bank_mask:0xf
	v_pk_fma_f32 v[28:29], v[58:59], v[92:93], v[28:29]
	v_pk_mul_f32 v[18:19], v[18:19], v[96:97] op_sel_hi:[1,0]
	v_pk_mul_f32 v[78:79], v[28:29], v[28:29]
	v_mov_b32_dpp v39, v27 row_ror:2 row_mask:0xf bank_mask:0xf
	v_pk_fma_f32 v[78:79], v[78:79], s[24:25], v[40:41] op_sel_hi:[1,0,0]
	s_nop 0
	v_pk_mul_f32 v[78:79], v[28:29], v[78:79]
	s_nop 0
	v_exp_f32_e32 v78, v78
	v_exp_f32_e32 v79, v79
	s_nop 0
	v_pk_add_f32 v[78:79], v[78:79], 1.0 op_sel_hi:[1,0]
	s_nop 0
	v_rcp_f32_e32 v78, v78
	v_rcp_f32_e32 v79, v79
	s_nop 0
	v_pk_fma_f32 v[28:29], v[28:29], v[78:79], v[28:29] neg_lo:[1,0,0] neg_hi:[1,0,0]
	s_nop 0
	v_pk_mul_f32 v[22:23], v[22:23], v[28:29]
	v_pk_fma_f32 v[28:29], v[52:53], v[32:33], v[56:57]
	s_nop 0
	v_pk_fma_f32 v[28:29], v[48:49], v[84:85], v[28:29]
	s_nop 0
	v_pk_fma_f32 v[28:29], v[44:45], v[90:91], v[28:29]
	s_nop 0
	v_pk_mul_f32 v[78:79], v[28:29], v[28:29]
	s_nop 0
	v_pk_fma_f32 v[78:79], v[78:79], s[24:25], v[40:41] op_sel_hi:[1,0,0]
	s_nop 0
	v_pk_mul_f32 v[78:79], v[28:29], v[78:79]
	s_nop 0
	v_exp_f32_e32 v78, v78
	v_exp_f32_e32 v79, v79
	s_nop 0
	v_pk_add_f32 v[78:79], v[78:79], 1.0 op_sel_hi:[1,0]
	s_nop 0
	v_rcp_f32_e32 v78, v78
	v_rcp_f32_e32 v79, v79
	s_nop 0
	v_pk_fma_f32 v[28:29], v[28:29], v[78:79], v[28:29] neg_lo:[1,0,0] neg_hi:[1,0,0]
	s_nop 0
	v_pk_mul_f32 v[20:21], v[20:21], v[28:29]
	v_pk_fma_f32 v[28:29], v[50:51], v[36:37], v[54:55]
	s_nop 0
	v_pk_fma_f32 v[28:29], v[46:47], v[68:69], v[28:29]
	s_nop 0
	v_pk_fma_f32 v[28:29], v[42:43], v[86:87], v[28:29]
	s_nop 0
	v_pk_mul_f32 v[68:69], v[28:29], v[28:29]
	s_nop 0
	v_pk_fma_f32 v[68:69], v[68:69], s[24:25], v[40:41] op_sel_hi:[1,0,0]
	s_nop 0
	v_pk_mul_f32 v[68:69], v[28:29], v[68:69]
	s_nop 0
	v_exp_f32_e32 v68, v68
	v_exp_f32_e32 v69, v69
	s_nop 0
	v_pk_add_f32 v[68:69], v[68:69], 1.0 op_sel_hi:[1,0]
	s_nop 0
	v_rcp_f32_e32 v68, v68
	v_rcp_f32_e32 v69, v69
	s_nop 0
	v_pk_fma_f32 v[28:29], v[28:29], v[68:69], v[28:29] neg_lo:[1,0,0] neg_hi:[1,0,0]
	s_nop 0
	v_pk_mul_f32 v[18:19], v[18:19], v[28:29]
	v_mov_b32_e32 v28, v1
	v_cvt_pk_bf16_f32 v18, v18, v19
	v_cvt_pk_bf16_f32 v19, v20, v21
	v_cvt_pk_bf16_f32 v20, v22, v23
	v_cvt_pk_bf16_f32 v21, v24, v25
	global_store_dwordx4 v[66:67], v[18:21], off nt
	v_mov_b32_e32 v22, v1
	v_mov_b32_e32 v23, v1
	v_mul_f32_e32 v18, 0x4b800000, v38
	v_cndmask_b32_e32 v18, v38, v18, vcc
	v_rsq_f32_e32 v18, v18
	v_mov_b32_e32 v20, v1
	v_mov_b32_e32 v21, v1
	v_mov_b32_e32 v24, v1
	v_mov_b32_e32 v25, v1
	v_mov_b32_e32 v29, v1
	v_mul_f32_e32 v19, 0x45800000, v18
	v_mov_b32_dpp v20, v36 row_ror:1 row_mask:0xf bank_mask:0xf
	v_mov_b32_dpp v21, v37 row_ror:1 row_mask:0xf bank_mask:0xf
	v_mov_b32_dpp v22, v36 row_ror:2 row_mask:0xf bank_mask:0xf
	v_mov_b32_dpp v23, v37 row_ror:2 row_mask:0xf bank_mask:0xf
	v_mov_b32_dpp v24, v32 row_ror:1 row_mask:0xf bank_mask:0xf
	v_mov_b32_dpp v25, v33 row_ror:1 row_mask:0xf bank_mask:0xf
	v_mov_b32_dpp v28, v32 row_ror:2 row_mask:0xf bank_mask:0xf
	v_mov_b32_dpp v29, v33 row_ror:2 row_mask:0xf bank_mask:0xf
	v_mov_b32_e32 v32, v1
	v_mov_b32_e32 v33, v1
	v_mov_b32_e32 v36, v1
	v_mov_b32_e32 v37, v1
	v_cndmask_b32_e32 v18, v18, v19, vcc
	v_mov_b32_dpp v32, v30 row_ror:1 row_mask:0xf bank_mask:0xf
	v_mov_b32_dpp v33, v31 row_ror:1 row_mask:0xf bank_mask:0xf
	v_mov_b32_dpp v36, v30 row_ror:2 row_mask:0xf bank_mask:0xf
	v_mov_b32_dpp v37, v31 row_ror:2 row_mask:0xf bank_mask:0xf
	v_mov_b32_e32 v30, v1
	v_mov_b32_e32 v31, v1
	v_pk_mul_f32 v[12:13], v[12:13], v[18:19] op_sel_hi:[1,0]
	v_mov_b32_dpp v30, v26 row_ror:1 row_mask:0xf bank_mask:0xf
	v_mov_b32_dpp v31, v27 row_ror:1 row_mask:0xf bank_mask:0xf
	v_mov_b32_e32 v38, v1
	v_mov_b32_dpp v30, v12 row_shr:1 row_mask:0xf bank_mask:0xf
	v_mov_b32_dpp v31, v13 row_shr:1 row_mask:0xf bank_mask:0xf
	v_mov_b32_dpp v38, v26 row_ror:2 row_mask:0xf bank_mask:0xf
	v_pk_fma_f32 v[26:27], v[72:73], v[12:13], v[76:77]
	v_mov_b32_dpp v39, v13 row_shr:2 row_mask:0xf bank_mask:0xf
	v_mov_b32_dpp v38, v12 row_shr:2 row_mask:0xf bank_mask:0xf
	v_pk_fma_f32 v[26:27], v[64:65], v[30:31], v[26:27]
	v_pk_mul_f32 v[10:11], v[10:11], v[18:19] op_sel_hi:[1,0]
	v_pk_fma_f32 v[26:27], v[60:61], v[38:39], v[26:27]
; __device__ __forceinline__ u32x4 pack8(const float* f) { u32x4 w; w.x = pk2(f[0], f[1]); w.y = pk2(f[2], f[3]); w.z = pk2(f[4], f[5]); w.w = pk2(f[6], f[7]); return w; }
;     __device__ __forceinline__ void operator()(const f32x4 (&acc)[2][2][4][2], const Unit& u, int wr, int wc, int fr, int fq) const {
;     ...
;                 if (m == 0 && fr < 2) {
;                     const size_t so = ((size_t)(row >> 6) * 2 + fr) * DFF + f0;
;                     *(u32x4*)(gs01 + so) = pack8(g); *(u32x4*)(us01 + so) = pack8(up);
;                 } else *(u32x4*)(act + (size_t)row * DFF + f0) = pack8(o);
;                 if (m == 3 && fr >= 14) *(u32x4*)(gs23 + ((size_t)(row >> 6) * 2 + (fr - 14)) * DFF + f0) = pack8(g);
;                 const int ts = row & (SEQ - 1);
;                 if (ts >= SEQ - 2) { float* fo = fcp + ((size_t)(row >> 11) * 2 + (ts - (SEQ - 2))) * DFF + f0;
;                     *(f32x4*)fo = (f32x4){g[0], g[1], g[2], g[3]}; *(f32x4*)(fo + 4) = (f32x4){g[4], g[5], g[6], g[7]}; }
; #pragma unroll
;                 for (int e = 0; e < 8; ++e) gp[e] = g[e];
	v_pk_mul_f32 v[8:9], v[8:9], v[18:19] op_sel_hi:[1,0]
	v_pk_mul_f32 v[30:31], v[26:27], v[26:27]
	v_mov_b32_dpp v32, v10 row_shr:1 row_mask:0xf bank_mask:0xf
	v_pk_fma_f32 v[30:31], v[30:31], s[24:25], v[40:41] op_sel_hi:[1,0,0]
	v_mov_b32_dpp v33, v11 row_shr:1 row_mask:0xf bank_mask:0xf
	v_pk_mul_f32 v[30:31], v[26:27], v[30:31]
	v_mov_b32_dpp v36, v10 row_shr:2 row_mask:0xf bank_mask:0xf
	v_exp_f32_e32 v30, v30
	v_exp_f32_e32 v31, v31
	v_mov_b32_dpp v37, v11 row_shr:2 row_mask:0xf bank_mask:0xf
	v_pk_mul_f32 v[14:15], v[14:15], v[18:19] op_sel_hi:[1,0]
	v_pk_mul_f32 v[16:17], v[16:17], v[18:19] op_sel_hi:[1,0]
	v_pk_add_f32 v[30:31], v[30:31], 1.0 op_sel_hi:[1,0]
	v_pk_mul_f32 v[6:7], v[6:7], v[18:19] op_sel_hi:[1,0]
	v_rcp_f32_e32 v30, v30
	v_rcp_f32_e32 v31, v31
	v_mov_b32_dpp v20, v14 row_shr:1 row_mask:0xf bank_mask:0xf
	v_mov_b32_dpp v21, v15 row_shr:1 row_mask:0xf bank_mask:0xf
	v_mov_b32_dpp v24, v16 row_shr:1 row_mask:0xf bank_mask:0xf
	v_pk_fma_f32 v[26:27], v[26:27], v[30:31], v[26:27] neg_lo:[1,0,0] neg_hi:[1,0,0]
	v_mov_b32_dpp v25, v17 row_shr:1 row_mask:0xf bank_mask:0xf
	v_pk_mul_f32 v[8:9], v[8:9], v[26:27]
	v_pk_fma_f32 v[26:27], v[70:71], v[10:11], v[74:75]
	v_pk_mul_f32 v[4:5], v[4:5], v[18:19] op_sel_hi:[1,0]
	v_pk_fma_f32 v[26:27], v[62:63], v[32:33], v[26:27]
	v_pk_mul_f32 v[2:3], v[2:3], v[18:19] op_sel_hi:[1,0]
	v_pk_fma_f32 v[26:27], v[58:59], v[36:37], v[26:27]
	v_pk_fma_f32 v[18:19], v[50:51], v[14:15], v[54:55]
	v_pk_mul_f32 v[30:31], v[26:27], v[26:27]
	v_mov_b32_dpp v22, v14 row_shr:2 row_mask:0xf bank_mask:0xf
	v_pk_fma_f32 v[30:31], v[30:31], s[24:25], v[40:41] op_sel_hi:[1,0,0]
	v_mov_b32_dpp v23, v15 row_shr:2 row_mask:0xf bank_mask:0xf
	v_pk_mul_f32 v[30:31], v[26:27], v[30:31]
	v_mov_b32_dpp v28, v16 row_shr:2 row_mask:0xf bank_mask:0xf
	v_exp_f32_e32 v30, v30
	v_exp_f32_e32 v31, v31
	v_mov_b32_dpp v29, v17 row_shr:2 row_mask:0xf bank_mask:0xf
	v_pk_fma_f32 v[18:19], v[46:47], v[20:21], v[18:19]
	v_pk_add_f32 v[30:31], v[30:31], 1.0 op_sel_hi:[1,0]
	s_nop 0
	v_rcp_f32_e32 v30, v30
	v_rcp_f32_e32 v31, v31
	v_pk_fma_f32 v[18:19], v[42:43], v[22:23], v[18:19]
	v_pk_fma_f32 v[26:27], v[26:27], v[30:31], v[26:27] neg_lo:[1,0,0] neg_hi:[1,0,0]
	s_nop 0
	v_pk_mul_f32 v[6:7], v[6:7], v[26:27]
	v_pk_fma_f32 v[26:27], v[52:53], v[16:17], v[56:57]
	v_pk_mul_f32 v[20:21], v[18:19], v[18:19]
	v_pk_fma_f32 v[24:25], v[48:49], v[24:25], v[26:27]
	v_pk_fma_f32 v[20:21], v[20:21], s[24:25], v[40:41] op_sel_hi:[1,0,0]
	v_pk_fma_f32 v[24:25], v[44:45], v[28:29], v[24:25]
	v_pk_mul_f32 v[20:21], v[18:19], v[20:21]
	v_pk_mul_f32 v[26:27], v[24:25], v[24:25]
	v_exp_f32_e32 v20, v20
	v_pk_fma_f32 v[26:27], v[26:27], s[24:25], v[40:41] op_sel_hi:[1,0,0]
	v_exp_f32_e32 v21, v21
	v_pk_mul_f32 v[26:27], v[24:25], v[26:27]
	v_pk_add_f32 v[20:21], v[20:21], 1.0 op_sel_hi:[1,0]
	v_exp_f32_e32 v26, v26
	v_exp_f32_e32 v27, v27
	v_rcp_f32_e32 v20, v20
	v_rcp_f32_e32 v21, v21
	v_pk_add_f32 v[26:27], v[26:27], 1.0 op_sel_hi:[1,0]
	s_nop 0
	v_rcp_f32_e32 v26, v26
	v_rcp_f32_e32 v27, v27
	v_pk_fma_f32 v[18:19], v[18:19], v[20:21], v[18:19] neg_lo:[1,0,0] neg_hi:[1,0,0]
	v_pk_fma_f32 v[24:25], v[24:25], v[26:27], v[24:25] neg_lo:[1,0,0] neg_hi:[1,0,0]
	s_nop 0
	v_pk_mul_f32 v[4:5], v[4:5], v[24:25]
	v_pk_mul_f32 v[2:3], v[2:3], v[18:19]
	s_nop 0
	v_cvt_pk_bf16_f32 v2, v2, v3
	v_cvt_pk_bf16_f32 v3, v4, v5
	v_cvt_pk_bf16_f32 v4, v6, v7
	v_mad_i64_i32 v[6:7], s[0:1], v88, s3, v[34:35]
	v_lshl_add_u64 v[6:7], v[6:7], 0, v[130:131]
	v_cvt_pk_bf16_f32 v5, v8, v9
	global_store_dwordx4 v[6:7], v[2:5], off nt
	s_and_saveexec_b64 s[0:1], s[42:43]
	s_cbranch_execz .LBB0_226
	v_readlane_b32 s2, v250, 20
	v_readlane_b32 s3, v250, 21
	v_lshl_add_u64 v[6:7], v[82:83], 0, v[184:185]
	s_movk_i32 s24, 0x1600
	v_mov_b64_e32 v[8:9], s[2:3]
	v_mad_u64_u32 v[8:9], s[2:3], v6, s24, v[8:9]
	v_mad_i32_i24 v9, v7, s24, v9
	v_lshl_add_u64 v[6:7], v[190:191], 1, v[8:9]
	v_cvt_pk_bf16_f32 v2, v14, v15
	v_cvt_pk_bf16_f32 v3, v16, v17
	v_cvt_pk_bf16_f32 v4, v10, v11
	v_cvt_pk_bf16_f32 v5, v12, v13
	global_store_dwordx4 v[6:7], v[2:5], off nt
.LBB0_226:
	s_or_b64 exec, exec, s[0:1]
	s_nop 0
	v_and_b32_e32 v2, 0x7ff, v88
	s_movk_i32 s0, 0x7fd
	v_cmp_lt_u32_e32 vcc, s0, v2
	s_and_saveexec_b64 s[0:1], vcc
	s_cbranch_execz .LBB0_207
	v_ashrrev_i32_e32 v4, 11, v0
	v_ashrrev_i32_e32 v5, 31, v4
	v_add_u32_e32 v0, 0xfffff802, v2
	v_lshl_add_u64 v[2:3], v[4:5], 1, v[0:1]
	v_mov_b64_e32 v[4:5], s[60:61]
	s_movk_i32 s24, 0x2c00
	v_mad_u64_u32 v[4:5], s[2:3], v2, s24, v[4:5]
	v_mad_i32_i24 v5, v3, s24, v5
	v_lshl_add_u64 v[2:3], v[190:191], 2, v[4:5]
	global_store_dwordx4 v[2:3], v[14:17], off nt
	global_store_dwordx4 v[2:3], v[10:13], off offset:16 nt
	s_branch .LBB0_207

; #define PG8_STAGE(bufoff, gbase, voff) do { _Pragma("unroll") for (int _i = 0; _i < 2; ++_i) \
;         __builtin_amdgcn_global_load_lds((const unsigned*)((const char*)(gbase) + (voff)[_i]), (LAS unsigned*)(lds + (bufoff) + ldsw + _i * 8192), 16, 0, 0); } while (0)
; #define PG8_LDA(dst, b, h) do { _Pragma("unroll") for (int m = 0; m < 4; ++m) _Pragma("unroll") for (int k = 0; k < 2; ++k) dst[m][k] = *(const LAS bf16x8*)(lds + PG8_SA(b, h) + aoff + m * 2048 + k * 1024); } while (0)
; #define PG8_LDB(dst, b, h) do { _Pragma("unroll") for (int n = 0; n < 2; ++n) _Pragma("unroll") for (int k = 0; k < 2; ++k) dst[n][k] = *(const LAS bf16x8*)(lds + PG8_SB(b, h) + boff + n * 2048 + k * 1024); } while (0)
; #define PG8_MMA(ai, bj, At, Bt) do { __builtin_amdgcn_s_setprio(1); _Pragma("unroll") for (int m = 0; m < 4; ++m) _Pragma("unroll") for (int n = 0; n < 2; ++n) _Pragma("unroll") for (int k = 0; k < 2; ++k) \
;         acc[ai][bj][m][n] = __builtin_amdgcn_mfma_f32_16x16x32_bf16(Bt[n][k], At[m][k], acc[ai][bj][m][n], 0, 0, 0); __builtin_amdgcn_s_setprio(0); } while (0)
; #define PG8_WAIT_V(n) asm volatile("s_waitcnt vmcnt(" #n ")" ::: "memory")
; #define PG8_WAIT_L(n) asm volatile("s_waitcnt lgkmcnt(" #n ")" ::: "memory")
; template <class Epi>
; __device__ __forceinline__ void gemm_phase(LAS unsigned char* lds, const Gemm g, const StaticOrder& S, const Epi& E) {
;     ...
;         for (int t = 0; t < nt; t += 2) {
;             const bool last = (t == nt - 2);
;             const char* a1 = cA + (size_t)(t + 1) * kstep;
;             const char* a2 = last ? nA : cA + (size_t)(t + 2) * kstep; const char* b2 = last ? nB : cB + (size_t)(t + 2) * kstep;
;             const char* a3 = a2 + kstep; const char* b3 = b2 + kstep;
;             PG8_LDB(B0, 0, 0); PG8_SCHED; PG8_LDA(At, 0, 0); PG8_STAGE(PG8_SA(1, 1), a1 + hstep, voffA);
;             PG8_WAIT_L(8); PG8_BAR; PG8_WAIT_L(0); PG8_MMA(0, 0, At, B0); PG8_BAR; PG8_SCHED;
;             PG8_LDB(B1, 0, 1); PG8_STAGE(PG8_SB(0, 0), b2, voffB);
;             PG8_BAR; PG8_WAIT_L(0); PG8_MMA(0, 1, At, B1); PG8_BAR;
;             PG8_LDA(At, 0, 1); PG8_STAGE(PG8_SA(0, 0), a2, voffA);
;             PG8_BAR; PG8_WAIT_L(0); PG8_MMA(1, 0, At, B0); PG8_BAR; PG8_SCHED;
;             PG8_STAGE(PG8_SB(0, 1), b2 + hstep, voffB);
;             PG8_WAIT_V(6); PG8_BAR; PG8_MMA(1, 1, At, B1); PG8_BAR;
.LBB0_505:
	s_add_u32 s48, s46, 0xfffc0080
	s_addc_u32 s49, s47, -1
	s_add_i32 s63, 0, 0x10000
	v_add_u32_e32 v152, s63, v171
	ds_read_b128 v[140:143], v152
	ds_read_b128 v[144:147], v152 offset:1024
	ds_read_b128 v[148:151], v152 offset:2048
	ds_read_b128 v[152:155], v152 offset:3072
	s_cmp_eq_u32 s62, 12
	s_cselect_b32 s51, s39, s49
	s_cselect_b32 s50, s58, s48
	s_cselect_b32 s49, s1, s61
	s_cselect_b32 s48, s59, s60
	v_lshl_add_u64 v[160:161], s[46:47], 0, v[136:137]
	s_add_i32 m0, s24, 0xc000
	ds_read_b128 v[156:159], v179
	ds_read_b128 v[180:183], v179 offset:1024
	ds_read_b128 v[184:187], v179 offset:2048
	ds_read_b128 v[188:191], v179 offset:3072
	ds_read_b128 v[192:195], v179 offset:4096
	ds_read_b128 v[196:199], v179 offset:5120
	ds_read_b128 v[200:203], v179 offset:6144
	ds_read_b128 v[204:207], v179 offset:7168
	global_load_lds_dwordx4 v[160:161], off
	v_lshl_add_u64 v[160:161], s[46:47], 0, v[138:139]
	s_add_i32 m0, s24, 0xe000
	s_nop 0
	global_load_lds_dwordx4 v[160:161], off
	s_waitcnt lgkmcnt(8)
	s_barrier
	s_waitcnt lgkmcnt(0)
	s_setprio 1
	s_waitcnt lgkmcnt(0)
	v_mfma_f32_16x16x32_bf16 v[126:129], v[140:143], v[156:159], v[126:129]
	v_mfma_f32_16x16x32_bf16 v[122:125], v[148:151], v[156:159], v[122:125]
	v_mfma_f32_16x16x32_bf16 v[110:113], v[140:143], v[184:187], v[110:113]
	v_mfma_f32_16x16x32_bf16 v[106:109], v[148:151], v[184:187], v[106:109]
	v_mfma_f32_16x16x32_bf16 v[94:97], v[140:143], v[192:195], v[94:97]
	v_mfma_f32_16x16x32_bf16 v[90:93], v[148:151], v[192:195], v[90:93]
	v_mfma_f32_16x16x32_bf16 v[78:81], v[140:143], v[200:203], v[78:81]
	v_mfma_f32_16x16x32_bf16 v[74:77], v[148:151], v[200:203], v[74:77]
	v_mfma_f32_16x16x32_bf16 v[126:129], v[144:147], v[180:183], v[126:129]
	v_mfma_f32_16x16x32_bf16 v[122:125], v[152:155], v[180:183], v[122:125]
	v_mfma_f32_16x16x32_bf16 v[110:113], v[144:147], v[188:191], v[110:113]
	v_mfma_f32_16x16x32_bf16 v[106:109], v[152:155], v[188:191], v[106:109]
	v_mfma_f32_16x16x32_bf16 v[94:97], v[144:147], v[196:199], v[94:97]
	v_mfma_f32_16x16x32_bf16 v[90:93], v[152:155], v[196:199], v[90:93]
	v_mfma_f32_16x16x32_bf16 v[78:81], v[144:147], v[204:207], v[78:81]
	v_mfma_f32_16x16x32_bf16 v[74:77], v[152:155], v[204:207], v[74:77]
	s_setprio 0
	s_barrier
	s_add_i32 s66, 0, 0x14000
	v_add_u32_e32 v160, s66, v171
	s_add_i32 s63, s63, s3
	ds_read_b128 v[208:211], v160
	ds_read_b128 v[212:215], v160 offset:1024
	ds_read_b128 v[216:219], v160 offset:2048
	ds_read_b128 v[220:223], v160 offset:3072
	v_lshl_add_u64 v[160:161], s[48:49], 0, v[0:1]
	s_mov_b32 m0, s63
	v_lshl_add_u64 v[172:173], s[48:49], 0, v[130:131]
	global_load_lds_dwordx4 v[160:161], off
	s_add_i32 m0, s63, 0x2000
	s_nop 0
	global_load_lds_dwordx4 v[172:173], off
	s_barrier
	s_waitcnt lgkmcnt(0)
	s_setprio 1
	s_waitcnt lgkmcnt(0)
	v_mfma_f32_16x16x32_bf16 v[118:121], v[208:211], v[156:159], v[118:121]
	v_mfma_f32_16x16x32_bf16 v[114:117], v[216:219], v[156:159], v[114:117]
	v_mfma_f32_16x16x32_bf16 v[102:105], v[208:211], v[184:187], v[102:105]
	v_mfma_f32_16x16x32_bf16 v[98:101], v[216:219], v[184:187], v[98:101]
	v_mfma_f32_16x16x32_bf16 v[86:89], v[208:211], v[192:195], v[86:89]
	v_mfma_f32_16x16x32_bf16 v[82:85], v[216:219], v[192:195], v[82:85]
	v_mfma_f32_16x16x32_bf16 v[70:73], v[208:211], v[200:203], v[70:73]
	v_mfma_f32_16x16x32_bf16 v[66:69], v[216:219], v[200:203], v[66:69]
	v_mfma_f32_16x16x32_bf16 v[118:121], v[212:215], v[180:183], v[118:121]
	v_mfma_f32_16x16x32_bf16 v[114:117], v[220:223], v[180:183], v[114:117]
	v_mfma_f32_16x16x32_bf16 v[102:105], v[212:215], v[188:191], v[102:105]
	v_mfma_f32_16x16x32_bf16 v[98:101], v[220:223], v[188:191], v[98:101]
	v_mfma_f32_16x16x32_bf16 v[86:89], v[212:215], v[196:199], v[86:89]
	v_mfma_f32_16x16x32_bf16 v[82:85], v[220:223], v[196:199], v[82:85]
	v_mfma_f32_16x16x32_bf16 v[70:73], v[212:215], v[204:207], v[70:73]
	v_mfma_f32_16x16x32_bf16 v[66:69], v[220:223], v[204:207], v[66:69]
	s_setprio 0
	s_mov_b32 m0, s24
	v_lshl_add_u64 v[174:175], s[50:51], 0, v[134:135]
	s_barrier
	ds_read_b128 v[156:159], v179 offset:16384
	ds_read_b128 v[180:183], v179 offset:17408
	ds_read_b128 v[184:187], v179 offset:18432
	ds_read_b128 v[188:191], v179 offset:19456
	ds_read_b128 v[192:195], v179 offset:20480
	ds_read_b128 v[196:199], v179 offset:21504
	ds_read_b128 v[200:203], v179 offset:22528
	ds_read_b128 v[204:207], v179 offset:23552
	global_load_lds_dwordx4 v[174:175], off
	v_lshl_add_u64 v[176:177], s[50:51], 0, v[132:133]
	s_mov_b32 m0, s26
	s_nop 0
	global_load_lds_dwordx4 v[176:177], off
	s_barrier
	s_waitcnt lgkmcnt(0)
	s_setprio 1
	s_waitcnt lgkmcnt(0)
	v_mfma_f32_16x16x32_bf16 v[62:65], v[140:143], v[156:159], v[62:65]
	v_mfma_f32_16x16x32_bf16 v[58:61], v[148:151], v[156:159], v[58:61]
	v_mfma_f32_16x16x32_bf16 v[46:49], v[140:143], v[184:187], v[46:49]
	v_mfma_f32_16x16x32_bf16 v[42:45], v[148:151], v[184:187], v[42:45]
	v_mfma_f32_16x16x32_bf16 v[30:33], v[140:143], v[192:195], v[30:33]
	v_mfma_f32_16x16x32_bf16 v[26:29], v[148:151], v[192:195], v[26:29]
	v_mfma_f32_16x16x32_bf16 v[14:17], v[140:143], v[200:203], v[14:17]
	v_mfma_f32_16x16x32_bf16 v[10:13], v[148:151], v[200:203], v[10:13]
	v_mfma_f32_16x16x32_bf16 v[62:65], v[144:147], v[180:183], v[62:65]
	v_mfma_f32_16x16x32_bf16 v[58:61], v[152:155], v[180:183], v[58:61]
	v_mfma_f32_16x16x32_bf16 v[46:49], v[144:147], v[188:191], v[46:49]
	v_mfma_f32_16x16x32_bf16 v[42:45], v[152:155], v[188:191], v[42:45]
	v_mfma_f32_16x16x32_bf16 v[30:33], v[144:147], v[196:199], v[30:33]
	v_mfma_f32_16x16x32_bf16 v[26:29], v[152:155], v[196:199], v[26:29]
	v_mfma_f32_16x16x32_bf16 v[14:17], v[144:147], v[204:207], v[14:17]
	v_mfma_f32_16x16x32_bf16 v[10:13], v[152:155], v[204:207], v[10:13]
	s_setprio 0
	s_barrier
	s_add_u32 s64, s48, 0x40000
	s_addc_u32 s65, s49, 0
	s_add_i32 s63, s66, s3
	v_lshl_add_u64 v[140:141], s[64:65], 0, v[0:1]
	s_mov_b32 m0, s63
	s_nop 0
	global_load_lds_dwordx4 v[140:141], off
	v_lshl_add_u64 v[140:141], s[64:65], 0, v[130:131]
	s_add_i32 m0, s63, 0x2000
	s_nop 0
	global_load_lds_dwordx4 v[140:141], off
	s_cmp_lg_u32 s62, -2
	s_cbranch_scc1 .Lrx_s0_std
	s_cmp_lt_u32 s55, 2
	s_cbranch_scc1 .Lrx_s0_std
	s_waitcnt vmcnt(24)
	s_branch .Lrx_s0_done

; #define PG8_STAGE(bufoff, gbase, voff) do { _Pragma("unroll") for (int _i = 0; _i < 2; ++_i) \
;         __builtin_amdgcn_global_load_lds((const unsigned*)((const char*)(gbase) + (voff)[_i]), (LAS unsigned*)(lds + (bufoff) + ldsw + _i * 8192), 16, 0, 0); } while (0)
; #define PG8_LDA(dst, b, h) do { _Pragma("unroll") for (int m = 0; m < 4; ++m) _Pragma("unroll") for (int k = 0; k < 2; ++k) dst[m][k] = *(const LAS bf16x8*)(lds + PG8_SA(b, h) + aoff + m * 2048 + k * 1024); } while (0)
; #define PG8_LDB(dst, b, h) do { _Pragma("unroll") for (int n = 0; n < 2; ++n) _Pragma("unroll") for (int k = 0; k < 2; ++k) dst[n][k] = *(const LAS bf16x8*)(lds + PG8_SB(b, h) + boff + n * 2048 + k * 1024); } while (0)
; #define PG8_MMA(ai, bj, At, Bt) do { __builtin_amdgcn_s_setprio(1); _Pragma("unroll") for (int m = 0; m < 4; ++m) _Pragma("unroll") for (int n = 0; n < 2; ++n) _Pragma("unroll") for (int k = 0; k < 2; ++k) \
;         acc[ai][bj][m][n] = __builtin_amdgcn_mfma_f32_16x16x32_bf16(Bt[n][k], At[m][k], acc[ai][bj][m][n], 0, 0, 0); __builtin_amdgcn_s_setprio(0); } while (0)
; #define PG8_WAIT_V(n) asm volatile("s_waitcnt vmcnt(" #n ")" ::: "memory")
; #define PG8_WAIT_L(n) asm volatile("s_waitcnt lgkmcnt(" #n ")" ::: "memory")
; #define PG8_BAR __builtin_amdgcn_s_barrier()
; #define PG8_SCHED __builtin_amdgcn_sched_barrier(0)
; template <class Epi>
; __device__ __forceinline__ void gemm_phase(LAS unsigned char* lds, const Gemm g, const StaticOrder& S, const Epi& E) {
;     ...
;             PG8_WAIT_V(6); PG8_BAR; PG8_MMA(1, 1, At, B1); PG8_BAR;
;             PG8_LDB(B0, 1, 0); PG8_SCHED; PG8_LDA(At, 1, 0); PG8_STAGE(PG8_SA(0, 1), a2 + hstep, voffA);
;             PG8_WAIT_L(8); PG8_BAR; PG8_WAIT_L(0); PG8_MMA(0, 0, At, B0); PG8_BAR; PG8_SCHED;
;             PG8_LDB(B1, 1, 1); PG8_STAGE(PG8_SB(1, 0), b3, voffB);
;             PG8_BAR; PG8_WAIT_L(0); PG8_MMA(0, 1, At, B1); PG8_BAR;
;             PG8_LDA(At, 1, 1); PG8_STAGE(PG8_SA(1, 0), a3, voffA);
;             PG8_BAR; PG8_WAIT_L(0); PG8_MMA(1, 0, At, B0); PG8_BAR; PG8_SCHED;
.Lrx_s0_done:
	s_barrier
	s_setprio 1
	v_mfma_f32_16x16x32_bf16 v[54:57], v[208:211], v[156:159], v[54:57]
	v_mfma_f32_16x16x32_bf16 v[50:53], v[216:219], v[156:159], v[50:53]
	v_mfma_f32_16x16x32_bf16 v[38:41], v[208:211], v[184:187], v[38:41]
	v_mfma_f32_16x16x32_bf16 v[34:37], v[216:219], v[184:187], v[34:37]
	v_mfma_f32_16x16x32_bf16 v[22:25], v[208:211], v[192:195], v[22:25]
	v_mfma_f32_16x16x32_bf16 v[18:21], v[216:219], v[192:195], v[18:21]
	v_mfma_f32_16x16x32_bf16 v[6:9], v[208:211], v[200:203], v[6:9]
	v_mfma_f32_16x16x32_bf16 v[2:5], v[216:219], v[200:203], v[2:5]
	v_mfma_f32_16x16x32_bf16 v[54:57], v[212:215], v[180:183], v[54:57]
	v_mfma_f32_16x16x32_bf16 v[50:53], v[220:223], v[180:183], v[50:53]
	v_mfma_f32_16x16x32_bf16 v[38:41], v[212:215], v[188:191], v[38:41]
	v_mfma_f32_16x16x32_bf16 v[34:37], v[220:223], v[188:191], v[34:37]
	v_mfma_f32_16x16x32_bf16 v[22:25], v[212:215], v[196:199], v[22:25]
	v_mfma_f32_16x16x32_bf16 v[18:21], v[220:223], v[196:199], v[18:21]
	v_mfma_f32_16x16x32_bf16 v[6:9], v[212:215], v[204:207], v[6:9]
	v_mfma_f32_16x16x32_bf16 v[2:5], v[220:223], v[204:207], v[2:5]
	s_setprio 0
	s_add_i32 s63, 0, 0x18000
	v_add_u32_e32 v152, s63, v171
	s_barrier
	ds_read_b128 v[140:143], v152
	ds_read_b128 v[144:147], v152 offset:1024
	ds_read_b128 v[148:151], v152 offset:2048
	ds_read_b128 v[152:155], v152 offset:3072
	s_add_u32 s50, s50, 0x40000
	s_addc_u32 s51, s51, 0
	s_mov_b32 m0, s30
	v_lshl_add_u64 v[208:209], s[50:51], 0, v[134:135]
	ds_read_b128 v[156:159], v179 offset:32768
	ds_read_b128 v[180:183], v179 offset:33792
	ds_read_b128 v[184:187], v179 offset:34816
	ds_read_b128 v[188:191], v179 offset:35840
	ds_read_b128 v[192:195], v179 offset:36864
	ds_read_b128 v[196:199], v179 offset:37888
	ds_read_b128 v[200:203], v179 offset:38912
	ds_read_b128 v[204:207], v179 offset:39936
	global_load_lds_dwordx4 v[208:209], off
	v_lshl_add_u64 v[208:209], s[50:51], 0, v[132:133]
	s_mov_b32 m0, s52
	s_nop 0
	global_load_lds_dwordx4 v[208:209], off
	s_waitcnt lgkmcnt(8)
	s_barrier
	s_waitcnt lgkmcnt(0)
	s_setprio 1
	s_waitcnt lgkmcnt(0)
	v_mfma_f32_16x16x32_bf16 v[126:129], v[140:143], v[156:159], v[126:129]
	v_mfma_f32_16x16x32_bf16 v[122:125], v[148:151], v[156:159], v[122:125]
	v_mfma_f32_16x16x32_bf16 v[110:113], v[140:143], v[184:187], v[110:113]
	v_mfma_f32_16x16x32_bf16 v[106:109], v[148:151], v[184:187], v[106:109]
	v_mfma_f32_16x16x32_bf16 v[94:97], v[140:143], v[192:195], v[94:97]
	v_mfma_f32_16x16x32_bf16 v[90:93], v[148:151], v[192:195], v[90:93]
	v_mfma_f32_16x16x32_bf16 v[78:81], v[140:143], v[200:203], v[78:81]
	v_mfma_f32_16x16x32_bf16 v[74:77], v[148:151], v[200:203], v[74:77]
	v_mfma_f32_16x16x32_bf16 v[126:129], v[144:147], v[180:183], v[126:129]
	v_mfma_f32_16x16x32_bf16 v[122:125], v[152:155], v[180:183], v[122:125]
	v_mfma_f32_16x16x32_bf16 v[110:113], v[144:147], v[188:191], v[110:113]
	v_mfma_f32_16x16x32_bf16 v[106:109], v[152:155], v[188:191], v[106:109]
	v_mfma_f32_16x16x32_bf16 v[94:97], v[144:147], v[196:199], v[94:97]
	v_mfma_f32_16x16x32_bf16 v[90:93], v[152:155], v[196:199], v[90:93]
	v_mfma_f32_16x16x32_bf16 v[78:81], v[144:147], v[204:207], v[78:81]
	v_mfma_f32_16x16x32_bf16 v[74:77], v[152:155], v[204:207], v[74:77]
	s_setprio 0
	s_barrier
	s_add_i32 s50, 0, 0x1c000
	s_add_i32 s51, s63, s3
	v_add_u32_e32 v220, s50, v171
	v_lshl_add_u64 v[160:161], v[160:161], 0, s[28:29]
	s_mov_b32 m0, s51
	ds_read_b128 v[208:211], v220
	ds_read_b128 v[212:215], v220 offset:1024
	ds_read_b128 v[216:219], v220 offset:2048
	ds_read_b128 v[220:223], v220 offset:3072
	global_load_lds_dwordx4 v[160:161], off
	v_lshl_add_u64 v[160:161], v[172:173], 0, s[28:29]
	s_add_i32 m0, s51, 0x2000
	s_nop 0
	global_load_lds_dwordx4 v[160:161], off
	s_barrier
	s_waitcnt lgkmcnt(0)
	s_setprio 1
	s_waitcnt lgkmcnt(0)
	v_mfma_f32_16x16x32_bf16 v[118:121], v[208:211], v[156:159], v[118:121]
	v_mfma_f32_16x16x32_bf16 v[114:117], v[216:219], v[156:159], v[114:117]
	v_mfma_f32_16x16x32_bf16 v[102:105], v[208:211], v[184:187], v[102:105]
	v_mfma_f32_16x16x32_bf16 v[98:101], v[216:219], v[184:187], v[98:101]
	v_mfma_f32_16x16x32_bf16 v[86:89], v[208:211], v[192:195], v[86:89]
	v_mfma_f32_16x16x32_bf16 v[82:85], v[216:219], v[192:195], v[82:85]
	v_mfma_f32_16x16x32_bf16 v[70:73], v[208:211], v[200:203], v[70:73]
	v_mfma_f32_16x16x32_bf16 v[66:69], v[216:219], v[200:203], v[66:69]
	v_mfma_f32_16x16x32_bf16 v[118:121], v[212:215], v[180:183], v[118:121]
	v_mfma_f32_16x16x32_bf16 v[114:117], v[220:223], v[180:183], v[114:117]
	v_mfma_f32_16x16x32_bf16 v[102:105], v[212:215], v[188:191], v[102:105]
	v_mfma_f32_16x16x32_bf16 v[98:101], v[220:223], v[188:191], v[98:101]
	v_mfma_f32_16x16x32_bf16 v[86:89], v[212:215], v[196:199], v[86:89]
	v_mfma_f32_16x16x32_bf16 v[82:85], v[220:223], v[196:199], v[82:85]
	v_mfma_f32_16x16x32_bf16 v[70:73], v[212:215], v[204:207], v[70:73]
	v_mfma_f32_16x16x32_bf16 v[66:69], v[220:223], v[204:207], v[66:69]
	s_setprio 0
	s_mov_b32 m0, s53
	v_lshl_add_u64 v[160:161], v[174:175], 0, s[28:29]
	s_waitcnt vmcnt(10)
	s_barrier
	ds_read_b128 v[156:159], v179 offset:49152
	ds_read_b128 v[180:183], v179 offset:50176
	ds_read_b128 v[184:187], v179 offset:51200
	ds_read_b128 v[188:191], v179 offset:52224
	ds_read_b128 v[192:195], v179 offset:53248
	ds_read_b128 v[196:199], v179 offset:54272
	ds_read_b128 v[200:203], v179 offset:55296
	ds_read_b128 v[204:207], v179 offset:56320
	global_load_lds_dwordx4 v[160:161], off
	v_lshl_add_u64 v[160:161], v[176:177], 0, s[28:29]
	s_mov_b32 m0, s54
	s_nop 0
	global_load_lds_dwordx4 v[160:161], off
	s_barrier
; __device__ __forceinline__ float rstd_fix(u64 v) { return rsqrtf((float)v * (1.f / (1048576.f * 1024.f)) + 1e-6f); }
; __device__ __forceinline__ unsigned pk2(float lo, float hi) { unsigned r; asm volatile("v_cvt_pk_bf16_f32 %0, %1, %2" : "=v"(r) : "v"(lo), "v"(hi)); return r; }
; #define PG8_STAGE(bufoff, gbase, voff) do { _Pragma("unroll") for (int _i = 0; _i < 2; ++_i) \
;         __builtin_amdgcn_global_load_lds((const unsigned*)((const char*)(gbase) + (voff)[_i]), (LAS unsigned*)(lds + (bufoff) + ldsw + _i * 8192), 16, 0, 0); } while (0)
; #define PG8_MMA(ai, bj, At, Bt) do { __builtin_amdgcn_s_setprio(1); _Pragma("unroll") for (int m = 0; m < 4; ++m) _Pragma("unroll") for (int n = 0; n < 2; ++n) _Pragma("unroll") for (int k = 0; k < 2; ++k) \
;         acc[ai][bj][m][n] = __builtin_amdgcn_mfma_f32_16x16x32_bf16(Bt[n][k], At[m][k], acc[ai][bj][m][n], 0, 0, 0); __builtin_amdgcn_s_setprio(0); } while (0)
; #define PG8_WAIT_V(n) asm volatile("s_waitcnt vmcnt(" #n ")" ::: "memory")
; #define PG8_WAIT_L(n) asm volatile("s_waitcnt lgkmcnt(" #n ")" ::: "memory")
; #define PG8_BAR __builtin_amdgcn_s_barrier()
; #define PG8_SCHED __builtin_amdgcn_sched_barrier(0)
; template <class Epi>
; __device__ __forceinline__ void gemm_phase(LAS unsigned char* lds, const Gemm g, const StaticOrder& S, const Epi& E) {
;     ...
;             PG8_BAR; PG8_WAIT_L(0); PG8_MMA(1, 0, At, B0); PG8_BAR; PG8_SCHED;
;             PG8_STAGE(PG8_SB(1, 1), b3 + hstep, voffB);
;             PG8_WAIT_V(6); PG8_BAR; PG8_MMA(1, 1, At, B1); PG8_BAR;
;     __device__ __forceinline__ void operator()(const f32x4 (&acc)[2][2][4][2], const Unit& u, int wr, int wc, int fr, int fq) const {
;     ...
;             for (int m = 0; m < 4; ++m) { const int row = row0 + ai * HALF + m * 16; bf16_t* rowp = O + (size_t)row * ldc + col0;
;                 const float rs = rstd_fix(rv[ai][m]);
; #pragma unroll
;                 for (int bj = 0; bj < 2; ++bj) { const f32x4 v0 = acc[ai][bj][m][0] * rs, v1 = acc[ai][bj][m][1] * rs;
;                     u32x4 w; w.x = pk2(v0[0], v0[1]); w.y = pk2(v0[2], v0[3]); w.z = pk2(v1[0], v1[1]); w.w = pk2(v1[2], v1[3]);
;                     *(u32x4*)(rowp + bj * HALF) = w; } }
	s_waitcnt lgkmcnt(0)
	s_setprio 1
	s_waitcnt lgkmcnt(0)
	v_mfma_f32_16x16x32_bf16 v[62:65], v[140:143], v[156:159], v[62:65]
	v_mfma_f32_16x16x32_bf16 v[58:61], v[148:151], v[156:159], v[58:61]
	v_mfma_f32_16x16x32_bf16 v[46:49], v[140:143], v[184:187], v[46:49]
	v_mfma_f32_16x16x32_bf16 v[42:45], v[148:151], v[184:187], v[42:45]
	v_mfma_f32_16x16x32_bf16 v[30:33], v[140:143], v[192:195], v[30:33]
	v_mfma_f32_16x16x32_bf16 v[26:29], v[148:151], v[192:195], v[26:29]
	v_mfma_f32_16x16x32_bf16 v[14:17], v[140:143], v[200:203], v[14:17]
	v_mfma_f32_16x16x32_bf16 v[10:13], v[148:151], v[200:203], v[10:13]
	v_mfma_f32_16x16x32_bf16 v[62:65], v[144:147], v[180:183], v[62:65]
	v_mfma_f32_16x16x32_bf16 v[58:61], v[152:155], v[180:183], v[58:61]
	v_mfma_f32_16x16x32_bf16 v[46:49], v[144:147], v[188:191], v[46:49]
	v_mfma_f32_16x16x32_bf16 v[42:45], v[152:155], v[188:191], v[42:45]
	v_mfma_f32_16x16x32_bf16 v[30:33], v[144:147], v[196:199], v[30:33]
	v_mfma_f32_16x16x32_bf16 v[26:29], v[152:155], v[196:199], v[26:29]
	v_mfma_f32_16x16x32_bf16 v[14:17], v[144:147], v[204:207], v[14:17]
	v_mfma_f32_16x16x32_bf16 v[10:13], v[152:155], v[204:207], v[10:13]
	s_setprio 0
	s_barrier
	s_add_u32 s48, s48, 0x40080
	s_addc_u32 s49, s49, 0
	s_add_i32 s50, s50, s3
	v_lshl_add_u64 v[140:141], s[48:49], 0, v[0:1]
	s_mov_b32 m0, s50
	s_nop 0
	global_load_lds_dwordx4 v[140:141], off
	v_lshl_add_u64 v[140:141], s[48:49], 0, v[130:131]
	s_add_i32 m0, s50, 0x2000
	s_nop 0
	global_load_lds_dwordx4 v[140:141], off
	s_waitcnt vmcnt(6)
	s_barrier
	s_setprio 1
	v_mfma_f32_16x16x32_bf16 v[54:57], v[208:211], v[156:159], v[54:57]
	v_mfma_f32_16x16x32_bf16 v[50:53], v[216:219], v[156:159], v[50:53]
	v_mfma_f32_16x16x32_bf16 v[38:41], v[208:211], v[184:187], v[38:41]
	v_mfma_f32_16x16x32_bf16 v[34:37], v[216:219], v[184:187], v[34:37]
	v_mfma_f32_16x16x32_bf16 v[22:25], v[208:211], v[192:195], v[22:25]
	v_mfma_f32_16x16x32_bf16 v[18:21], v[216:219], v[192:195], v[18:21]
	v_mfma_f32_16x16x32_bf16 v[6:9], v[208:211], v[200:203], v[6:9]
	v_mfma_f32_16x16x32_bf16 v[2:5], v[216:219], v[200:203], v[2:5]
	v_mfma_f32_16x16x32_bf16 v[54:57], v[212:215], v[180:183], v[54:57]
	v_mfma_f32_16x16x32_bf16 v[50:53], v[220:223], v[180:183], v[50:53]
	v_mfma_f32_16x16x32_bf16 v[38:41], v[212:215], v[188:191], v[38:41]
	v_mfma_f32_16x16x32_bf16 v[34:37], v[220:223], v[188:191], v[34:37]
	v_mfma_f32_16x16x32_bf16 v[22:25], v[212:215], v[196:199], v[22:25]
	v_mfma_f32_16x16x32_bf16 v[18:21], v[220:223], v[196:199], v[18:21]
	v_mfma_f32_16x16x32_bf16 v[6:9], v[212:215], v[204:207], v[6:9]
	v_mfma_f32_16x16x32_bf16 v[2:5], v[220:223], v[204:207], v[2:5]
	s_setprio 0
	s_add_i32 s62, s62, 2
	s_add_u32 s46, s46, 0x100
	s_addc_u32 s47, s47, 0
	s_add_u32 s60, s60, 0x100
	s_addc_u32 s61, s61, 0
	s_cmp_gt_u32 s62, 13
	s_barrier
	s_cbranch_scc0 .LBB0_505
	v_lshl_add_u32 v142, s57, 8, v168
	v_ashrrev_i32_e32 v143, 31, v142
	s_nop 0
	v_lshl_or_b32 v154, s56, 8, v178
	v_or_b32_e32 v160, 16, v142
	v_or_b32_e32 v158, 32, v142
	v_or_b32_e32 v152, 48, v142
	v_ashrrev_i32_e32 v155, 31, v154
	v_lshlrev_b64 v[142:143], 13, v[142:143]
	v_lshl_add_u64 v[142:143], s[34:35], 0, v[142:143]
	v_lshlrev_b64 v[154:155], 1, v[154:155]
	v_lshl_add_u64 v[142:143], v[142:143], 0, v[154:155]
	v_ashrrev_i32_e32 v161, 31, v160
	v_ashrrev_i32_e32 v159, 31, v158
	v_ashrrev_i32_e32 v153, 31, v152
	s_mov_b32 s1, 0x100000
	s_mov_b64 s[46:47], 0x100000
	s_mov_b32 s56, s0
	s_mov_b32 s57, s38
	s_mov_b64 s[48:49], s[44:45]
	v_mov_b32_e32 v172, v236
	s_nop 0
	s_nop 0
	v_pk_mul_f32 v[128:129], v[128:129], v[172:173] op_sel_hi:[1,0]
	v_pk_mul_f32 v[126:127], v[126:127], v[172:173] op_sel_hi:[1,0]
	v_pk_mul_f32 v[174:175], v[124:125], v[172:173] op_sel_hi:[1,0]
	v_pk_mul_f32 v[124:125], v[122:123], v[172:173] op_sel_hi:[1,0]
	v_cvt_pk_bf16_f32 v122, v126, v127
	v_cvt_pk_bf16_f32 v123, v128, v129
	v_pk_mul_f32 v[120:121], v[120:121], v[172:173] op_sel_hi:[1,0]
	v_cvt_pk_bf16_f32 v124, v124, v125
	v_cvt_pk_bf16_f32 v125, v174, v175
	global_store_dwordx4 v[142:143], v[122:125], off nt
	v_pk_mul_f32 v[118:119], v[118:119], v[172:173] op_sel_hi:[1,0]
	s_nop 0
	v_pk_mul_f32 v[122:123], v[116:117], v[172:173] op_sel_hi:[1,0]
	v_pk_mul_f32 v[116:117], v[114:115], v[172:173] op_sel_hi:[1,0]
	v_cvt_pk_bf16_f32 v114, v118, v119
	v_cvt_pk_bf16_f32 v115, v120, v121
	s_nop 0
	v_cvt_pk_bf16_f32 v116, v116, v117
	v_cvt_pk_bf16_f32 v117, v122, v123
	global_store_dwordx4 v[142:143], v[114:117], off offset:256 nt
	s_nop 1
	v_mov_b32_e32 v116, v237
	v_lshlrev_b64 v[114:115], 13, v[160:161]
	v_lshl_add_u64 v[114:115], s[34:35], 0, v[114:115]
	v_lshl_add_u64 v[114:115], v[114:115], 0, v[154:155]
	s_nop 0
	v_pk_mul_f32 v[112:113], v[112:113], v[116:117] op_sel_hi:[1,0]
	v_pk_mul_f32 v[110:111], v[110:111], v[116:117] op_sel_hi:[1,0]
	v_pk_mul_f32 v[118:119], v[108:109], v[116:117] op_sel_hi:[1,0]
	v_pk_mul_f32 v[108:109], v[106:107], v[116:117] op_sel_hi:[1,0]
	v_cvt_pk_bf16_f32 v106, v110, v111
	v_cvt_pk_bf16_f32 v107, v112, v113
	v_pk_mul_f32 v[104:105], v[104:105], v[116:117] op_sel_hi:[1,0]
	v_cvt_pk_bf16_f32 v108, v108, v109
	v_cvt_pk_bf16_f32 v109, v118, v119
	global_store_dwordx4 v[114:115], v[106:109], off nt
	v_pk_mul_f32 v[102:103], v[102:103], v[116:117] op_sel_hi:[1,0]
	s_nop 0
	v_pk_mul_f32 v[106:107], v[100:101], v[116:117] op_sel_hi:[1,0]
	v_pk_mul_f32 v[100:101], v[98:99], v[116:117] op_sel_hi:[1,0]
	v_cvt_pk_bf16_f32 v98, v102, v103
	v_cvt_pk_bf16_f32 v99, v104, v105
	s_nop 0
	v_cvt_pk_bf16_f32 v100, v100, v101
	v_cvt_pk_bf16_f32 v101, v106, v107
	global_store_dwordx4 v[114:115], v[98:101], off offset:256 nt
	s_nop 1
	v_mov_b32_e32 v100, v241
; __device__ __forceinline__ float rstd_fix(u64 v) { return rsqrtf((float)v * (1.f / (1048576.f * 1024.f)) + 1e-6f); }
; __device__ __forceinline__ unsigned pk2(float lo, float hi) { unsigned r; asm volatile("v_cvt_pk_bf16_f32 %0, %1, %2" : "=v"(r) : "v"(lo), "v"(hi)); return r; }
;     __device__ __forceinline__ void operator()(const f32x4 (&acc)[2][2][4][2], const Unit& u, int wr, int wc, int fr, int fq) const {
;     ...
;         for (int ai = 0; ai < 2; ++ai)
; #pragma unroll
;             for (int m = 0; m < 4; ++m) { const int row = row0 + ai * HALF + m * 16; bf16_t* rowp = O + (size_t)row * ldc + col0;
;                 const float rs = rstd_fix(rv[ai][m]);
; #pragma unroll
;                 for (int bj = 0; bj < 2; ++bj) { const f32x4 v0 = acc[ai][bj][m][0] * rs, v1 = acc[ai][bj][m][1] * rs;
;                     u32x4 w; w.x = pk2(v0[0], v0[1]); w.y = pk2(v0[2], v0[3]); w.z = pk2(v1[0], v1[1]); w.w = pk2(v1[2], v1[3]);
;                     *(u32x4*)(rowp + bj * HALF) = w; } }
	v_lshlrev_b64 v[98:99], 13, v[158:159]
	v_lshl_add_u64 v[98:99], s[34:35], 0, v[98:99]
	v_lshl_add_u64 v[98:99], v[98:99], 0, v[154:155]
	s_nop 0
	v_pk_mul_f32 v[96:97], v[96:97], v[100:101] op_sel_hi:[1,0]
	v_pk_mul_f32 v[94:95], v[94:95], v[100:101] op_sel_hi:[1,0]
	v_pk_mul_f32 v[102:103], v[92:93], v[100:101] op_sel_hi:[1,0]
	v_pk_mul_f32 v[92:93], v[90:91], v[100:101] op_sel_hi:[1,0]
	v_cvt_pk_bf16_f32 v90, v94, v95
	v_cvt_pk_bf16_f32 v91, v96, v97
	v_pk_mul_f32 v[88:89], v[88:89], v[100:101] op_sel_hi:[1,0]
	v_cvt_pk_bf16_f32 v92, v92, v93
	v_cvt_pk_bf16_f32 v93, v102, v103
	global_store_dwordx4 v[98:99], v[90:93], off nt
	v_pk_mul_f32 v[86:87], v[86:87], v[100:101] op_sel_hi:[1,0]
	s_nop 0
	v_pk_mul_f32 v[90:91], v[84:85], v[100:101] op_sel_hi:[1,0]
	v_pk_mul_f32 v[84:85], v[82:83], v[100:101] op_sel_hi:[1,0]
	v_cvt_pk_bf16_f32 v82, v86, v87
	v_cvt_pk_bf16_f32 v83, v88, v89
	s_nop 0
	v_cvt_pk_bf16_f32 v84, v84, v85
	v_cvt_pk_bf16_f32 v85, v90, v91
	global_store_dwordx4 v[98:99], v[82:85], off offset:256 nt
	s_nop 1
	v_mov_b32_e32 v84, v242
	v_lshlrev_b64 v[82:83], 13, v[152:153]
	v_lshl_add_u64 v[82:83], s[34:35], 0, v[82:83]
	v_lshl_add_u64 v[82:83], v[82:83], 0, v[154:155]
	s_nop 0
	v_pk_mul_f32 v[80:81], v[80:81], v[84:85] op_sel_hi:[1,0]
	v_pk_mul_f32 v[78:79], v[78:79], v[84:85] op_sel_hi:[1,0]
	v_pk_mul_f32 v[86:87], v[76:77], v[84:85] op_sel_hi:[1,0]
	v_pk_mul_f32 v[76:77], v[74:75], v[84:85] op_sel_hi:[1,0]
	v_cvt_pk_bf16_f32 v74, v78, v79
	v_cvt_pk_bf16_f32 v75, v80, v81
	v_pk_mul_f32 v[72:73], v[72:73], v[84:85] op_sel_hi:[1,0]
	v_cvt_pk_bf16_f32 v76, v76, v77
	v_cvt_pk_bf16_f32 v77, v86, v87
	global_store_dwordx4 v[82:83], v[74:77], off nt
	v_pk_mul_f32 v[70:71], v[70:71], v[84:85] op_sel_hi:[1,0]
	s_nop 0
	v_pk_mul_f32 v[74:75], v[68:69], v[84:85] op_sel_hi:[1,0]
	v_pk_mul_f32 v[68:69], v[66:67], v[84:85] op_sel_hi:[1,0]
	v_cvt_pk_bf16_f32 v66, v70, v71
	v_cvt_pk_bf16_f32 v67, v72, v73
	s_nop 0
	v_cvt_pk_bf16_f32 v68, v68, v69
	v_cvt_pk_bf16_f32 v69, v74, v75
	global_store_dwordx4 v[82:83], v[66:69], off offset:256 nt
	s_nop 1
	v_mov_b32_e32 v68, v243
	v_lshl_add_u64 v[66:67], v[142:143], 0, s[46:47]
	s_mov_b64 s[46:47], 0x120000
	s_nop 0
	s_nop 0
	v_pk_mul_f32 v[62:63], v[62:63], v[68:69] op_sel_hi:[1,0]
	v_pk_mul_f32 v[70:71], v[60:61], v[68:69] op_sel_hi:[1,0]
	v_pk_mul_f32 v[60:61], v[58:59], v[68:69] op_sel_hi:[1,0]
	v_cvt_pk_bf16_f32 v58, v62, v63
	v_add_co_u32_e32 v62, vcc, s1, v142
	v_pk_mul_f32 v[64:65], v[64:65], v[68:69] op_sel_hi:[1,0]
	s_nop 0
	v_addc_co_u32_e32 v63, vcc, 0, v143, vcc
	v_cvt_pk_bf16_f32 v59, v64, v65
	v_cvt_pk_bf16_f32 v60, v60, v61
	v_cvt_pk_bf16_f32 v61, v70, v71
	global_store_dwordx4 v[62:63], v[58:61], off nt
	v_pk_mul_f32 v[56:57], v[56:57], v[68:69] op_sel_hi:[1,0]
	v_pk_mul_f32 v[54:55], v[54:55], v[68:69] op_sel_hi:[1,0]
	v_pk_mul_f32 v[58:59], v[52:53], v[68:69] op_sel_hi:[1,0]
	v_pk_mul_f32 v[52:53], v[50:51], v[68:69] op_sel_hi:[1,0]
	v_cvt_pk_bf16_f32 v50, v54, v55
	v_cvt_pk_bf16_f32 v51, v56, v57
	s_mov_b32 s1, 0x120000
	v_cvt_pk_bf16_f32 v52, v52, v53
	v_cvt_pk_bf16_f32 v53, v58, v59
	global_store_dwordx4 v[66:67], v[50:53], off offset:256 nt
	s_nop 1
	v_mov_b32_e32 v52, v246
	v_lshl_add_u64 v[50:51], v[142:143], 0, s[46:47]
	s_mov_b64 s[46:47], 0x140000
	s_nop 0
	s_nop 0
	v_pk_mul_f32 v[46:47], v[46:47], v[52:53] op_sel_hi:[1,0]
	v_pk_mul_f32 v[54:55], v[44:45], v[52:53] op_sel_hi:[1,0]
	v_pk_mul_f32 v[44:45], v[42:43], v[52:53] op_sel_hi:[1,0]
	v_cvt_pk_bf16_f32 v42, v46, v47
	v_add_co_u32_e32 v46, vcc, s1, v142
	v_pk_mul_f32 v[48:49], v[48:49], v[52:53] op_sel_hi:[1,0]
	s_nop 0
	v_addc_co_u32_e32 v47, vcc, 0, v143, vcc
	v_cvt_pk_bf16_f32 v43, v48, v49
	v_cvt_pk_bf16_f32 v44, v44, v45
	v_cvt_pk_bf16_f32 v45, v54, v55
	global_store_dwordx4 v[46:47], v[42:45], off nt
	v_pk_mul_f32 v[40:41], v[40:41], v[52:53] op_sel_hi:[1,0]
	v_pk_mul_f32 v[38:39], v[38:39], v[52:53] op_sel_hi:[1,0]
	v_pk_mul_f32 v[42:43], v[36:37], v[52:53] op_sel_hi:[1,0]
	v_pk_mul_f32 v[36:37], v[34:35], v[52:53] op_sel_hi:[1,0]
	v_cvt_pk_bf16_f32 v34, v38, v39
	v_cvt_pk_bf16_f32 v35, v40, v41
	s_mov_b32 s1, 0x140000
	v_cvt_pk_bf16_f32 v36, v36, v37
	v_cvt_pk_bf16_f32 v37, v42, v43
	global_store_dwordx4 v[50:51], v[34:37], off offset:256 nt
	s_nop 1
	v_mov_b32_e32 v36, v247
	v_lshl_add_u64 v[34:35], v[142:143], 0, s[46:47]
	s_mov_b64 s[46:47], 0x160000
	s_nop 0
	s_nop 0
	v_pk_mul_f32 v[30:31], v[30:31], v[36:37] op_sel_hi:[1,0]
	v_pk_mul_f32 v[38:39], v[28:29], v[36:37] op_sel_hi:[1,0]
	v_pk_mul_f32 v[28:29], v[26:27], v[36:37] op_sel_hi:[1,0]
	v_cvt_pk_bf16_f32 v26, v30, v31
	v_add_co_u32_e32 v30, vcc, s1, v142
	v_pk_mul_f32 v[32:33], v[32:33], v[36:37] op_sel_hi:[1,0]
	s_nop 0
	v_addc_co_u32_e32 v31, vcc, 0, v143, vcc
	v_cvt_pk_bf16_f32 v27, v32, v33
	v_cvt_pk_bf16_f32 v28, v28, v29
	v_cvt_pk_bf16_f32 v29, v38, v39
	global_store_dwordx4 v[30:31], v[26:29], off nt
	v_pk_mul_f32 v[24:25], v[24:25], v[36:37] op_sel_hi:[1,0]
	v_pk_mul_f32 v[22:23], v[22:23], v[36:37] op_sel_hi:[1,0]
	v_pk_mul_f32 v[26:27], v[20:21], v[36:37] op_sel_hi:[1,0]
	v_pk_mul_f32 v[20:21], v[18:19], v[36:37] op_sel_hi:[1,0]
	v_cvt_pk_bf16_f32 v18, v22, v23
	v_cvt_pk_bf16_f32 v19, v24, v25
	s_mov_b32 s1, 0x160000
	v_cvt_pk_bf16_f32 v20, v20, v21
	v_cvt_pk_bf16_f32 v21, v26, v27
	global_store_dwordx4 v[34:35], v[18:21], off offset:256 nt
	s_nop 1
	v_mov_b32_e32 v20, v248
	v_lshl_add_u64 v[18:19], v[142:143], 0, s[46:47]
	s_mov_b64 s[46:47], s[42:43]
	s_nop 0
	s_nop 0
	v_pk_mul_f32 v[14:15], v[14:15], v[20:21] op_sel_hi:[1,0]
	v_pk_mul_f32 v[22:23], v[12:13], v[20:21] op_sel_hi:[1,0]
	v_pk_mul_f32 v[12:13], v[10:11], v[20:21] op_sel_hi:[1,0]
	v_cvt_pk_bf16_f32 v10, v14, v15
	v_add_co_u32_e32 v14, vcc, s1, v142
	v_pk_mul_f32 v[16:17], v[16:17], v[20:21] op_sel_hi:[1,0]
	s_nop 0
	v_addc_co_u32_e32 v15, vcc, 0, v143, vcc
	v_cvt_pk_bf16_f32 v11, v16, v17
	v_cvt_pk_bf16_f32 v12, v12, v13
	v_cvt_pk_bf16_f32 v13, v22, v23
	global_store_dwordx4 v[14:15], v[10:13], off nt
	s_and_b64 vcc, exec, s[40:41]
	v_pk_mul_f32 v[8:9], v[8:9], v[20:21] op_sel_hi:[1,0]
	v_pk_mul_f32 v[10:11], v[4:5], v[20:21] op_sel_hi:[1,0]
	v_pk_mul_f32 v[4:5], v[2:3], v[20:21] op_sel_hi:[1,0]
	v_pk_mul_f32 v[6:7], v[6:7], v[20:21] op_sel_hi:[1,0]
	s_nop 0
	v_cvt_pk_bf16_f32 v2, v6, v7
	v_cvt_pk_bf16_f32 v3, v8, v9
	v_cvt_pk_bf16_f32 v4, v4, v5
	v_cvt_pk_bf16_f32 v5, v10, v11
	global_store_dwordx4 v[18:19], v[2:5], off offset:256 nt
	s_cbranch_vccz .LBB0_498
	s_waitcnt vmcnt(0)
	v_readlane_b32 s84, v254, 44
	s_cmpk_gt_u32 s2, 0xff
	v_readlane_b32 s85, v254, 45
	s_cbranch_scc1 .LBB0_509
	s_barrier
